# baseline (speedup 1.0000x reference)
; __device__ __forceinline__ void gemm_phase(KP p, char* shmc, const u16* __restrict__ A,
;                                            const u16* __restrict__ Bt, const int N, const int K, const int mode,
;                                            const float* __restrict__ xin, const float resw) {
;     ...
;   const int nM = S_ / BM, nN = N / BM, nwg = nM * nN;
;   const int nt = K / BK;
;     ...
;   int tix = bid_s();
;   int brow = 0, bcol = 0, pn = 0, par = 0;
.LBB0_44:
	s_andn2_b64 vcc, exec, s[6:7]
	s_cbranch_vccnz .LBB0_316
	s_lshr_b32 s6, s50, 6
	s_add_i32 s56, s6, -1
	s_add_i32 s67, s6, -2
	s_lshl_b32 s8, s50, 6
	s_lshl_b64 s[6:7], s[56:57], 7
	s_add_u32 s56, s12, s6
	s_addc_u32 s80, s13, s7
	s_lshl_b32 s81, s22, 2
	v_cvt_f32_u32_e32 v0, s81
	s_lshl_b32 s68, s22, 3
	s_waitcnt lgkmcnt(0)
	s_cmp_lg_u64 s[20:21], 0
	s_cselect_b64 s[22:23], -1, 0
	v_rcp_iflag_f32_e32 v0, v0
	s_sub_i32 s6, 0, s81
	s_mov_b32 s19, s18
	s_mov_b32 s90, 0
	v_mul_f32_e32 v0, 0x4f7ffffe, v0
	v_cvt_u32_f32_e32 v0, v0
	s_lshl_b32 s72, s8, 1
	v_readfirstlane_b32 s7, v0
	s_mul_i32 s6, s6, s7
	s_mul_hi_u32 s6, s7, s6
	s_add_i32 s69, s7, s6
	s_bitset1_b32 s101, 31
	s_branch .LBB0_47

; #define STAGE(P, BASE, br, kt) do { const u16* _gb = (BASE) + ((size_t)(br) * K + (size_t)(kt) * BK); \
;     __builtin_amdgcn_global_load_lds((const unsigned*)(_gb + goff0), (unsigned*)((char*)(P) + tid * 16), 16, 0, 0); \
;     __builtin_amdgcn_global_load_lds((const unsigned*)(_gb + (size_t)64 * K + goff0), (unsigned*)((char*)(P) + tid * 16 + 8192), 16, 0, 0); } while (0)
; #define LDA(dst, b, h) _Pragma("unroll") for (int m = 0; m < 4; ++m) _Pragma("unroll") for (int k = 0; k < 2; ++k) \
;     dst[m][k] = *reinterpret_cast<const bf16x8*>((char*)SA(b, h) + lds_byte(wr * 64 + m * 16 + fr, k * 32 + fq * 8))
; #define LDB(dst, b, h) _Pragma("unroll") for (int n = 0; n < 2; ++n) _Pragma("unroll") for (int k = 0; k < 2; ++k) \
;     dst[n][k] = *reinterpret_cast<const bf16x8*>((char*)SB(b, h) + lds_byte(wc * 32 + n * 16 + fr, k * 32 + fq * 8))
; #define WAIT_V(n) asm volatile("s_waitcnt vmcnt(" #n ")" ::: "memory")
; #define BAR __builtin_amdgcn_s_barrier()
; #define SCHED __builtin_amdgcn_sched_barrier(0)
; __device__ __forceinline__ void gemm_phase(KP p, char* shmc, const u16* __restrict__ A,
;                                            const u16* __restrict__ Bt, const int N, const int K, const int mode,
;                                            const float* __restrict__ xin, const float resw) {
;     ...
;   while (tix < nwg) {
;     int tid = threadIdx.x;
;     asm volatile("" : "+v"(tid));
;     const int wid = tid >> 6, lane = tid & 63, wr = wid >> 2, wc = wid & 3, fr = lane & 15, fq = lane >> 4;
;     int goff0;
;     { int r_, c_; stage_rc(tid * 16, r_, c_); goff0 = r_ * K + c_; }
;     f32x4 acc[2][2][4][2];
; #pragma unroll
;     for (int a = 0; a < 2; ++a)
; #pragma unroll
;       for (int b = 0; b < 2; ++b)
; #pragma unroll
;         for (int m = 0; m < 4; ++m)
; #pragma unroll
;           for (int n = 0; n < 2; ++n) acc[a][b][m][n] = f32x4{0.f, 0.f, 0.f, 0.f};
;     bf16x8 At[4][2], B0[2][2], B1[2][2];
;     WAIT_V(0);
;     if (wr == 1) BAR;
;     BAR;
;     for (int t = 0; t < nt - 2; t += 2) {
;       LDB(B0, 0, 0); SCHED; LDA(At, 0, 0); STAGE(SA(1, 1), A, brow + HALF, t + 1);
.LBB0_47:
	v_mov_b32_e32 v217, v210
	s_waitcnt vmcnt(0)
	s_nop 0
	v_ashrrev_i32_e32 v0, 8, v217
	v_bfe_i32 v2, v217, 27, 1
	v_lshlrev_b32_e32 v135, 4, v217
	v_lshrrev_b32_e32 v2, 22, v2
	s_add_i32 s6, s24, 0x80
	v_add_u32_e32 v2, v135, v2
	s_mul_hi_i32 s7, s6, s50
	s_mul_i32 s6, s6, s50
	v_and_b32_e32 v2, 0xfffffc00, v2
	s_lshl_b64 s[6:7], s[6:7], 1
	v_sub_u32_e32 v2, v135, v2
	s_add_u32 s8, s12, s6
	s_mul_hi_i32 s27, s28, s50
	s_mul_i32 s26, s28, s50
	v_ashrrev_i32_e32 v1, 31, v217
	v_lshrrev_b32_e32 v3, 4, v2
	s_addc_u32 s9, s13, s7
	s_ashr_i32 s29, s28, 31
	s_lshl_b64 s[26:27], s[26:27], 1
	v_lshrrev_b32_e32 v1, 26, v1
	v_bitop3_b32 v2, v3, v2, 32 bitop3:0x6c
	s_add_u32 s26, s14, s26
	s_mul_hi_i32 s31, s24, s50
	s_mul_i32 s30, s24, s50
	v_add_u32_e32 v1, v217, v1
	v_ashrrev_i32_e32 v4, 31, v2
	s_addc_u32 s27, s15, s27
	s_ashr_i32 s25, s24, 31
	s_lshl_b64 s[30:31], s[30:31], 1
	v_ashrrev_i32_e32 v1, 6, v1
	v_lshrrev_b32_e32 v4, 26, v4
	s_add_u32 s36, s12, s30
	v_lshlrev_b32_e32 v3, 3, v1
	v_add_u32_e32 v4, v2, v4
	s_addc_u32 s37, s13, s31
	s_add_i32 s30, s28, 0x80
	v_and_b32_e32 v3, -16, v3
	v_ashrrev_i32_e32 v5, 6, v4
	s_mul_hi_i32 s31, s30, s50
	s_mul_i32 s30, s30, s50
	v_add_u32_e32 v3, v5, v3
	s_lshl_b64 s[30:31], s[30:31], 1
	v_mul_lo_u32 v138, v3, s50
	v_and_b32_e32 v3, 48, v217
	s_add_u32 s38, s14, s30
	v_lshlrev_b32_e32 v8, 6, v217
	s_movk_i32 s30, 0x3c0
	s_addc_u32 s39, s15, s31
	v_lshlrev_b32_e32 v10, 13, v0
	v_and_or_b32 v0, v8, s30, v3
	s_lshl_b64 s[30:31], s[28:29], 1
	s_add_u32 s40, s30, 0x80
	s_addc_u32 s41, s31, 0
	s_mul_i32 s41, s50, s41
	s_mul_hi_u32 s42, s50, s40
	s_add_i32 s42, s42, s41
	s_mul_i32 s40, s50, s40
	s_add_u32 s40, s14, s40
	s_addc_u32 s41, s15, s42
	s_lshl_b64 s[46:47], s[24:25], 1
	s_add_u32 s42, s46, 0x80
	s_addc_u32 s43, s47, 0
	s_mul_i32 s43, s50, s43
	s_mul_hi_u32 s44, s50, s42
	s_add_i32 s44, s44, s43
	s_mul_i32 s42, s50, s42
	s_add_u32 s42, s12, s42
	s_addc_u32 s43, s13, s44
	s_add_u32 s44, s30, 0x180
	s_addc_u32 s45, s31, 0
	v_lshlrev_b32_e32 v1, 5, v1
	s_mul_i32 s45, s50, s45
	s_mul_hi_u32 vcc_lo, s50, s44
	v_and_b32_e32 v137, 32, v1
	v_and_b32_e32 v1, 0xc0, v4
	s_add_i32 vcc_lo, vcc_lo, s45
	s_mul_i32 s44, s50, s44
	v_sub_u32_e32 v1, v2, v1
	s_add_u32 s44, s14, s44
	v_ashrrev_i16_sdwa v1, v212, sext(v1) dst_sel:DWORD dst_unused:UNUSED_PAD src0_sel:DWORD src1_sel:BYTE_0
	v_and_b32_e32 v2, 15, v217
	s_addc_u32 s45, s15, vcc_lo
	v_bfe_i32 v139, v1, 0, 16
	v_lshlrev_b32_e32 v1, 6, v2
	v_lshlrev_b32_e32 v2, 2, v217
	s_add_u32 s46, s46, 0x180
	v_and_b32_e32 v2, 32, v2
	s_addc_u32 s47, s47, 0
	v_bitop3_b32 v1, v1, v2, v3 bitop3:0x36
	v_xad_u32 v2, v0, v2, 0
	v_add3_u32 v0, v138, v137, v139
	s_mul_i32 s47, s50, s47
	s_mul_hi_u32 vcc_lo, s50, s46
	v_add_u32_e32 v4, s83, v1
	v_add_u32_e32 v5, s84, v1
	v_add_u32_e32 v6, s85, v1
	v_add_u32_e32 v7, s86, v1
	v_add_u32_e32 v11, 0, v1
	v_ashrrev_i32_e32 v1, 31, v0
	s_add_i32 vcc_lo, vcc_lo, s47
	s_mul_i32 s46, s50, s46
	v_and_b32_e32 v9, 0x3000, v8
	v_or_b32_e32 v3, 0x800, v10
	v_or_b32_e32 v8, 0x1000, v10
	v_or_b32_e32 v12, 0x1800, v10
	s_waitcnt lgkmcnt(0)
	v_lshlrev_b64 v[128:129], 1, v[0:1]
	s_add_u32 s46, s12, s46
	v_mov_b32_e32 v0, 0
	s_addc_u32 s47, s13, vcc_lo
	s_mov_b32 vcc_lo, 0
	v_add_u32_e32 v141, v4, v9
	v_add_u32_e32 v133, v11, v10
	v_add_u32_e32 v132, v2, v3
	v_add_u32_e32 v131, v2, v8
	v_add_u32_e32 v130, v2, v12
	v_add_u32_e32 v140, v5, v9
	v_add_u32_e32 v136, v6, v9
	v_add_u32_e32 v134, v7, v9
	v_mov_b32_e32 v234, v133
	v_mov_b32_e32 v235, v141
	v_mov_b32_e32 v236, v128
	v_add_u32_e32 v237, s72, v128
	v_lshrrev_b32_e32 v238, 6, v210
	v_lshlrev_b32_e32 v238, 10, v238
	s_lshr_b32 s41, s50, 7
	s_add_i32 s41, s41, -2
	v_readfirstlane_b32 s40, v238
	s_add_u32 s8, s8, 0x80
	s_addc_u32 s9, s9, 0
	s_bitcmp0_b32 s101, 31
	s_cbranch_scc1 .Lmy_noextra
	s_add_u32 m0, s40, 0xc000
	s_nop 0
	global_load_lds_dwordx4 v236, s[8:9]
	s_add_u32 m0, s40, 0xe000
	s_nop 0
	global_load_lds_dwordx4 v237, s[8:9]
	s_bitset0_b32 s101, 31
.Lmy_noextra:
	s_add_u32 s8, s8, 0x80
	s_addc_u32 s9, s9, 0
	s_add_u32 s36, s36, 0x100
	s_addc_u32 s37, s37, 0
	s_add_u32 s26, s26, 0x100
	s_addc_u32 s27, s27, 0
	s_add_u32 s38, s38, 0x100
	s_addc_u32 s39, s39, 0
	v_mov_b32_e32 v1, v0
	v_mov_b32_e32 v2, v0
	v_mov_b32_e32 v3, v0
	v_mov_b32_e32 v4, v0
	v_mov_b32_e32 v5, v0
	v_mov_b32_e32 v6, v0
	v_mov_b32_e32 v7, v0
	v_mov_b32_e32 v8, v0
	v_mov_b32_e32 v9, v0
	v_mov_b32_e32 v10, v0
	v_mov_b32_e32 v11, v0
	v_mov_b32_e32 v12, v0
	v_mov_b32_e32 v13, v0
	v_mov_b32_e32 v14, v0
	v_mov_b32_e32 v15, v0
	v_mov_b32_e32 v16, v0
	v_mov_b32_e32 v17, v0
	v_mov_b32_e32 v18, v0
	v_mov_b32_e32 v19, v0
	v_mov_b32_e32 v20, v0
	v_mov_b32_e32 v21, v0
	v_mov_b32_e32 v22, v0
	v_mov_b32_e32 v23, v0
	v_mov_b32_e32 v24, v0
	v_mov_b32_e32 v25, v0
	v_mov_b32_e32 v26, v0
	v_mov_b32_e32 v27, v0
	v_mov_b32_e32 v28, v0
	v_mov_b32_e32 v29, v0
	v_mov_b32_e32 v30, v0
	v_mov_b32_e32 v31, v0
	v_mov_b32_e32 v32, v0
	v_mov_b32_e32 v33, v0
	v_mov_b32_e32 v34, v0
	v_mov_b32_e32 v35, v0
	v_mov_b32_e32 v36, v0
	v_mov_b32_e32 v37, v0
	v_mov_b32_e32 v38, v0
	v_mov_b32_e32 v39, v0
	v_mov_b32_e32 v40, v0
	v_mov_b32_e32 v41, v0
	v_mov_b32_e32 v42, v0
	v_mov_b32_e32 v43, v0
	v_mov_b32_e32 v44, v0
	v_mov_b32_e32 v45, v0
	v_mov_b32_e32 v46, v0
	v_mov_b32_e32 v47, v0
	v_mov_b32_e32 v48, v0
	v_mov_b32_e32 v49, v0
	v_mov_b32_e32 v50, v0
	v_mov_b32_e32 v51, v0
	v_mov_b32_e32 v52, v0
	v_mov_b32_e32 v53, v0
	v_mov_b32_e32 v54, v0
	v_mov_b32_e32 v55, v0
	v_mov_b32_e32 v56, v0
	v_mov_b32_e32 v57, v0
	v_mov_b32_e32 v58, v0
	v_mov_b32_e32 v59, v0
	v_mov_b32_e32 v60, v0
	v_mov_b32_e32 v61, v0
	v_mov_b32_e32 v62, v0
	v_mov_b32_e32 v63, v0
; #define STAGE(P, BASE, br, kt) do { const u16* _gb = (BASE) + ((size_t)(br) * K + (size_t)(kt) * BK); \
;     __builtin_amdgcn_global_load_lds((const unsigned*)(_gb + goff0), (unsigned*)((char*)(P) + tid * 16), 16, 0, 0); \
;     __builtin_amdgcn_global_load_lds((const unsigned*)(_gb + (size_t)64 * K + goff0), (unsigned*)((char*)(P) + tid * 16 + 8192), 16, 0, 0); } while (0)
; #define LDA(dst, b, h) _Pragma("unroll") for (int m = 0; m < 4; ++m) _Pragma("unroll") for (int k = 0; k < 2; ++k) \
;     dst[m][k] = *reinterpret_cast<const bf16x8*>((char*)SA(b, h) + lds_byte(wr * 64 + m * 16 + fr, k * 32 + fq * 8))
; #define LDB(dst, b, h) _Pragma("unroll") for (int n = 0; n < 2; ++n) _Pragma("unroll") for (int k = 0; k < 2; ++k) \
;     dst[n][k] = *reinterpret_cast<const bf16x8*>((char*)SB(b, h) + lds_byte(wc * 32 + n * 16 + fr, k * 32 + fq * 8))
; #define MMA(ai, bj, At, Bt_) do { __builtin_amdgcn_s_setprio(1); \
;     _Pragma("unroll") for (int m = 0; m < 4; ++m) _Pragma("unroll") for (int n = 0; n < 2; ++n) _Pragma("unroll") for (int k = 0; k < 2; ++k) \
;       acc[ai][bj][m][n] = __builtin_amdgcn_mfma_f32_16x16x32_bf16(Bt_[n][k], At[m][k], acc[ai][bj][m][n], 0, 0, 0); \
;     __builtin_amdgcn_s_setprio(0); } while (0)
; #define WAIT_V(n) asm volatile("s_waitcnt vmcnt(" #n ")" ::: "memory")
; #define WAIT_L(n) asm volatile("s_waitcnt lgkmcnt(" #n ")" ::: "memory")
; __device__ __forceinline__ void gemm_phase(KP p, char* shmc, const u16* __restrict__ A,
;                                            const u16* __restrict__ Bt, const int N, const int K, const int mode,
;                                            const float* __restrict__ xin, const float resw) {
;     ...
;           for (int n = 0; n < 2; ++n) acc[a][b][m][n] = f32x4{0.f, 0.f, 0.f, 0.f};
;     bf16x8 At[4][2], B0[2][2], B1[2][2];
;     WAIT_V(0);
;     if (wr == 1) BAR;
;     BAR;
;     for (int t = 0; t < nt - 2; t += 2) {
;       LDB(B0, 0, 0); SCHED; LDA(At, 0, 0); STAGE(SA(1, 1), A, brow + HALF, t + 1);
;       WAIT_L(8); BAR; WAIT_L(0); MMA(0, 0, At, B0); BAR; SCHED;
;       LDB(B1, 0, 1); STAGE(SB(0, 0), Bt, bcol, t + 2);
;       BAR; WAIT_L(0); MMA(0, 1, At, B1); BAR;
;       LDA(At, 0, 1); STAGE(SA(0, 0), A, brow, t + 2);
;       BAR; WAIT_L(0); MMA(1, 0, At, B0); BAR; SCHED;
;       STAGE(SB(0, 1), Bt, bcol + HALF, t + 2);
;       WAIT_V(6); BAR; MMA(1, 1, At, B1); BAR;
	v_mov_b32_e32 v64, v0
	v_mov_b32_e32 v65, v0
	v_mov_b32_e32 v66, v0
	v_mov_b32_e32 v67, v0
	v_mov_b32_e32 v68, v0
	v_mov_b32_e32 v69, v0
	v_mov_b32_e32 v70, v0
	v_mov_b32_e32 v71, v0
	v_mov_b32_e32 v72, v0
	v_mov_b32_e32 v73, v0
	v_mov_b32_e32 v74, v0
	v_mov_b32_e32 v75, v0
	v_mov_b32_e32 v76, v0
	v_mov_b32_e32 v77, v0
	v_mov_b32_e32 v78, v0
	v_mov_b32_e32 v79, v0
	v_mov_b32_e32 v80, v0
	v_mov_b32_e32 v81, v0
	v_mov_b32_e32 v82, v0
	v_mov_b32_e32 v83, v0
	v_mov_b32_e32 v84, v0
	v_mov_b32_e32 v85, v0
	v_mov_b32_e32 v86, v0
	v_mov_b32_e32 v87, v0
	v_mov_b32_e32 v88, v0
	v_mov_b32_e32 v89, v0
	v_mov_b32_e32 v90, v0
	v_mov_b32_e32 v91, v0
	v_mov_b32_e32 v92, v0
	v_mov_b32_e32 v93, v0
	v_mov_b32_e32 v94, v0
	v_mov_b32_e32 v95, v0
	v_mov_b32_e32 v96, v0
	v_mov_b32_e32 v97, v0
	v_mov_b32_e32 v98, v0
	v_mov_b32_e32 v99, v0
	v_mov_b32_e32 v100, v0
	v_mov_b32_e32 v101, v0
	v_mov_b32_e32 v102, v0
	v_mov_b32_e32 v103, v0
	v_mov_b32_e32 v104, v0
	v_mov_b32_e32 v105, v0
	v_mov_b32_e32 v106, v0
	v_mov_b32_e32 v107, v0
	v_mov_b32_e32 v108, v0
	v_mov_b32_e32 v109, v0
	v_mov_b32_e32 v110, v0
	v_mov_b32_e32 v111, v0
	v_mov_b32_e32 v112, v0
	v_mov_b32_e32 v113, v0
	v_mov_b32_e32 v114, v0
	v_mov_b32_e32 v115, v0
	v_mov_b32_e32 v116, v0
	v_mov_b32_e32 v117, v0
	v_mov_b32_e32 v118, v0
	v_mov_b32_e32 v119, v0
	v_mov_b32_e32 v120, v0
	v_mov_b32_e32 v121, v0
	v_mov_b32_e32 v122, v0
	v_mov_b32_e32 v123, v0
	v_mov_b32_e32 v124, v0
	v_mov_b32_e32 v125, v0
	v_mov_b32_e32 v126, v0
	v_mov_b32_e32 v127, v0
	s_waitcnt vmcnt(0)
	s_barrier
	ds_read_b128 v[194:197], v235 offset:0
	ds_read_b128 v[198:201], v235 offset:1024
	ds_read_b128 v[202:205], v235 offset:2048
	ds_read_b128 v[206:209], v235 offset:3072
	ds_read_b128 v[128:131], v234 offset:0
	ds_read_b128 v[132:135], v234 offset:1024
	ds_read_b128 v[136:139], v234 offset:2048
	ds_read_b128 v[140:143], v234 offset:3072
	ds_read_b128 v[144:147], v234 offset:4096
	ds_read_b128 v[148:151], v234 offset:5120
	ds_read_b128 v[152:155], v234 offset:6144
	ds_read_b128 v[156:159], v234 offset:7168
	s_waitcnt lgkmcnt(0)
	s_barrier
	s_add_u32 m0, s40, 0x0
	s_nop 0
	global_load_lds_dwordx4 v236, s[36:37]
	s_add_u32 m0, s40, 0x2000
	s_nop 0
	global_load_lds_dwordx4 v237, s[36:37]
	s_add_u32 s36, s36, 0x80
	s_addc_u32 s37, s37, 0
	s_cmp_lg_u32 s49, 2
	s_cbranch_scc1 .Lmy_kloop
	s_sub_i32 s42, s73, 8
	s_cmp_lt_u32 s42, 4
	s_cbranch_scc1 .Lmy_kloop_sw
.Lmy_kloop:
	s_waitcnt vmcnt(12) lgkmcnt(0)
	s_barrier
	v_mfma_f32_16x16x32_bf16 v[120:123], v[194:197], v[128:131], v[120:123]
	v_mfma_f32_16x16x32_bf16 v[112:115], v[202:205], v[128:131], v[112:115]
	ds_read_b128 v[218:221], v235 offset:16384
	v_mfma_f32_16x16x32_bf16 v[104:107], v[194:197], v[136:139], v[104:107]
	ds_read_b128 v[222:225], v235 offset:17408
	v_mfma_f32_16x16x32_bf16 v[96:99], v[202:205], v[136:139], v[96:99]
	ds_read_b128 v[226:229], v235 offset:18432
	s_add_u32 m0, s40, 0x10000
	v_mfma_f32_16x16x32_bf16 v[88:91], v[194:197], v[144:147], v[88:91]
	ds_read_b128 v[230:233], v235 offset:19456
	v_mfma_f32_16x16x32_bf16 v[80:83], v[202:205], v[144:147], v[80:83]
	global_load_lds_dwordx4 v236, s[26:27]
	v_mfma_f32_16x16x32_bf16 v[72:75], v[194:197], v[152:155], v[72:75]
	v_mfma_f32_16x16x32_bf16 v[64:67], v[202:205], v[152:155], v[64:67]
	s_add_u32 m0, s40, 0x12000
	v_mfma_f32_16x16x32_bf16 v[120:123], v[198:201], v[132:135], v[120:123]
	v_mfma_f32_16x16x32_bf16 v[112:115], v[206:209], v[132:135], v[112:115]
	global_load_lds_dwordx4 v237, s[26:27]
	v_mfma_f32_16x16x32_bf16 v[104:107], v[198:201], v[140:143], v[104:107]
	v_mfma_f32_16x16x32_bf16 v[96:99], v[206:209], v[140:143], v[96:99]
	s_add_u32 s26, s26, 0x80
	s_addc_u32 s27, s27, 0
	v_mfma_f32_16x16x32_bf16 v[88:91], v[198:201], v[148:151], v[88:91]
	v_mfma_f32_16x16x32_bf16 v[80:83], v[206:209], v[148:151], v[80:83]
	v_mfma_f32_16x16x32_bf16 v[72:75], v[198:201], v[156:159], v[72:75]
	v_mfma_f32_16x16x32_bf16 v[64:67], v[206:209], v[156:159], v[64:67]
	s_waitcnt vmcnt(12) lgkmcnt(0)
	s_barrier
	v_mfma_f32_16x16x32_bf16 v[124:127], v[218:221], v[128:131], v[124:127]
	v_mfma_f32_16x16x32_bf16 v[116:119], v[226:229], v[128:131], v[116:119]
	ds_read_b128 v[160:163], v234 offset:16384
	v_mfma_f32_16x16x32_bf16 v[108:111], v[218:221], v[136:139], v[108:111]
	ds_read_b128 v[164:167], v234 offset:17408
	v_mfma_f32_16x16x32_bf16 v[100:103], v[226:229], v[136:139], v[100:103]
	ds_read_b128 v[168:171], v234 offset:18432
	s_add_u32 m0, s40, 0x14000
	v_mfma_f32_16x16x32_bf16 v[92:95], v[218:221], v[144:147], v[92:95]
	ds_read_b128 v[172:175], v234 offset:19456
	v_mfma_f32_16x16x32_bf16 v[84:87], v[226:229], v[144:147], v[84:87]
	ds_read_b128 v[176:179], v234 offset:20480
	global_load_lds_dwordx4 v236, s[38:39]
	v_mfma_f32_16x16x32_bf16 v[76:79], v[218:221], v[152:155], v[76:79]
	ds_read_b128 v[180:183], v234 offset:21504
	v_mfma_f32_16x16x32_bf16 v[68:71], v[226:229], v[152:155], v[68:71]
	ds_read_b128 v[184:187], v234 offset:22528
	s_add_u32 m0, s40, 0x16000
	v_mfma_f32_16x16x32_bf16 v[124:127], v[222:225], v[132:135], v[124:127]
	ds_read_b128 v[188:191], v234 offset:23552
	v_mfma_f32_16x16x32_bf16 v[116:119], v[230:233], v[132:135], v[116:119]
	global_load_lds_dwordx4 v237, s[38:39]
	v_mfma_f32_16x16x32_bf16 v[108:111], v[222:225], v[140:143], v[108:111]
	v_mfma_f32_16x16x32_bf16 v[100:103], v[230:233], v[140:143], v[100:103]
	s_add_u32 s38, s38, 0x80
	s_addc_u32 s39, s39, 0
	v_mfma_f32_16x16x32_bf16 v[92:95], v[222:225], v[148:151], v[92:95]
	v_mfma_f32_16x16x32_bf16 v[84:87], v[230:233], v[148:151], v[84:87]
	v_mfma_f32_16x16x32_bf16 v[76:79], v[222:225], v[156:159], v[76:79]
	v_mfma_f32_16x16x32_bf16 v[68:71], v[230:233], v[156:159], v[68:71]
	s_waitcnt vmcnt(12) lgkmcnt(0)
	s_barrier
; #define STAGE(P, BASE, br, kt) do { const u16* _gb = (BASE) + ((size_t)(br) * K + (size_t)(kt) * BK); \
;     __builtin_amdgcn_global_load_lds((const unsigned*)(_gb + goff0), (unsigned*)((char*)(P) + tid * 16), 16, 0, 0); \
;     __builtin_amdgcn_global_load_lds((const unsigned*)(_gb + (size_t)64 * K + goff0), (unsigned*)((char*)(P) + tid * 16 + 8192), 16, 0, 0); } while (0)
; #define LDA(dst, b, h) _Pragma("unroll") for (int m = 0; m < 4; ++m) _Pragma("unroll") for (int k = 0; k < 2; ++k) \
;     dst[m][k] = *reinterpret_cast<const bf16x8*>((char*)SA(b, h) + lds_byte(wr * 64 + m * 16 + fr, k * 32 + fq * 8))
; #define LDB(dst, b, h) _Pragma("unroll") for (int n = 0; n < 2; ++n) _Pragma("unroll") for (int k = 0; k < 2; ++k) \
;     dst[n][k] = *reinterpret_cast<const bf16x8*>((char*)SB(b, h) + lds_byte(wc * 32 + n * 16 + fr, k * 32 + fq * 8))
; #define WAIT_V(n) asm volatile("s_waitcnt vmcnt(" #n ")" ::: "memory")
; #define WAIT_L(n) asm volatile("s_waitcnt lgkmcnt(" #n ")" ::: "memory")
; #define BAR __builtin_amdgcn_s_barrier()
; #define SCHED __builtin_amdgcn_sched_barrier(0)
; __device__ __forceinline__ void gemm_phase(KP p, char* shmc, const u16* __restrict__ A,
;                                            const u16* __restrict__ Bt, const int N, const int K, const int mode,
;                                            const float* __restrict__ xin, const float resw) {
;     ...
;     for (int t = 0; t < nt - 2; t += 2) {
;       LDB(B0, 0, 0); SCHED; LDA(At, 0, 0); STAGE(SA(1, 1), A, brow + HALF, t + 1);
;       WAIT_L(8); BAR; WAIT_L(0); MMA(0, 0, At, B0); BAR; SCHED;
;       LDB(B1, 0, 1); STAGE(SB(0, 0), Bt, bcol, t + 2);
;       BAR; WAIT_L(0); MMA(0, 1, At, B1); BAR;
;       LDA(At, 0, 1); STAGE(SA(0, 0), A, brow, t + 2);
;       BAR; WAIT_L(0); MMA(1, 0, At, B0); BAR; SCHED;
;       STAGE(SB(0, 1), Bt, bcol + HALF, t + 2);
;       WAIT_V(6); BAR; MMA(1, 1, At, B1); BAR;
;       LDB(B0, 1, 0); SCHED; LDA(At, 1, 0); STAGE(SA(0, 1), A, brow + HALF, t + 2);
;       WAIT_L(8); BAR; WAIT_L(0); MMA(0, 0, At, B0); BAR; SCHED;
;       LDB(B1, 1, 1); STAGE(SB(1, 0), Bt, bcol, t + 3);
;       BAR; WAIT_L(0); MMA(0, 1, At, B1); BAR;
;       LDA(At, 1, 1); STAGE(SA(1, 0), A, brow, t + 3);
;       BAR; WAIT_L(0); MMA(1, 0, At, B0); BAR; SCHED;
;       STAGE(SB(1, 1), Bt, bcol + HALF, t + 3);
;       WAIT_V(6); BAR; MMA(1, 1, At, B1); BAR;
;     }
	v_mfma_f32_16x16x32_bf16 v[56:59], v[194:197], v[160:163], v[56:59]
	v_mfma_f32_16x16x32_bf16 v[48:51], v[202:205], v[160:163], v[48:51]
	ds_read_b128 v[128:131], v234 offset:32768
	v_mfma_f32_16x16x32_bf16 v[40:43], v[194:197], v[168:171], v[40:43]
	ds_read_b128 v[132:135], v234 offset:33792
	v_mfma_f32_16x16x32_bf16 v[32:35], v[202:205], v[168:171], v[32:35]
	ds_read_b128 v[136:139], v234 offset:34816
	s_add_u32 m0, s40, 0x4000
	v_mfma_f32_16x16x32_bf16 v[24:27], v[194:197], v[176:179], v[24:27]
	ds_read_b128 v[140:143], v234 offset:35840
	v_mfma_f32_16x16x32_bf16 v[16:19], v[202:205], v[176:179], v[16:19]
	ds_read_b128 v[144:147], v234 offset:36864
	global_load_lds_dwordx4 v236, s[8:9]
	v_mfma_f32_16x16x32_bf16 v[8:11], v[194:197], v[184:187], v[8:11]
	ds_read_b128 v[148:151], v234 offset:37888
	v_mfma_f32_16x16x32_bf16 v[0:3], v[202:205], v[184:187], v[0:3]
	ds_read_b128 v[152:155], v234 offset:38912
	s_add_u32 m0, s40, 0x6000
	v_mfma_f32_16x16x32_bf16 v[56:59], v[198:201], v[164:167], v[56:59]
	ds_read_b128 v[156:159], v234 offset:39936
	v_mfma_f32_16x16x32_bf16 v[48:51], v[206:209], v[164:167], v[48:51]
	global_load_lds_dwordx4 v237, s[8:9]
	v_mfma_f32_16x16x32_bf16 v[40:43], v[198:201], v[172:175], v[40:43]
	v_mfma_f32_16x16x32_bf16 v[32:35], v[206:209], v[172:175], v[32:35]
	s_add_u32 s8, s8, 0x80
	s_addc_u32 s9, s9, 0
	v_mfma_f32_16x16x32_bf16 v[24:27], v[198:201], v[180:183], v[24:27]
	v_mfma_f32_16x16x32_bf16 v[16:19], v[206:209], v[180:183], v[16:19]
	v_mfma_f32_16x16x32_bf16 v[8:11], v[198:201], v[188:191], v[8:11]
	v_mfma_f32_16x16x32_bf16 v[0:3], v[206:209], v[188:191], v[0:3]
	s_waitcnt vmcnt(12) lgkmcnt(0)
	s_barrier
	v_mfma_f32_16x16x32_bf16 v[60:63], v[218:221], v[160:163], v[60:63]
	v_mfma_f32_16x16x32_bf16 v[52:55], v[226:229], v[160:163], v[52:55]
	ds_read_b128 v[194:197], v235 offset:32768
	v_mfma_f32_16x16x32_bf16 v[44:47], v[218:221], v[168:171], v[44:47]
	ds_read_b128 v[198:201], v235 offset:33792
	v_mfma_f32_16x16x32_bf16 v[36:39], v[226:229], v[168:171], v[36:39]
	ds_read_b128 v[202:205], v235 offset:34816
	s_add_u32 m0, s40, 0x8000
	v_mfma_f32_16x16x32_bf16 v[28:31], v[218:221], v[176:179], v[28:31]
	ds_read_b128 v[206:209], v235 offset:35840
	v_mfma_f32_16x16x32_bf16 v[20:23], v[226:229], v[176:179], v[20:23]
	global_load_lds_dwordx4 v236, s[36:37]
	v_mfma_f32_16x16x32_bf16 v[12:15], v[218:221], v[184:187], v[12:15]
	v_mfma_f32_16x16x32_bf16 v[4:7], v[226:229], v[184:187], v[4:7]
	s_add_u32 m0, s40, 0xa000
	v_mfma_f32_16x16x32_bf16 v[60:63], v[222:225], v[164:167], v[60:63]
	v_mfma_f32_16x16x32_bf16 v[52:55], v[230:233], v[164:167], v[52:55]
	global_load_lds_dwordx4 v237, s[36:37]
	v_mfma_f32_16x16x32_bf16 v[44:47], v[222:225], v[172:175], v[44:47]
	v_mfma_f32_16x16x32_bf16 v[36:39], v[230:233], v[172:175], v[36:39]
	s_add_u32 s36, s36, 0x80
	s_addc_u32 s37, s37, 0
	v_mfma_f32_16x16x32_bf16 v[28:31], v[222:225], v[180:183], v[28:31]
	v_mfma_f32_16x16x32_bf16 v[20:23], v[230:233], v[180:183], v[20:23]
	v_mfma_f32_16x16x32_bf16 v[12:15], v[222:225], v[188:191], v[12:15]
	v_mfma_f32_16x16x32_bf16 v[4:7], v[230:233], v[188:191], v[4:7]
	s_waitcnt vmcnt(12) lgkmcnt(0)
	s_barrier
	v_mfma_f32_16x16x32_bf16 v[120:123], v[194:197], v[128:131], v[120:123]
	v_mfma_f32_16x16x32_bf16 v[112:115], v[202:205], v[128:131], v[112:115]
	ds_read_b128 v[218:221], v235 offset:49152
	v_mfma_f32_16x16x32_bf16 v[104:107], v[194:197], v[136:139], v[104:107]
	ds_read_b128 v[222:225], v235 offset:50176
	v_mfma_f32_16x16x32_bf16 v[96:99], v[202:205], v[136:139], v[96:99]
	ds_read_b128 v[226:229], v235 offset:51200
	s_add_u32 m0, s40, 0x18000
	v_mfma_f32_16x16x32_bf16 v[88:91], v[194:197], v[144:147], v[88:91]
	ds_read_b128 v[230:233], v235 offset:52224
	v_mfma_f32_16x16x32_bf16 v[80:83], v[202:205], v[144:147], v[80:83]
	global_load_lds_dwordx4 v236, s[26:27]
	v_mfma_f32_16x16x32_bf16 v[72:75], v[194:197], v[152:155], v[72:75]
	v_mfma_f32_16x16x32_bf16 v[64:67], v[202:205], v[152:155], v[64:67]
	s_add_u32 m0, s40, 0x1a000
	v_mfma_f32_16x16x32_bf16 v[120:123], v[198:201], v[132:135], v[120:123]
	v_mfma_f32_16x16x32_bf16 v[112:115], v[206:209], v[132:135], v[112:115]
	global_load_lds_dwordx4 v237, s[26:27]
	v_mfma_f32_16x16x32_bf16 v[104:107], v[198:201], v[140:143], v[104:107]
	v_mfma_f32_16x16x32_bf16 v[96:99], v[206:209], v[140:143], v[96:99]
	s_add_u32 s26, s26, 0x80
	s_addc_u32 s27, s27, 0
	v_mfma_f32_16x16x32_bf16 v[88:91], v[198:201], v[148:151], v[88:91]
	v_mfma_f32_16x16x32_bf16 v[80:83], v[206:209], v[148:151], v[80:83]
	v_mfma_f32_16x16x32_bf16 v[72:75], v[198:201], v[156:159], v[72:75]
	v_mfma_f32_16x16x32_bf16 v[64:67], v[206:209], v[156:159], v[64:67]
	s_waitcnt vmcnt(12) lgkmcnt(0)
	s_barrier
	v_mfma_f32_16x16x32_bf16 v[124:127], v[218:221], v[128:131], v[124:127]
	v_mfma_f32_16x16x32_bf16 v[116:119], v[226:229], v[128:131], v[116:119]
	ds_read_b128 v[160:163], v234 offset:49152
	v_mfma_f32_16x16x32_bf16 v[108:111], v[218:221], v[136:139], v[108:111]
	ds_read_b128 v[164:167], v234 offset:50176
	v_mfma_f32_16x16x32_bf16 v[100:103], v[226:229], v[136:139], v[100:103]
	ds_read_b128 v[168:171], v234 offset:51200
	s_add_u32 m0, s40, 0x1c000
	v_mfma_f32_16x16x32_bf16 v[92:95], v[218:221], v[144:147], v[92:95]
	ds_read_b128 v[172:175], v234 offset:52224
	v_mfma_f32_16x16x32_bf16 v[84:87], v[226:229], v[144:147], v[84:87]
	ds_read_b128 v[176:179], v234 offset:53248
	global_load_lds_dwordx4 v236, s[38:39]
	v_mfma_f32_16x16x32_bf16 v[76:79], v[218:221], v[152:155], v[76:79]
	ds_read_b128 v[180:183], v234 offset:54272
	v_mfma_f32_16x16x32_bf16 v[68:71], v[226:229], v[152:155], v[68:71]
	ds_read_b128 v[184:187], v234 offset:55296
	s_add_u32 m0, s40, 0x1e000
	v_mfma_f32_16x16x32_bf16 v[124:127], v[222:225], v[132:135], v[124:127]
	ds_read_b128 v[188:191], v234 offset:56320
	v_mfma_f32_16x16x32_bf16 v[116:119], v[230:233], v[132:135], v[116:119]
	global_load_lds_dwordx4 v237, s[38:39]
	v_mfma_f32_16x16x32_bf16 v[108:111], v[222:225], v[140:143], v[108:111]
	v_mfma_f32_16x16x32_bf16 v[100:103], v[230:233], v[140:143], v[100:103]
	s_add_u32 s38, s38, 0x80
	s_addc_u32 s39, s39, 0
	v_mfma_f32_16x16x32_bf16 v[92:95], v[222:225], v[148:151], v[92:95]
	v_mfma_f32_16x16x32_bf16 v[84:87], v[230:233], v[148:151], v[84:87]
	v_mfma_f32_16x16x32_bf16 v[76:79], v[222:225], v[156:159], v[76:79]
	v_mfma_f32_16x16x32_bf16 v[68:71], v[230:233], v[156:159], v[68:71]
	s_waitcnt vmcnt(12) lgkmcnt(0)
	s_barrier
; #define STAGE(P, BASE, br, kt) do { const u16* _gb = (BASE) + ((size_t)(br) * K + (size_t)(kt) * BK); \
;     __builtin_amdgcn_global_load_lds((const unsigned*)(_gb + goff0), (unsigned*)((char*)(P) + tid * 16), 16, 0, 0); \
;     __builtin_amdgcn_global_load_lds((const unsigned*)(_gb + (size_t)64 * K + goff0), (unsigned*)((char*)(P) + tid * 16 + 8192), 16, 0, 0); } while (0)
; #define LDA(dst, b, h) _Pragma("unroll") for (int m = 0; m < 4; ++m) _Pragma("unroll") for (int k = 0; k < 2; ++k) \
;     dst[m][k] = *reinterpret_cast<const bf16x8*>((char*)SA(b, h) + lds_byte(wr * 64 + m * 16 + fr, k * 32 + fq * 8))
; #define LDB(dst, b, h) _Pragma("unroll") for (int n = 0; n < 2; ++n) _Pragma("unroll") for (int k = 0; k < 2; ++k) \
;     dst[n][k] = *reinterpret_cast<const bf16x8*>((char*)SB(b, h) + lds_byte(wc * 32 + n * 16 + fr, k * 32 + fq * 8))
; #define MMA(ai, bj, At, Bt_) do { __builtin_amdgcn_s_setprio(1); \
;     _Pragma("unroll") for (int m = 0; m < 4; ++m) _Pragma("unroll") for (int n = 0; n < 2; ++n) _Pragma("unroll") for (int k = 0; k < 2; ++k) \
;       acc[ai][bj][m][n] = __builtin_amdgcn_mfma_f32_16x16x32_bf16(Bt_[n][k], At[m][k], acc[ai][bj][m][n], 0, 0, 0); \
;     __builtin_amdgcn_s_setprio(0); } while (0)
; #define BAR __builtin_amdgcn_s_barrier()
; __device__ __forceinline__ void gemm_phase(KP p, char* shmc, const u16* __restrict__ A,
;                                            const u16* __restrict__ Bt, const int N, const int K, const int mode,
;                                            const float* __restrict__ xin, const float resw) {
;     ...
;       WAIT_V(6); BAR; MMA(1, 1, At, B1); BAR;
;       LDB(B0, 1, 0); SCHED; LDA(At, 1, 0); STAGE(SA(0, 1), A, brow + HALF, t + 2);
;       WAIT_L(8); BAR; WAIT_L(0); MMA(0, 0, At, B0); BAR; SCHED;
;       LDB(B1, 1, 1); STAGE(SB(1, 0), Bt, bcol, t + 3);
;       BAR; WAIT_L(0); MMA(0, 1, At, B1); BAR;
;       LDA(At, 1, 1); STAGE(SA(1, 0), A, brow, t + 3);
;       BAR; WAIT_L(0); MMA(1, 0, At, B0); BAR; SCHED;
;       STAGE(SB(1, 1), Bt, bcol + HALF, t + 3);
;       WAIT_V(6); BAR; MMA(1, 1, At, B1); BAR;
;     }
;     { LDB(B0, 0, 0); LDA(At, 0, 0); STAGE(SA(1, 1), A, brow + HALF, nt - 1);
;       BAR; WAIT_L(0); MMA(0, 0, At, B0); BAR;
;       LDB(B1, 0, 1); BAR; WAIT_L(0); MMA(0, 1, At, B1); BAR;
;       LDA(At, 0, 1); WAIT_V(4); BAR; WAIT_L(0); MMA(1, 0, At, B0); MMA(1, 1, At, B1); BAR; }
	v_mfma_f32_16x16x32_bf16 v[56:59], v[194:197], v[160:163], v[56:59]
	v_mfma_f32_16x16x32_bf16 v[48:51], v[202:205], v[160:163], v[48:51]
	ds_read_b128 v[128:131], v234 offset:0
	v_mfma_f32_16x16x32_bf16 v[40:43], v[194:197], v[168:171], v[40:43]
	ds_read_b128 v[132:135], v234 offset:1024
	v_mfma_f32_16x16x32_bf16 v[32:35], v[202:205], v[168:171], v[32:35]
	ds_read_b128 v[136:139], v234 offset:2048
	s_add_u32 m0, s40, 0xc000
	v_mfma_f32_16x16x32_bf16 v[24:27], v[194:197], v[176:179], v[24:27]
	ds_read_b128 v[140:143], v234 offset:3072
	v_mfma_f32_16x16x32_bf16 v[16:19], v[202:205], v[176:179], v[16:19]
	ds_read_b128 v[144:147], v234 offset:4096
	global_load_lds_dwordx4 v236, s[8:9]
	v_mfma_f32_16x16x32_bf16 v[8:11], v[194:197], v[184:187], v[8:11]
	ds_read_b128 v[148:151], v234 offset:5120
	v_mfma_f32_16x16x32_bf16 v[0:3], v[202:205], v[184:187], v[0:3]
	ds_read_b128 v[152:155], v234 offset:6144
	s_add_u32 m0, s40, 0xe000
	v_mfma_f32_16x16x32_bf16 v[56:59], v[198:201], v[164:167], v[56:59]
	ds_read_b128 v[156:159], v234 offset:7168
	v_mfma_f32_16x16x32_bf16 v[48:51], v[206:209], v[164:167], v[48:51]
	global_load_lds_dwordx4 v237, s[8:9]
	v_mfma_f32_16x16x32_bf16 v[40:43], v[198:201], v[172:175], v[40:43]
	v_mfma_f32_16x16x32_bf16 v[32:35], v[206:209], v[172:175], v[32:35]
	s_add_u32 s8, s8, 0x80
	s_addc_u32 s9, s9, 0
	v_mfma_f32_16x16x32_bf16 v[24:27], v[198:201], v[180:183], v[24:27]
	v_mfma_f32_16x16x32_bf16 v[16:19], v[206:209], v[180:183], v[16:19]
	v_mfma_f32_16x16x32_bf16 v[8:11], v[198:201], v[188:191], v[8:11]
	v_mfma_f32_16x16x32_bf16 v[0:3], v[206:209], v[188:191], v[0:3]
	s_waitcnt vmcnt(12) lgkmcnt(0)
	s_barrier
	v_mfma_f32_16x16x32_bf16 v[60:63], v[218:221], v[160:163], v[60:63]
	v_mfma_f32_16x16x32_bf16 v[52:55], v[226:229], v[160:163], v[52:55]
	ds_read_b128 v[194:197], v235 offset:0
	v_mfma_f32_16x16x32_bf16 v[44:47], v[218:221], v[168:171], v[44:47]
	ds_read_b128 v[198:201], v235 offset:1024
	v_mfma_f32_16x16x32_bf16 v[36:39], v[226:229], v[168:171], v[36:39]
	ds_read_b128 v[202:205], v235 offset:2048
	s_add_u32 m0, s40, 0x0
	v_mfma_f32_16x16x32_bf16 v[28:31], v[218:221], v[176:179], v[28:31]
	ds_read_b128 v[206:209], v235 offset:3072
	v_mfma_f32_16x16x32_bf16 v[20:23], v[226:229], v[176:179], v[20:23]
	global_load_lds_dwordx4 v236, s[36:37]
	v_mfma_f32_16x16x32_bf16 v[12:15], v[218:221], v[184:187], v[12:15]
	v_mfma_f32_16x16x32_bf16 v[4:7], v[226:229], v[184:187], v[4:7]
	s_add_u32 m0, s40, 0x2000
	v_mfma_f32_16x16x32_bf16 v[60:63], v[222:225], v[164:167], v[60:63]
	v_mfma_f32_16x16x32_bf16 v[52:55], v[230:233], v[164:167], v[52:55]
	global_load_lds_dwordx4 v237, s[36:37]
	v_mfma_f32_16x16x32_bf16 v[44:47], v[222:225], v[172:175], v[44:47]
	v_mfma_f32_16x16x32_bf16 v[36:39], v[230:233], v[172:175], v[36:39]
	s_add_u32 s36, s36, 0x80
	s_addc_u32 s37, s37, 0
	v_mfma_f32_16x16x32_bf16 v[28:31], v[222:225], v[180:183], v[28:31]
	v_mfma_f32_16x16x32_bf16 v[20:23], v[230:233], v[180:183], v[20:23]
	v_mfma_f32_16x16x32_bf16 v[12:15], v[222:225], v[188:191], v[12:15]
	v_mfma_f32_16x16x32_bf16 v[4:7], v[230:233], v[188:191], v[4:7]
	s_add_i32 s41, s41, -1
	s_cmp_lg_u32 s41, 0
	s_cbranch_scc1 .Lmy_kloop
	s_waitcnt vmcnt(12) lgkmcnt(0)
	s_barrier
	v_mfma_f32_16x16x32_bf16 v[120:123], v[194:197], v[128:131], v[120:123]
	v_mfma_f32_16x16x32_bf16 v[112:115], v[202:205], v[128:131], v[112:115]
	ds_read_b128 v[218:221], v235 offset:16384
	v_mfma_f32_16x16x32_bf16 v[104:107], v[194:197], v[136:139], v[104:107]
	ds_read_b128 v[222:225], v235 offset:17408
	v_mfma_f32_16x16x32_bf16 v[96:99], v[202:205], v[136:139], v[96:99]
	ds_read_b128 v[226:229], v235 offset:18432
	s_add_u32 m0, s40, 0x10000
	v_mfma_f32_16x16x32_bf16 v[88:91], v[194:197], v[144:147], v[88:91]
	ds_read_b128 v[230:233], v235 offset:19456
	v_mfma_f32_16x16x32_bf16 v[80:83], v[202:205], v[144:147], v[80:83]
	global_load_lds_dwordx4 v236, s[26:27]
	v_mfma_f32_16x16x32_bf16 v[72:75], v[194:197], v[152:155], v[72:75]
	v_mfma_f32_16x16x32_bf16 v[64:67], v[202:205], v[152:155], v[64:67]
	s_add_u32 m0, s40, 0x12000
	v_mfma_f32_16x16x32_bf16 v[120:123], v[198:201], v[132:135], v[120:123]
	v_mfma_f32_16x16x32_bf16 v[112:115], v[206:209], v[132:135], v[112:115]
	global_load_lds_dwordx4 v237, s[26:27]
	v_mfma_f32_16x16x32_bf16 v[104:107], v[198:201], v[140:143], v[104:107]
	v_mfma_f32_16x16x32_bf16 v[96:99], v[206:209], v[140:143], v[96:99]
	s_add_u32 s26, s26, 0x80
	s_addc_u32 s27, s27, 0
	v_mfma_f32_16x16x32_bf16 v[88:91], v[198:201], v[148:151], v[88:91]
	v_mfma_f32_16x16x32_bf16 v[80:83], v[206:209], v[148:151], v[80:83]
	v_mfma_f32_16x16x32_bf16 v[72:75], v[198:201], v[156:159], v[72:75]
	v_mfma_f32_16x16x32_bf16 v[64:67], v[206:209], v[156:159], v[64:67]
	s_waitcnt vmcnt(12) lgkmcnt(0)
	s_barrier
	v_mfma_f32_16x16x32_bf16 v[124:127], v[218:221], v[128:131], v[124:127]
	v_mfma_f32_16x16x32_bf16 v[116:119], v[226:229], v[128:131], v[116:119]
	ds_read_b128 v[160:163], v234 offset:16384
	v_mfma_f32_16x16x32_bf16 v[108:111], v[218:221], v[136:139], v[108:111]
	ds_read_b128 v[164:167], v234 offset:17408
	v_mfma_f32_16x16x32_bf16 v[100:103], v[226:229], v[136:139], v[100:103]
	ds_read_b128 v[168:171], v234 offset:18432
	s_add_u32 m0, s40, 0x14000
	v_mfma_f32_16x16x32_bf16 v[92:95], v[218:221], v[144:147], v[92:95]
	ds_read_b128 v[172:175], v234 offset:19456
	v_mfma_f32_16x16x32_bf16 v[84:87], v[226:229], v[144:147], v[84:87]
	ds_read_b128 v[176:179], v234 offset:20480
	global_load_lds_dwordx4 v236, s[38:39]
	v_mfma_f32_16x16x32_bf16 v[76:79], v[218:221], v[152:155], v[76:79]
	ds_read_b128 v[180:183], v234 offset:21504
	v_mfma_f32_16x16x32_bf16 v[68:71], v[226:229], v[152:155], v[68:71]
	ds_read_b128 v[184:187], v234 offset:22528
	s_add_u32 m0, s40, 0x16000
	v_mfma_f32_16x16x32_bf16 v[124:127], v[222:225], v[132:135], v[124:127]
	ds_read_b128 v[188:191], v234 offset:23552
	v_mfma_f32_16x16x32_bf16 v[116:119], v[230:233], v[132:135], v[116:119]
	global_load_lds_dwordx4 v237, s[38:39]
	v_mfma_f32_16x16x32_bf16 v[108:111], v[222:225], v[140:143], v[108:111]
	v_mfma_f32_16x16x32_bf16 v[100:103], v[230:233], v[140:143], v[100:103]
	s_add_u32 s38, s38, 0x80
	s_addc_u32 s39, s39, 0
	v_mfma_f32_16x16x32_bf16 v[92:95], v[222:225], v[148:151], v[92:95]
	v_mfma_f32_16x16x32_bf16 v[84:87], v[230:233], v[148:151], v[84:87]
	v_mfma_f32_16x16x32_bf16 v[76:79], v[222:225], v[156:159], v[76:79]
	v_mfma_f32_16x16x32_bf16 v[68:71], v[230:233], v[156:159], v[68:71]
	s_waitcnt vmcnt(12) lgkmcnt(0)
	s_barrier
; #define STAGE(P, BASE, br, kt) do { const u16* _gb = (BASE) + ((size_t)(br) * K + (size_t)(kt) * BK); \
;     __builtin_amdgcn_global_load_lds((const unsigned*)(_gb + goff0), (unsigned*)((char*)(P) + tid * 16), 16, 0, 0); \
;     __builtin_amdgcn_global_load_lds((const unsigned*)(_gb + (size_t)64 * K + goff0), (unsigned*)((char*)(P) + tid * 16 + 8192), 16, 0, 0); } while (0)
; #define WAIT_V(n) asm volatile("s_waitcnt vmcnt(" #n ")" ::: "memory")
; #define WAIT_L(n) asm volatile("s_waitcnt lgkmcnt(" #n ")" ::: "memory")
; #define BAR __builtin_amdgcn_s_barrier()
; __device__ __forceinline__ void gemm_phase(KP p, char* shmc, const u16* __restrict__ A,
;                                            const u16* __restrict__ Bt, const int N, const int K, const int mode,
;                                            const float* __restrict__ xin, const float resw) {
;     ...
;     for (int t = 0; t < nt - 2; t += 2) {
;       LDB(B0, 0, 0); SCHED; LDA(At, 0, 0); STAGE(SA(1, 1), A, brow + HALF, t + 1);
;       WAIT_L(8); BAR; WAIT_L(0); MMA(0, 0, At, B0); BAR; SCHED;
;       LDB(B1, 0, 1); STAGE(SB(0, 0), Bt, bcol, t + 2);
;       BAR; WAIT_L(0); MMA(0, 1, At, B1); BAR;
;       LDA(At, 0, 1); STAGE(SA(0, 0), A, brow, t + 2);
;       BAR; WAIT_L(0); MMA(1, 0, At, B0); BAR; SCHED;
;       STAGE(SB(0, 1), Bt, bcol + HALF, t + 2);
;       WAIT_V(6); BAR; MMA(1, 1, At, B1); BAR;
;       LDB(B0, 1, 0); SCHED; LDA(At, 1, 0); STAGE(SA(0, 1), A, brow + HALF, t + 2);
;       WAIT_L(8); BAR; WAIT_L(0); MMA(0, 0, At, B0); BAR; SCHED;
;       LDB(B1, 1, 1); STAGE(SB(1, 0), Bt, bcol, t + 3);
;       BAR; WAIT_L(0); MMA(0, 1, At, B1); BAR;
;       LDA(At, 1, 1); STAGE(SA(1, 0), A, brow, t + 3);
;       BAR; WAIT_L(0); MMA(1, 0, At, B0); BAR; SCHED;
;       STAGE(SB(1, 1), Bt, bcol + HALF, t + 3);
;       WAIT_V(6); BAR; MMA(1, 1, At, B1); BAR;
;     }
;     { LDB(B0, 0, 0); LDA(At, 0, 0); STAGE(SA(1, 1), A, brow + HALF, nt - 1);
;       BAR; WAIT_L(0); MMA(0, 0, At, B0); BAR;
;       LDB(B1, 0, 1); BAR; WAIT_L(0); MMA(0, 1, At, B1); BAR;
;       LDA(At, 0, 1); WAIT_V(4); BAR; WAIT_L(0); MMA(1, 0, At, B0); MMA(1, 1, At, B1); BAR; }
;     { LDB(B0, 1, 0); LDA(At, 1, 0); WAIT_V(2); BAR; WAIT_L(0); MMA(0, 0, At, B0); BAR;
;       LDB(B1, 1, 1); WAIT_V(0); BAR; WAIT_L(0); MMA(0, 1, At, B1); BAR;
;       LDA(At, 1, 1); BAR; WAIT_L(0); MMA(1, 0, At, B0); MMA(1, 1, At, B1); BAR; }
	v_mfma_f32_16x16x32_bf16 v[56:59], v[194:197], v[160:163], v[56:59]
	v_mfma_f32_16x16x32_bf16 v[48:51], v[202:205], v[160:163], v[48:51]
	ds_read_b128 v[128:131], v234 offset:32768
	v_mfma_f32_16x16x32_bf16 v[40:43], v[194:197], v[168:171], v[40:43]
	ds_read_b128 v[132:135], v234 offset:33792
	v_mfma_f32_16x16x32_bf16 v[32:35], v[202:205], v[168:171], v[32:35]
	ds_read_b128 v[136:139], v234 offset:34816
	s_add_u32 m0, s40, 0x4000
	v_mfma_f32_16x16x32_bf16 v[24:27], v[194:197], v[176:179], v[24:27]
	ds_read_b128 v[140:143], v234 offset:35840
	v_mfma_f32_16x16x32_bf16 v[16:19], v[202:205], v[176:179], v[16:19]
	ds_read_b128 v[144:147], v234 offset:36864
	global_load_lds_dwordx4 v236, s[8:9]
	v_mfma_f32_16x16x32_bf16 v[8:11], v[194:197], v[184:187], v[8:11]
	ds_read_b128 v[148:151], v234 offset:37888
	v_mfma_f32_16x16x32_bf16 v[0:3], v[202:205], v[184:187], v[0:3]
	ds_read_b128 v[152:155], v234 offset:38912
	s_add_u32 m0, s40, 0x6000
	v_mfma_f32_16x16x32_bf16 v[56:59], v[198:201], v[164:167], v[56:59]
	ds_read_b128 v[156:159], v234 offset:39936
	v_mfma_f32_16x16x32_bf16 v[48:51], v[206:209], v[164:167], v[48:51]
	global_load_lds_dwordx4 v237, s[8:9]
	v_mfma_f32_16x16x32_bf16 v[40:43], v[198:201], v[172:175], v[40:43]
	v_mfma_f32_16x16x32_bf16 v[32:35], v[206:209], v[172:175], v[32:35]
	s_add_u32 s8, s8, 0x80
	s_addc_u32 s9, s9, 0
	v_mfma_f32_16x16x32_bf16 v[24:27], v[198:201], v[180:183], v[24:27]
	v_mfma_f32_16x16x32_bf16 v[16:19], v[206:209], v[180:183], v[16:19]
	v_mfma_f32_16x16x32_bf16 v[8:11], v[198:201], v[188:191], v[8:11]
	v_mfma_f32_16x16x32_bf16 v[0:3], v[206:209], v[188:191], v[0:3]
	s_waitcnt vmcnt(12) lgkmcnt(0)
	s_barrier
	v_mfma_f32_16x16x32_bf16 v[60:63], v[218:221], v[160:163], v[60:63]
	v_mfma_f32_16x16x32_bf16 v[52:55], v[226:229], v[160:163], v[52:55]
	ds_read_b128 v[194:197], v235 offset:32768
	v_mfma_f32_16x16x32_bf16 v[44:47], v[218:221], v[168:171], v[44:47]
	ds_read_b128 v[198:201], v235 offset:33792
	v_mfma_f32_16x16x32_bf16 v[36:39], v[226:229], v[168:171], v[36:39]
	ds_read_b128 v[202:205], v235 offset:34816
	s_add_u32 m0, s40, 0x8000
	v_mfma_f32_16x16x32_bf16 v[28:31], v[218:221], v[176:179], v[28:31]
	ds_read_b128 v[206:209], v235 offset:35840
	v_mfma_f32_16x16x32_bf16 v[20:23], v[226:229], v[176:179], v[20:23]
	global_load_lds_dwordx4 v236, s[36:37]
	v_mfma_f32_16x16x32_bf16 v[12:15], v[218:221], v[184:187], v[12:15]
	v_mfma_f32_16x16x32_bf16 v[4:7], v[226:229], v[184:187], v[4:7]
	s_add_u32 m0, s40, 0xa000
	v_mfma_f32_16x16x32_bf16 v[60:63], v[222:225], v[164:167], v[60:63]
	v_mfma_f32_16x16x32_bf16 v[52:55], v[230:233], v[164:167], v[52:55]
	global_load_lds_dwordx4 v237, s[36:37]
	v_mfma_f32_16x16x32_bf16 v[44:47], v[222:225], v[172:175], v[44:47]
	v_mfma_f32_16x16x32_bf16 v[36:39], v[230:233], v[172:175], v[36:39]
	s_add_u32 s36, s36, 0x80
	s_addc_u32 s37, s37, 0
	v_mfma_f32_16x16x32_bf16 v[28:31], v[222:225], v[180:183], v[28:31]
	v_mfma_f32_16x16x32_bf16 v[20:23], v[230:233], v[180:183], v[20:23]
	v_mfma_f32_16x16x32_bf16 v[12:15], v[222:225], v[188:191], v[12:15]
	v_mfma_f32_16x16x32_bf16 v[4:7], v[230:233], v[188:191], v[4:7]
	s_waitcnt vmcnt(12) lgkmcnt(0)
	s_barrier
	v_mfma_f32_16x16x32_bf16 v[120:123], v[194:197], v[128:131], v[120:123]
	v_mfma_f32_16x16x32_bf16 v[112:115], v[202:205], v[128:131], v[112:115]
	ds_read_b128 v[218:221], v235 offset:49152
	v_mfma_f32_16x16x32_bf16 v[104:107], v[194:197], v[136:139], v[104:107]
	ds_read_b128 v[222:225], v235 offset:50176
	v_mfma_f32_16x16x32_bf16 v[96:99], v[202:205], v[136:139], v[96:99]
	ds_read_b128 v[226:229], v235 offset:51200
	s_add_u32 m0, s40, 0x18000
	v_mfma_f32_16x16x32_bf16 v[88:91], v[194:197], v[144:147], v[88:91]
	ds_read_b128 v[230:233], v235 offset:52224
	v_mfma_f32_16x16x32_bf16 v[80:83], v[202:205], v[144:147], v[80:83]
	global_load_lds_dwordx4 v236, s[26:27]
	v_mfma_f32_16x16x32_bf16 v[72:75], v[194:197], v[152:155], v[72:75]
	v_mfma_f32_16x16x32_bf16 v[64:67], v[202:205], v[152:155], v[64:67]
	s_add_u32 m0, s40, 0x1a000
	v_mfma_f32_16x16x32_bf16 v[120:123], v[198:201], v[132:135], v[120:123]
	v_mfma_f32_16x16x32_bf16 v[112:115], v[206:209], v[132:135], v[112:115]
	global_load_lds_dwordx4 v237, s[26:27]
	v_mfma_f32_16x16x32_bf16 v[104:107], v[198:201], v[140:143], v[104:107]
	v_mfma_f32_16x16x32_bf16 v[96:99], v[206:209], v[140:143], v[96:99]
	s_add_u32 s26, s26, 0x80
	s_addc_u32 s27, s27, 0
	v_mfma_f32_16x16x32_bf16 v[88:91], v[198:201], v[148:151], v[88:91]
	v_mfma_f32_16x16x32_bf16 v[80:83], v[206:209], v[148:151], v[80:83]
	v_mfma_f32_16x16x32_bf16 v[72:75], v[198:201], v[156:159], v[72:75]
	v_mfma_f32_16x16x32_bf16 v[64:67], v[206:209], v[156:159], v[64:67]
	s_waitcnt vmcnt(12) lgkmcnt(0)
	s_barrier
	v_mfma_f32_16x16x32_bf16 v[124:127], v[218:221], v[128:131], v[124:127]
	v_mfma_f32_16x16x32_bf16 v[116:119], v[226:229], v[128:131], v[116:119]
	ds_read_b128 v[160:163], v234 offset:49152
	v_mfma_f32_16x16x32_bf16 v[108:111], v[218:221], v[136:139], v[108:111]
	ds_read_b128 v[164:167], v234 offset:50176
	v_mfma_f32_16x16x32_bf16 v[100:103], v[226:229], v[136:139], v[100:103]
	ds_read_b128 v[168:171], v234 offset:51200
	s_add_u32 m0, s40, 0x1c000
	v_mfma_f32_16x16x32_bf16 v[92:95], v[218:221], v[144:147], v[92:95]
	ds_read_b128 v[172:175], v234 offset:52224
	v_mfma_f32_16x16x32_bf16 v[84:87], v[226:229], v[144:147], v[84:87]
	ds_read_b128 v[176:179], v234 offset:53248
	global_load_lds_dwordx4 v236, s[38:39]
	v_mfma_f32_16x16x32_bf16 v[76:79], v[218:221], v[152:155], v[76:79]
	ds_read_b128 v[180:183], v234 offset:54272
	v_mfma_f32_16x16x32_bf16 v[68:71], v[226:229], v[152:155], v[68:71]
	ds_read_b128 v[184:187], v234 offset:55296
	s_add_u32 m0, s40, 0x1e000
	v_mfma_f32_16x16x32_bf16 v[124:127], v[222:225], v[132:135], v[124:127]
	ds_read_b128 v[188:191], v234 offset:56320
	v_mfma_f32_16x16x32_bf16 v[116:119], v[230:233], v[132:135], v[116:119]
	global_load_lds_dwordx4 v237, s[38:39]
	v_mfma_f32_16x16x32_bf16 v[108:111], v[222:225], v[140:143], v[108:111]
	v_mfma_f32_16x16x32_bf16 v[100:103], v[230:233], v[140:143], v[100:103]
	s_add_u32 s38, s38, 0x80
	s_addc_u32 s39, s39, 0
	v_mfma_f32_16x16x32_bf16 v[92:95], v[222:225], v[148:151], v[92:95]
	v_mfma_f32_16x16x32_bf16 v[84:87], v[230:233], v[148:151], v[84:87]
	v_mfma_f32_16x16x32_bf16 v[76:79], v[222:225], v[156:159], v[76:79]
	v_mfma_f32_16x16x32_bf16 v[68:71], v[230:233], v[156:159], v[68:71]
	s_waitcnt vmcnt(12) lgkmcnt(0)
	s_barrier
; #define STAGE(P, BASE, br, kt) do { const u16* _gb = (BASE) + ((size_t)(br) * K + (size_t)(kt) * BK); \
;     __builtin_amdgcn_global_load_lds((const unsigned*)(_gb + goff0), (unsigned*)((char*)(P) + tid * 16), 16, 0, 0); \
;     __builtin_amdgcn_global_load_lds((const unsigned*)(_gb + (size_t)64 * K + goff0), (unsigned*)((char*)(P) + tid * 16 + 8192), 16, 0, 0); } while (0)
; #define LDA(dst, b, h) _Pragma("unroll") for (int m = 0; m < 4; ++m) _Pragma("unroll") for (int k = 0; k < 2; ++k) \
;     dst[m][k] = *reinterpret_cast<const bf16x8*>((char*)SA(b, h) + lds_byte(wr * 64 + m * 16 + fr, k * 32 + fq * 8))
; #define LDB(dst, b, h) _Pragma("unroll") for (int n = 0; n < 2; ++n) _Pragma("unroll") for (int k = 0; k < 2; ++k) \
;     dst[n][k] = *reinterpret_cast<const bf16x8*>((char*)SB(b, h) + lds_byte(wc * 32 + n * 16 + fr, k * 32 + fq * 8))
; #define MMA(ai, bj, At, Bt_) do { __builtin_amdgcn_s_setprio(1); \
;     _Pragma("unroll") for (int m = 0; m < 4; ++m) _Pragma("unroll") for (int n = 0; n < 2; ++n) _Pragma("unroll") for (int k = 0; k < 2; ++k) \
;       acc[ai][bj][m][n] = __builtin_amdgcn_mfma_f32_16x16x32_bf16(Bt_[n][k], At[m][k], acc[ai][bj][m][n], 0, 0, 0); \
;     __builtin_amdgcn_s_setprio(0); } while (0)
; #define WAIT_V(n) asm volatile("s_waitcnt vmcnt(" #n ")" ::: "memory")
; #define WAIT_L(n) asm volatile("s_waitcnt lgkmcnt(" #n ")" ::: "memory")
; #define BAR __builtin_amdgcn_s_barrier()
; __device__ __forceinline__ void gemm_phase(KP p, char* shmc, const u16* __restrict__ A,
;                                            const u16* __restrict__ Bt, const int N, const int K, const int mode,
;                                            const float* __restrict__ xin, const float resw) {
;     ...
;     { LDB(B0, 0, 0); LDA(At, 0, 0); STAGE(SA(1, 1), A, brow + HALF, nt - 1);
;       BAR; WAIT_L(0); MMA(0, 0, At, B0); BAR;
;       LDB(B1, 0, 1); BAR; WAIT_L(0); MMA(0, 1, At, B1); BAR;
;       LDA(At, 0, 1); WAIT_V(4); BAR; WAIT_L(0); MMA(1, 0, At, B0); MMA(1, 1, At, B1); BAR; }
;     { LDB(B0, 1, 0); LDA(At, 1, 0); WAIT_V(2); BAR; WAIT_L(0); MMA(0, 0, At, B0); BAR;
;       LDB(B1, 1, 1); WAIT_V(0); BAR; WAIT_L(0); MMA(0, 1, At, B1); BAR;
;       LDA(At, 1, 1); BAR; WAIT_L(0); MMA(1, 0, At, B0); MMA(1, 1, At, B1); BAR; }
	v_mfma_f32_16x16x32_bf16 v[56:59], v[194:197], v[160:163], v[56:59]
	v_mfma_f32_16x16x32_bf16 v[48:51], v[202:205], v[160:163], v[48:51]
	ds_read_b128 v[128:131], v234 offset:0
	v_mfma_f32_16x16x32_bf16 v[40:43], v[194:197], v[168:171], v[40:43]
	ds_read_b128 v[132:135], v234 offset:1024
	v_mfma_f32_16x16x32_bf16 v[32:35], v[202:205], v[168:171], v[32:35]
	ds_read_b128 v[136:139], v234 offset:2048
	s_add_u32 m0, s40, 0xc000
	v_mfma_f32_16x16x32_bf16 v[24:27], v[194:197], v[176:179], v[24:27]
	ds_read_b128 v[140:143], v234 offset:3072
	v_mfma_f32_16x16x32_bf16 v[16:19], v[202:205], v[176:179], v[16:19]
	ds_read_b128 v[144:147], v234 offset:4096
	global_load_lds_dwordx4 v236, s[8:9]
	v_mfma_f32_16x16x32_bf16 v[8:11], v[194:197], v[184:187], v[8:11]
	ds_read_b128 v[148:151], v234 offset:5120
	v_mfma_f32_16x16x32_bf16 v[0:3], v[202:205], v[184:187], v[0:3]
	ds_read_b128 v[152:155], v234 offset:6144
	s_add_u32 m0, s40, 0xe000
	v_mfma_f32_16x16x32_bf16 v[56:59], v[198:201], v[164:167], v[56:59]
	ds_read_b128 v[156:159], v234 offset:7168
	v_mfma_f32_16x16x32_bf16 v[48:51], v[206:209], v[164:167], v[48:51]
	global_load_lds_dwordx4 v237, s[8:9]
	v_mfma_f32_16x16x32_bf16 v[40:43], v[198:201], v[172:175], v[40:43]
	v_mfma_f32_16x16x32_bf16 v[32:35], v[206:209], v[172:175], v[32:35]
	s_add_u32 s8, s8, 0x80
	s_addc_u32 s9, s9, 0
	v_mfma_f32_16x16x32_bf16 v[24:27], v[198:201], v[180:183], v[24:27]
	v_mfma_f32_16x16x32_bf16 v[16:19], v[206:209], v[180:183], v[16:19]
	v_mfma_f32_16x16x32_bf16 v[8:11], v[198:201], v[188:191], v[8:11]
	v_mfma_f32_16x16x32_bf16 v[0:3], v[206:209], v[188:191], v[0:3]
	s_waitcnt vmcnt(12) lgkmcnt(0)
	s_barrier
	v_mfma_f32_16x16x32_bf16 v[60:63], v[218:221], v[160:163], v[60:63]
	v_mfma_f32_16x16x32_bf16 v[52:55], v[226:229], v[160:163], v[52:55]
	ds_read_b128 v[194:197], v235 offset:0
	v_mfma_f32_16x16x32_bf16 v[44:47], v[218:221], v[168:171], v[44:47]
	ds_read_b128 v[198:201], v235 offset:1024
	v_mfma_f32_16x16x32_bf16 v[36:39], v[226:229], v[168:171], v[36:39]
	ds_read_b128 v[202:205], v235 offset:2048
	v_mfma_f32_16x16x32_bf16 v[28:31], v[218:221], v[176:179], v[28:31]
	ds_read_b128 v[206:209], v235 offset:3072
	v_mfma_f32_16x16x32_bf16 v[20:23], v[226:229], v[176:179], v[20:23]
	v_mfma_f32_16x16x32_bf16 v[12:15], v[218:221], v[184:187], v[12:15]
	v_mfma_f32_16x16x32_bf16 v[4:7], v[226:229], v[184:187], v[4:7]
	v_mfma_f32_16x16x32_bf16 v[60:63], v[222:225], v[164:167], v[60:63]
	v_mfma_f32_16x16x32_bf16 v[52:55], v[230:233], v[164:167], v[52:55]
	v_mfma_f32_16x16x32_bf16 v[44:47], v[222:225], v[172:175], v[44:47]
	v_mfma_f32_16x16x32_bf16 v[36:39], v[230:233], v[172:175], v[36:39]
	v_mfma_f32_16x16x32_bf16 v[28:31], v[222:225], v[180:183], v[28:31]
	v_mfma_f32_16x16x32_bf16 v[20:23], v[230:233], v[180:183], v[20:23]
	v_mfma_f32_16x16x32_bf16 v[12:15], v[222:225], v[188:191], v[12:15]
	v_mfma_f32_16x16x32_bf16 v[4:7], v[230:233], v[188:191], v[4:7]
	s_waitcnt vmcnt(10) lgkmcnt(0)
	s_barrier
	v_mfma_f32_16x16x32_bf16 v[120:123], v[194:197], v[128:131], v[120:123]
	v_mfma_f32_16x16x32_bf16 v[112:115], v[202:205], v[128:131], v[112:115]
	ds_read_b128 v[218:221], v235 offset:16384
	v_mfma_f32_16x16x32_bf16 v[104:107], v[194:197], v[136:139], v[104:107]
	ds_read_b128 v[222:225], v235 offset:17408
	v_mfma_f32_16x16x32_bf16 v[96:99], v[202:205], v[136:139], v[96:99]
	ds_read_b128 v[226:229], v235 offset:18432
	v_mfma_f32_16x16x32_bf16 v[88:91], v[194:197], v[144:147], v[88:91]
	ds_read_b128 v[230:233], v235 offset:19456
	v_mfma_f32_16x16x32_bf16 v[80:83], v[202:205], v[144:147], v[80:83]
	v_mfma_f32_16x16x32_bf16 v[72:75], v[194:197], v[152:155], v[72:75]
	v_mfma_f32_16x16x32_bf16 v[64:67], v[202:205], v[152:155], v[64:67]
	v_mfma_f32_16x16x32_bf16 v[120:123], v[198:201], v[132:135], v[120:123]
	v_mfma_f32_16x16x32_bf16 v[112:115], v[206:209], v[132:135], v[112:115]
	v_mfma_f32_16x16x32_bf16 v[104:107], v[198:201], v[140:143], v[104:107]
	v_mfma_f32_16x16x32_bf16 v[96:99], v[206:209], v[140:143], v[96:99]
	v_mfma_f32_16x16x32_bf16 v[88:91], v[198:201], v[148:151], v[88:91]
	v_mfma_f32_16x16x32_bf16 v[80:83], v[206:209], v[148:151], v[80:83]
	v_mfma_f32_16x16x32_bf16 v[72:75], v[198:201], v[156:159], v[72:75]
	v_mfma_f32_16x16x32_bf16 v[64:67], v[206:209], v[156:159], v[64:67]
	s_waitcnt vmcnt(8) lgkmcnt(0)
	s_barrier
	v_mfma_f32_16x16x32_bf16 v[124:127], v[218:221], v[128:131], v[124:127]
	v_mfma_f32_16x16x32_bf16 v[116:119], v[226:229], v[128:131], v[116:119]
	ds_read_b128 v[160:163], v234 offset:16384
	v_mfma_f32_16x16x32_bf16 v[108:111], v[218:221], v[136:139], v[108:111]
	ds_read_b128 v[164:167], v234 offset:17408
	v_mfma_f32_16x16x32_bf16 v[100:103], v[226:229], v[136:139], v[100:103]
	ds_read_b128 v[168:171], v234 offset:18432
	v_mfma_f32_16x16x32_bf16 v[92:95], v[218:221], v[144:147], v[92:95]
	ds_read_b128 v[172:175], v234 offset:19456
	v_mfma_f32_16x16x32_bf16 v[84:87], v[226:229], v[144:147], v[84:87]
	ds_read_b128 v[176:179], v234 offset:20480
	v_mfma_f32_16x16x32_bf16 v[76:79], v[218:221], v[152:155], v[76:79]
	ds_read_b128 v[180:183], v234 offset:21504
	v_mfma_f32_16x16x32_bf16 v[68:71], v[226:229], v[152:155], v[68:71]
	ds_read_b128 v[184:187], v234 offset:22528
	v_mfma_f32_16x16x32_bf16 v[124:127], v[222:225], v[132:135], v[124:127]
	ds_read_b128 v[188:191], v234 offset:23552
	v_mfma_f32_16x16x32_bf16 v[116:119], v[230:233], v[132:135], v[116:119]
	v_mfma_f32_16x16x32_bf16 v[108:111], v[222:225], v[140:143], v[108:111]
	v_mfma_f32_16x16x32_bf16 v[100:103], v[230:233], v[140:143], v[100:103]
	v_mfma_f32_16x16x32_bf16 v[92:95], v[222:225], v[148:151], v[92:95]
	v_mfma_f32_16x16x32_bf16 v[84:87], v[230:233], v[148:151], v[84:87]
	v_mfma_f32_16x16x32_bf16 v[76:79], v[222:225], v[156:159], v[76:79]
	v_mfma_f32_16x16x32_bf16 v[68:71], v[230:233], v[156:159], v[68:71]
	s_waitcnt vmcnt(6) lgkmcnt(0)
	s_barrier
; #define STAGE(P, BASE, br, kt) do { const u16* _gb = (BASE) + ((size_t)(br) * K + (size_t)(kt) * BK); \
;     __builtin_amdgcn_global_load_lds((const unsigned*)(_gb + goff0), (unsigned*)((char*)(P) + tid * 16), 16, 0, 0); \
;     __builtin_amdgcn_global_load_lds((const unsigned*)(_gb + (size_t)64 * K + goff0), (unsigned*)((char*)(P) + tid * 16 + 8192), 16, 0, 0); } while (0)
; #define LDA(dst, b, h) _Pragma("unroll") for (int m = 0; m < 4; ++m) _Pragma("unroll") for (int k = 0; k < 2; ++k) \
;     dst[m][k] = *reinterpret_cast<const bf16x8*>((char*)SA(b, h) + lds_byte(wr * 64 + m * 16 + fr, k * 32 + fq * 8))
; #define LDB(dst, b, h) _Pragma("unroll") for (int n = 0; n < 2; ++n) _Pragma("unroll") for (int k = 0; k < 2; ++k) \
;     dst[n][k] = *reinterpret_cast<const bf16x8*>((char*)SB(b, h) + lds_byte(wc * 32 + n * 16 + fr, k * 32 + fq * 8))
; #define MMA(ai, bj, At, Bt_) do { __builtin_amdgcn_s_setprio(1); \
;     _Pragma("unroll") for (int m = 0; m < 4; ++m) _Pragma("unroll") for (int n = 0; n < 2; ++n) _Pragma("unroll") for (int k = 0; k < 2; ++k) \
;       acc[ai][bj][m][n] = __builtin_amdgcn_mfma_f32_16x16x32_bf16(Bt_[n][k], At[m][k], acc[ai][bj][m][n], 0, 0, 0); \
;     __builtin_amdgcn_s_setprio(0); } while (0)
; #define WAIT_V(n) asm volatile("s_waitcnt vmcnt(" #n ")" ::: "memory")
; #define WAIT_L(n) asm volatile("s_waitcnt lgkmcnt(" #n ")" ::: "memory")
; #define BAR __builtin_amdgcn_s_barrier()
; __device__ __forceinline__ void gemm_phase(KP p, char* shmc, const u16* __restrict__ A,
;                                            const u16* __restrict__ Bt, const int N, const int K, const int mode,
;                                            const float* __restrict__ xin, const float resw) {
;     ...
;     { LDB(B0, 0, 0); LDA(At, 0, 0); STAGE(SA(1, 1), A, brow + HALF, nt - 1);
;       BAR; WAIT_L(0); MMA(0, 0, At, B0); BAR;
;       LDB(B1, 0, 1); BAR; WAIT_L(0); MMA(0, 1, At, B1); BAR;
;       LDA(At, 0, 1); WAIT_V(4); BAR; WAIT_L(0); MMA(1, 0, At, B0); MMA(1, 1, At, B1); BAR; }
;     { LDB(B0, 1, 0); LDA(At, 1, 0); WAIT_V(2); BAR; WAIT_L(0); MMA(0, 0, At, B0); BAR;
;       LDB(B1, 1, 1); WAIT_V(0); BAR; WAIT_L(0); MMA(0, 1, At, B1); BAR;
;       LDA(At, 1, 1); BAR; WAIT_L(0); MMA(1, 0, At, B0); MMA(1, 1, At, B1); BAR; }
	v_mfma_f32_16x16x32_bf16 v[56:59], v[194:197], v[160:163], v[56:59]
	v_mfma_f32_16x16x32_bf16 v[48:51], v[202:205], v[160:163], v[48:51]
	ds_read_b128 v[128:131], v234 offset:32768
	v_mfma_f32_16x16x32_bf16 v[40:43], v[194:197], v[168:171], v[40:43]
	ds_read_b128 v[132:135], v234 offset:33792
	v_mfma_f32_16x16x32_bf16 v[32:35], v[202:205], v[168:171], v[32:35]
	ds_read_b128 v[136:139], v234 offset:34816
	v_mfma_f32_16x16x32_bf16 v[24:27], v[194:197], v[176:179], v[24:27]
	ds_read_b128 v[140:143], v234 offset:35840
	v_mfma_f32_16x16x32_bf16 v[16:19], v[202:205], v[176:179], v[16:19]
	ds_read_b128 v[144:147], v234 offset:36864
	v_mfma_f32_16x16x32_bf16 v[8:11], v[194:197], v[184:187], v[8:11]
	ds_read_b128 v[148:151], v234 offset:37888
	v_mfma_f32_16x16x32_bf16 v[0:3], v[202:205], v[184:187], v[0:3]
	ds_read_b128 v[152:155], v234 offset:38912
	v_mfma_f32_16x16x32_bf16 v[56:59], v[198:201], v[164:167], v[56:59]
	ds_read_b128 v[156:159], v234 offset:39936
	v_mfma_f32_16x16x32_bf16 v[48:51], v[206:209], v[164:167], v[48:51]
	v_mfma_f32_16x16x32_bf16 v[40:43], v[198:201], v[172:175], v[40:43]
	v_mfma_f32_16x16x32_bf16 v[32:35], v[206:209], v[172:175], v[32:35]
	v_mfma_f32_16x16x32_bf16 v[24:27], v[198:201], v[180:183], v[24:27]
	v_mfma_f32_16x16x32_bf16 v[16:19], v[206:209], v[180:183], v[16:19]
	v_mfma_f32_16x16x32_bf16 v[8:11], v[198:201], v[188:191], v[8:11]
	v_mfma_f32_16x16x32_bf16 v[0:3], v[206:209], v[188:191], v[0:3]
	s_waitcnt vmcnt(4) lgkmcnt(0)
	s_barrier
	v_mfma_f32_16x16x32_bf16 v[60:63], v[218:221], v[160:163], v[60:63]
	v_mfma_f32_16x16x32_bf16 v[52:55], v[226:229], v[160:163], v[52:55]
	ds_read_b128 v[194:197], v235 offset:32768
	v_mfma_f32_16x16x32_bf16 v[44:47], v[218:221], v[168:171], v[44:47]
	ds_read_b128 v[198:201], v235 offset:33792
	v_mfma_f32_16x16x32_bf16 v[36:39], v[226:229], v[168:171], v[36:39]
	ds_read_b128 v[202:205], v235 offset:34816
	v_mfma_f32_16x16x32_bf16 v[28:31], v[218:221], v[176:179], v[28:31]
	ds_read_b128 v[206:209], v235 offset:35840
	v_mfma_f32_16x16x32_bf16 v[20:23], v[226:229], v[176:179], v[20:23]
	v_mfma_f32_16x16x32_bf16 v[12:15], v[218:221], v[184:187], v[12:15]
	v_mfma_f32_16x16x32_bf16 v[4:7], v[226:229], v[184:187], v[4:7]
	v_mfma_f32_16x16x32_bf16 v[60:63], v[222:225], v[164:167], v[60:63]
	v_mfma_f32_16x16x32_bf16 v[52:55], v[230:233], v[164:167], v[52:55]
	v_mfma_f32_16x16x32_bf16 v[44:47], v[222:225], v[172:175], v[44:47]
	v_mfma_f32_16x16x32_bf16 v[36:39], v[230:233], v[172:175], v[36:39]
	v_mfma_f32_16x16x32_bf16 v[28:31], v[222:225], v[180:183], v[28:31]
	v_mfma_f32_16x16x32_bf16 v[20:23], v[230:233], v[180:183], v[20:23]
	v_mfma_f32_16x16x32_bf16 v[12:15], v[222:225], v[188:191], v[12:15]
	v_mfma_f32_16x16x32_bf16 v[4:7], v[230:233], v[188:191], v[4:7]
	s_waitcnt vmcnt(2) lgkmcnt(0)
	s_barrier
	v_mfma_f32_16x16x32_bf16 v[120:123], v[194:197], v[128:131], v[120:123]
	v_mfma_f32_16x16x32_bf16 v[112:115], v[202:205], v[128:131], v[112:115]
	ds_read_b128 v[218:221], v235 offset:49152
	v_mfma_f32_16x16x32_bf16 v[104:107], v[194:197], v[136:139], v[104:107]
	ds_read_b128 v[222:225], v235 offset:50176
	v_mfma_f32_16x16x32_bf16 v[96:99], v[202:205], v[136:139], v[96:99]
	ds_read_b128 v[226:229], v235 offset:51200
	v_mfma_f32_16x16x32_bf16 v[88:91], v[194:197], v[144:147], v[88:91]
	ds_read_b128 v[230:233], v235 offset:52224
	v_mfma_f32_16x16x32_bf16 v[80:83], v[202:205], v[144:147], v[80:83]
	v_mfma_f32_16x16x32_bf16 v[72:75], v[194:197], v[152:155], v[72:75]
	v_mfma_f32_16x16x32_bf16 v[64:67], v[202:205], v[152:155], v[64:67]
	v_mfma_f32_16x16x32_bf16 v[120:123], v[198:201], v[132:135], v[120:123]
	v_mfma_f32_16x16x32_bf16 v[112:115], v[206:209], v[132:135], v[112:115]
	v_mfma_f32_16x16x32_bf16 v[104:107], v[198:201], v[140:143], v[104:107]
	v_mfma_f32_16x16x32_bf16 v[96:99], v[206:209], v[140:143], v[96:99]
	v_mfma_f32_16x16x32_bf16 v[88:91], v[198:201], v[148:151], v[88:91]
	v_mfma_f32_16x16x32_bf16 v[80:83], v[206:209], v[148:151], v[80:83]
	v_mfma_f32_16x16x32_bf16 v[72:75], v[198:201], v[156:159], v[72:75]
	v_mfma_f32_16x16x32_bf16 v[64:67], v[206:209], v[156:159], v[64:67]
	s_waitcnt vmcnt(0) lgkmcnt(0)
	s_barrier
	v_mfma_f32_16x16x32_bf16 v[124:127], v[218:221], v[128:131], v[124:127]
	v_mfma_f32_16x16x32_bf16 v[116:119], v[226:229], v[128:131], v[116:119]
	ds_read_b128 v[160:163], v234 offset:49152
	v_mfma_f32_16x16x32_bf16 v[108:111], v[218:221], v[136:139], v[108:111]
	ds_read_b128 v[164:167], v234 offset:50176
	v_mfma_f32_16x16x32_bf16 v[100:103], v[226:229], v[136:139], v[100:103]
	ds_read_b128 v[168:171], v234 offset:51200
	v_mfma_f32_16x16x32_bf16 v[92:95], v[218:221], v[144:147], v[92:95]
	ds_read_b128 v[172:175], v234 offset:52224
	v_mfma_f32_16x16x32_bf16 v[84:87], v[226:229], v[144:147], v[84:87]
	ds_read_b128 v[176:179], v234 offset:53248
	v_mfma_f32_16x16x32_bf16 v[76:79], v[218:221], v[152:155], v[76:79]
	ds_read_b128 v[180:183], v234 offset:54272
	v_mfma_f32_16x16x32_bf16 v[68:71], v[226:229], v[152:155], v[68:71]
	ds_read_b128 v[184:187], v234 offset:55296
	v_mfma_f32_16x16x32_bf16 v[124:127], v[222:225], v[132:135], v[124:127]
	ds_read_b128 v[188:191], v234 offset:56320
	v_mfma_f32_16x16x32_bf16 v[116:119], v[230:233], v[132:135], v[116:119]
	v_mfma_f32_16x16x32_bf16 v[108:111], v[222:225], v[140:143], v[108:111]
	v_mfma_f32_16x16x32_bf16 v[100:103], v[230:233], v[140:143], v[100:103]
	v_mfma_f32_16x16x32_bf16 v[92:95], v[222:225], v[148:151], v[92:95]
	v_mfma_f32_16x16x32_bf16 v[84:87], v[230:233], v[148:151], v[84:87]
	v_mfma_f32_16x16x32_bf16 v[76:79], v[222:225], v[156:159], v[76:79]
	v_mfma_f32_16x16x32_bf16 v[68:71], v[230:233], v[156:159], v[68:71]
	s_waitcnt lgkmcnt(0)
	s_barrier
; #define STAGE(P, BASE, br, kt) do { const u16* _gb = (BASE) + ((size_t)(br) * K + (size_t)(kt) * BK); \
;     __builtin_amdgcn_global_load_lds((const unsigned*)(_gb + goff0), (unsigned*)((char*)(P) + tid * 16), 16, 0, 0); \
;     __builtin_amdgcn_global_load_lds((const unsigned*)(_gb + (size_t)64 * K + goff0), (unsigned*)((char*)(P) + tid * 16 + 8192), 16, 0, 0); } while (0)
; #define WAIT_V(n) asm volatile("s_waitcnt vmcnt(" #n ")" ::: "memory")
; #define WAIT_L(n) asm volatile("s_waitcnt lgkmcnt(" #n ")" ::: "memory")
; #define BAR __builtin_amdgcn_s_barrier()
; __device__ __forceinline__ void gemm_phase(KP p, char* shmc, const u16* __restrict__ A,
;                                            const u16* __restrict__ Bt, const int N, const int K, const int mode,
;                                            const float* __restrict__ xin, const float resw) {
;     ...
;     for (int t = 0; t < nt - 2; t += 2) {
;       LDB(B0, 0, 0); SCHED; LDA(At, 0, 0); STAGE(SA(1, 1), A, brow + HALF, t + 1);
;       WAIT_L(8); BAR; WAIT_L(0); MMA(0, 0, At, B0); BAR; SCHED;
;       LDB(B1, 0, 1); STAGE(SB(0, 0), Bt, bcol, t + 2);
;       BAR; WAIT_L(0); MMA(0, 1, At, B1); BAR;
;       LDA(At, 0, 1); STAGE(SA(0, 0), A, brow, t + 2);
;       BAR; WAIT_L(0); MMA(1, 0, At, B0); BAR; SCHED;
;       STAGE(SB(0, 1), Bt, bcol + HALF, t + 2);
;       WAIT_V(6); BAR; MMA(1, 1, At, B1); BAR;
;       LDB(B0, 1, 0); SCHED; LDA(At, 1, 0); STAGE(SA(0, 1), A, brow + HALF, t + 2);
;       WAIT_L(8); BAR; WAIT_L(0); MMA(0, 0, At, B0); BAR; SCHED;
;       LDB(B1, 1, 1); STAGE(SB(1, 0), Bt, bcol, t + 3);
;       BAR; WAIT_L(0); MMA(0, 1, At, B1); BAR;
;       LDA(At, 1, 1); STAGE(SA(1, 0), A, brow, t + 3);
;       BAR; WAIT_L(0); MMA(1, 0, At, B0); BAR; SCHED;
;       STAGE(SB(1, 1), Bt, bcol + HALF, t + 3);
;       WAIT_V(6); BAR; MMA(1, 1, At, B1); BAR;
;     }
;     { LDB(B0, 0, 0); LDA(At, 0, 0); STAGE(SA(1, 1), A, brow + HALF, nt - 1);
;       BAR; WAIT_L(0); MMA(0, 0, At, B0); BAR;
;       LDB(B1, 0, 1); BAR; WAIT_L(0); MMA(0, 1, At, B1); BAR;
;       LDA(At, 0, 1); WAIT_V(4); BAR; WAIT_L(0); MMA(1, 0, At, B0); MMA(1, 1, At, B1); BAR; }
;     { LDB(B0, 1, 0); LDA(At, 1, 0); WAIT_V(2); BAR; WAIT_L(0); MMA(0, 0, At, B0); BAR;
;       LDB(B1, 1, 1); WAIT_V(0); BAR; WAIT_L(0); MMA(0, 1, At, B1); BAR;
;       LDA(At, 1, 1); BAR; WAIT_L(0); MMA(1, 0, At, B0); MMA(1, 1, At, B1); BAR; }
	v_mfma_f32_16x16x32_bf16 v[56:59], v[194:197], v[160:163], v[56:59]
	v_mfma_f32_16x16x32_bf16 v[48:51], v[202:205], v[160:163], v[48:51]
	v_mfma_f32_16x16x32_bf16 v[40:43], v[194:197], v[168:171], v[40:43]
	v_mfma_f32_16x16x32_bf16 v[32:35], v[202:205], v[168:171], v[32:35]
	v_mfma_f32_16x16x32_bf16 v[24:27], v[194:197], v[176:179], v[24:27]
	v_mfma_f32_16x16x32_bf16 v[16:19], v[202:205], v[176:179], v[16:19]
	v_mfma_f32_16x16x32_bf16 v[8:11], v[194:197], v[184:187], v[8:11]
	v_mfma_f32_16x16x32_bf16 v[0:3], v[202:205], v[184:187], v[0:3]
	v_mfma_f32_16x16x32_bf16 v[56:59], v[198:201], v[164:167], v[56:59]
	v_mfma_f32_16x16x32_bf16 v[48:51], v[206:209], v[164:167], v[48:51]
	v_mfma_f32_16x16x32_bf16 v[40:43], v[198:201], v[172:175], v[40:43]
	v_mfma_f32_16x16x32_bf16 v[32:35], v[206:209], v[172:175], v[32:35]
	v_mfma_f32_16x16x32_bf16 v[24:27], v[198:201], v[180:183], v[24:27]
	v_mfma_f32_16x16x32_bf16 v[16:19], v[206:209], v[180:183], v[16:19]
	v_mfma_f32_16x16x32_bf16 v[8:11], v[198:201], v[188:191], v[8:11]
	v_mfma_f32_16x16x32_bf16 v[0:3], v[206:209], v[188:191], v[0:3]
	v_mfma_f32_16x16x32_bf16 v[60:63], v[218:221], v[160:163], v[60:63]
	v_mfma_f32_16x16x32_bf16 v[52:55], v[226:229], v[160:163], v[52:55]
	v_mfma_f32_16x16x32_bf16 v[44:47], v[218:221], v[168:171], v[44:47]
	v_mfma_f32_16x16x32_bf16 v[36:39], v[226:229], v[168:171], v[36:39]
	v_mfma_f32_16x16x32_bf16 v[28:31], v[218:221], v[176:179], v[28:31]
	v_mfma_f32_16x16x32_bf16 v[20:23], v[226:229], v[176:179], v[20:23]
	v_mfma_f32_16x16x32_bf16 v[12:15], v[218:221], v[184:187], v[12:15]
	v_mfma_f32_16x16x32_bf16 v[4:7], v[226:229], v[184:187], v[4:7]
	v_mfma_f32_16x16x32_bf16 v[60:63], v[222:225], v[164:167], v[60:63]
	v_mfma_f32_16x16x32_bf16 v[52:55], v[230:233], v[164:167], v[52:55]
	v_mfma_f32_16x16x32_bf16 v[44:47], v[222:225], v[172:175], v[44:47]
	v_mfma_f32_16x16x32_bf16 v[36:39], v[230:233], v[172:175], v[36:39]
	v_mfma_f32_16x16x32_bf16 v[28:31], v[222:225], v[180:183], v[28:31]
	v_mfma_f32_16x16x32_bf16 v[20:23], v[230:233], v[180:183], v[20:23]
	v_mfma_f32_16x16x32_bf16 v[12:15], v[222:225], v[188:191], v[12:15]
	v_mfma_f32_16x16x32_bf16 v[4:7], v[230:233], v[188:191], v[4:7]
	s_branch .Lmy_join
.Lmy_kloop_sw:
	s_waitcnt vmcnt(12) lgkmcnt(0)
	s_barrier
	v_mfma_f32_16x16x32_bf16 v[120:123], v[128:131], v[194:197], v[120:123]
	v_mfma_f32_16x16x32_bf16 v[112:115], v[128:131], v[202:205], v[112:115]
	ds_read_b128 v[218:221], v235 offset:16384
	v_mfma_f32_16x16x32_bf16 v[104:107], v[136:139], v[194:197], v[104:107]
	ds_read_b128 v[222:225], v235 offset:17408
	v_mfma_f32_16x16x32_bf16 v[96:99], v[136:139], v[202:205], v[96:99]
	ds_read_b128 v[226:229], v235 offset:18432
	s_add_u32 m0, s40, 0x10000
	v_mfma_f32_16x16x32_bf16 v[88:91], v[144:147], v[194:197], v[88:91]
	ds_read_b128 v[230:233], v235 offset:19456
	v_mfma_f32_16x16x32_bf16 v[80:83], v[144:147], v[202:205], v[80:83]
	global_load_lds_dwordx4 v236, s[26:27]
	v_mfma_f32_16x16x32_bf16 v[72:75], v[152:155], v[194:197], v[72:75]
	v_mfma_f32_16x16x32_bf16 v[64:67], v[152:155], v[202:205], v[64:67]
	s_add_u32 m0, s40, 0x12000
	v_mfma_f32_16x16x32_bf16 v[120:123], v[132:135], v[198:201], v[120:123]
	v_mfma_f32_16x16x32_bf16 v[112:115], v[132:135], v[206:209], v[112:115]
	global_load_lds_dwordx4 v237, s[26:27]
	v_mfma_f32_16x16x32_bf16 v[104:107], v[140:143], v[198:201], v[104:107]
	v_mfma_f32_16x16x32_bf16 v[96:99], v[140:143], v[206:209], v[96:99]
	s_add_u32 s26, s26, 0x80
	s_addc_u32 s27, s27, 0
	v_mfma_f32_16x16x32_bf16 v[88:91], v[148:151], v[198:201], v[88:91]
	v_mfma_f32_16x16x32_bf16 v[80:83], v[148:151], v[206:209], v[80:83]
	v_mfma_f32_16x16x32_bf16 v[72:75], v[156:159], v[198:201], v[72:75]
	v_mfma_f32_16x16x32_bf16 v[64:67], v[156:159], v[206:209], v[64:67]
	s_waitcnt vmcnt(12) lgkmcnt(0)
	s_barrier
	v_mfma_f32_16x16x32_bf16 v[124:127], v[128:131], v[218:221], v[124:127]
	v_mfma_f32_16x16x32_bf16 v[116:119], v[128:131], v[226:229], v[116:119]
	ds_read_b128 v[160:163], v234 offset:16384
	v_mfma_f32_16x16x32_bf16 v[108:111], v[136:139], v[218:221], v[108:111]
	ds_read_b128 v[164:167], v234 offset:17408
	v_mfma_f32_16x16x32_bf16 v[100:103], v[136:139], v[226:229], v[100:103]
	ds_read_b128 v[168:171], v234 offset:18432
	s_add_u32 m0, s40, 0x14000
	v_mfma_f32_16x16x32_bf16 v[92:95], v[144:147], v[218:221], v[92:95]
	ds_read_b128 v[172:175], v234 offset:19456
	v_mfma_f32_16x16x32_bf16 v[84:87], v[144:147], v[226:229], v[84:87]
	ds_read_b128 v[176:179], v234 offset:20480
	global_load_lds_dwordx4 v236, s[38:39]
	v_mfma_f32_16x16x32_bf16 v[76:79], v[152:155], v[218:221], v[76:79]
	ds_read_b128 v[180:183], v234 offset:21504
	v_mfma_f32_16x16x32_bf16 v[68:71], v[152:155], v[226:229], v[68:71]
	ds_read_b128 v[184:187], v234 offset:22528
	s_add_u32 m0, s40, 0x16000
	v_mfma_f32_16x16x32_bf16 v[124:127], v[132:135], v[222:225], v[124:127]
	ds_read_b128 v[188:191], v234 offset:23552
	v_mfma_f32_16x16x32_bf16 v[116:119], v[132:135], v[230:233], v[116:119]
	global_load_lds_dwordx4 v237, s[38:39]
	v_mfma_f32_16x16x32_bf16 v[108:111], v[140:143], v[222:225], v[108:111]
	v_mfma_f32_16x16x32_bf16 v[100:103], v[140:143], v[230:233], v[100:103]
	s_add_u32 s38, s38, 0x80
	s_addc_u32 s39, s39, 0
	v_mfma_f32_16x16x32_bf16 v[92:95], v[148:151], v[222:225], v[92:95]
	v_mfma_f32_16x16x32_bf16 v[84:87], v[148:151], v[230:233], v[84:87]
	v_mfma_f32_16x16x32_bf16 v[76:79], v[156:159], v[222:225], v[76:79]
	v_mfma_f32_16x16x32_bf16 v[68:71], v[156:159], v[230:233], v[68:71]
	s_waitcnt vmcnt(12) lgkmcnt(0)
	s_barrier
; #define STAGE(P, BASE, br, kt) do { const u16* _gb = (BASE) + ((size_t)(br) * K + (size_t)(kt) * BK); \
;     __builtin_amdgcn_global_load_lds((const unsigned*)(_gb + goff0), (unsigned*)((char*)(P) + tid * 16), 16, 0, 0); \
;     __builtin_amdgcn_global_load_lds((const unsigned*)(_gb + (size_t)64 * K + goff0), (unsigned*)((char*)(P) + tid * 16 + 8192), 16, 0, 0); } while (0)
; #define LDA(dst, b, h) _Pragma("unroll") for (int m = 0; m < 4; ++m) _Pragma("unroll") for (int k = 0; k < 2; ++k) \
;     dst[m][k] = *reinterpret_cast<const bf16x8*>((char*)SA(b, h) + lds_byte(wr * 64 + m * 16 + fr, k * 32 + fq * 8))
; #define LDB(dst, b, h) _Pragma("unroll") for (int n = 0; n < 2; ++n) _Pragma("unroll") for (int k = 0; k < 2; ++k) \
;     dst[n][k] = *reinterpret_cast<const bf16x8*>((char*)SB(b, h) + lds_byte(wc * 32 + n * 16 + fr, k * 32 + fq * 8))
; #define WAIT_V(n) asm volatile("s_waitcnt vmcnt(" #n ")" ::: "memory")
; #define WAIT_L(n) asm volatile("s_waitcnt lgkmcnt(" #n ")" ::: "memory")
; #define BAR __builtin_amdgcn_s_barrier()
; #define SCHED __builtin_amdgcn_sched_barrier(0)
; __device__ __forceinline__ void gemm_phase(KP p, char* shmc, const u16* __restrict__ A,
;                                            const u16* __restrict__ Bt, const int N, const int K, const int mode,
;                                            const float* __restrict__ xin, const float resw) {
;     ...
;     for (int t = 0; t < nt - 2; t += 2) {
;       LDB(B0, 0, 0); SCHED; LDA(At, 0, 0); STAGE(SA(1, 1), A, brow + HALF, t + 1);
;       WAIT_L(8); BAR; WAIT_L(0); MMA(0, 0, At, B0); BAR; SCHED;
;       LDB(B1, 0, 1); STAGE(SB(0, 0), Bt, bcol, t + 2);
;       BAR; WAIT_L(0); MMA(0, 1, At, B1); BAR;
;       LDA(At, 0, 1); STAGE(SA(0, 0), A, brow, t + 2);
;       BAR; WAIT_L(0); MMA(1, 0, At, B0); BAR; SCHED;
;       STAGE(SB(0, 1), Bt, bcol + HALF, t + 2);
;       WAIT_V(6); BAR; MMA(1, 1, At, B1); BAR;
;       LDB(B0, 1, 0); SCHED; LDA(At, 1, 0); STAGE(SA(0, 1), A, brow + HALF, t + 2);
;       WAIT_L(8); BAR; WAIT_L(0); MMA(0, 0, At, B0); BAR; SCHED;
;       LDB(B1, 1, 1); STAGE(SB(1, 0), Bt, bcol, t + 3);
;       BAR; WAIT_L(0); MMA(0, 1, At, B1); BAR;
;       LDA(At, 1, 1); STAGE(SA(1, 0), A, brow, t + 3);
;       BAR; WAIT_L(0); MMA(1, 0, At, B0); BAR; SCHED;
;       STAGE(SB(1, 1), Bt, bcol + HALF, t + 3);
;       WAIT_V(6); BAR; MMA(1, 1, At, B1); BAR;
;     }
	v_mfma_f32_16x16x32_bf16 v[56:59], v[160:163], v[194:197], v[56:59]
	v_mfma_f32_16x16x32_bf16 v[48:51], v[160:163], v[202:205], v[48:51]
	ds_read_b128 v[128:131], v234 offset:32768
	v_mfma_f32_16x16x32_bf16 v[40:43], v[168:171], v[194:197], v[40:43]
	ds_read_b128 v[132:135], v234 offset:33792
	v_mfma_f32_16x16x32_bf16 v[32:35], v[168:171], v[202:205], v[32:35]
	ds_read_b128 v[136:139], v234 offset:34816
	s_add_u32 m0, s40, 0x4000
	v_mfma_f32_16x16x32_bf16 v[24:27], v[176:179], v[194:197], v[24:27]
	ds_read_b128 v[140:143], v234 offset:35840
	v_mfma_f32_16x16x32_bf16 v[16:19], v[176:179], v[202:205], v[16:19]
	ds_read_b128 v[144:147], v234 offset:36864
	global_load_lds_dwordx4 v236, s[8:9]
	v_mfma_f32_16x16x32_bf16 v[8:11], v[184:187], v[194:197], v[8:11]
	ds_read_b128 v[148:151], v234 offset:37888
	v_mfma_f32_16x16x32_bf16 v[0:3], v[184:187], v[202:205], v[0:3]
	ds_read_b128 v[152:155], v234 offset:38912
	s_add_u32 m0, s40, 0x6000
	v_mfma_f32_16x16x32_bf16 v[56:59], v[164:167], v[198:201], v[56:59]
	ds_read_b128 v[156:159], v234 offset:39936
	v_mfma_f32_16x16x32_bf16 v[48:51], v[164:167], v[206:209], v[48:51]
	global_load_lds_dwordx4 v237, s[8:9]
	v_mfma_f32_16x16x32_bf16 v[40:43], v[172:175], v[198:201], v[40:43]
	v_mfma_f32_16x16x32_bf16 v[32:35], v[172:175], v[206:209], v[32:35]
	s_add_u32 s8, s8, 0x80
	s_addc_u32 s9, s9, 0
	v_mfma_f32_16x16x32_bf16 v[24:27], v[180:183], v[198:201], v[24:27]
	v_mfma_f32_16x16x32_bf16 v[16:19], v[180:183], v[206:209], v[16:19]
	v_mfma_f32_16x16x32_bf16 v[8:11], v[188:191], v[198:201], v[8:11]
	v_mfma_f32_16x16x32_bf16 v[0:3], v[188:191], v[206:209], v[0:3]
	s_waitcnt vmcnt(12) lgkmcnt(0)
	s_barrier
	v_mfma_f32_16x16x32_bf16 v[60:63], v[160:163], v[218:221], v[60:63]
	v_mfma_f32_16x16x32_bf16 v[52:55], v[160:163], v[226:229], v[52:55]
	ds_read_b128 v[194:197], v235 offset:32768
	v_mfma_f32_16x16x32_bf16 v[44:47], v[168:171], v[218:221], v[44:47]
	ds_read_b128 v[198:201], v235 offset:33792
	v_mfma_f32_16x16x32_bf16 v[36:39], v[168:171], v[226:229], v[36:39]
	ds_read_b128 v[202:205], v235 offset:34816
	s_add_u32 m0, s40, 0x8000
	v_mfma_f32_16x16x32_bf16 v[28:31], v[176:179], v[218:221], v[28:31]
	ds_read_b128 v[206:209], v235 offset:35840
	v_mfma_f32_16x16x32_bf16 v[20:23], v[176:179], v[226:229], v[20:23]
	global_load_lds_dwordx4 v236, s[36:37]
	v_mfma_f32_16x16x32_bf16 v[12:15], v[184:187], v[218:221], v[12:15]
	v_mfma_f32_16x16x32_bf16 v[4:7], v[184:187], v[226:229], v[4:7]
	s_add_u32 m0, s40, 0xa000
	v_mfma_f32_16x16x32_bf16 v[60:63], v[164:167], v[222:225], v[60:63]
	v_mfma_f32_16x16x32_bf16 v[52:55], v[164:167], v[230:233], v[52:55]
	global_load_lds_dwordx4 v237, s[36:37]
	v_mfma_f32_16x16x32_bf16 v[44:47], v[172:175], v[222:225], v[44:47]
	v_mfma_f32_16x16x32_bf16 v[36:39], v[172:175], v[230:233], v[36:39]
	s_add_u32 s36, s36, 0x80
	s_addc_u32 s37, s37, 0
	v_mfma_f32_16x16x32_bf16 v[28:31], v[180:183], v[222:225], v[28:31]
	v_mfma_f32_16x16x32_bf16 v[20:23], v[180:183], v[230:233], v[20:23]
	v_mfma_f32_16x16x32_bf16 v[12:15], v[188:191], v[222:225], v[12:15]
	v_mfma_f32_16x16x32_bf16 v[4:7], v[188:191], v[230:233], v[4:7]
	s_waitcnt vmcnt(12) lgkmcnt(0)
	s_barrier
	v_mfma_f32_16x16x32_bf16 v[120:123], v[128:131], v[194:197], v[120:123]
	v_mfma_f32_16x16x32_bf16 v[112:115], v[128:131], v[202:205], v[112:115]
	ds_read_b128 v[218:221], v235 offset:49152
	v_mfma_f32_16x16x32_bf16 v[104:107], v[136:139], v[194:197], v[104:107]
	ds_read_b128 v[222:225], v235 offset:50176
	v_mfma_f32_16x16x32_bf16 v[96:99], v[136:139], v[202:205], v[96:99]
	ds_read_b128 v[226:229], v235 offset:51200
	s_add_u32 m0, s40, 0x18000
	v_mfma_f32_16x16x32_bf16 v[88:91], v[144:147], v[194:197], v[88:91]
	ds_read_b128 v[230:233], v235 offset:52224
	v_mfma_f32_16x16x32_bf16 v[80:83], v[144:147], v[202:205], v[80:83]
	global_load_lds_dwordx4 v236, s[26:27]
	v_mfma_f32_16x16x32_bf16 v[72:75], v[152:155], v[194:197], v[72:75]
	v_mfma_f32_16x16x32_bf16 v[64:67], v[152:155], v[202:205], v[64:67]
	s_add_u32 m0, s40, 0x1a000
	v_mfma_f32_16x16x32_bf16 v[120:123], v[132:135], v[198:201], v[120:123]
	v_mfma_f32_16x16x32_bf16 v[112:115], v[132:135], v[206:209], v[112:115]
	global_load_lds_dwordx4 v237, s[26:27]
	v_mfma_f32_16x16x32_bf16 v[104:107], v[140:143], v[198:201], v[104:107]
	v_mfma_f32_16x16x32_bf16 v[96:99], v[140:143], v[206:209], v[96:99]
	s_add_u32 s26, s26, 0x80
	s_addc_u32 s27, s27, 0
	v_mfma_f32_16x16x32_bf16 v[88:91], v[148:151], v[198:201], v[88:91]
	v_mfma_f32_16x16x32_bf16 v[80:83], v[148:151], v[206:209], v[80:83]
	v_mfma_f32_16x16x32_bf16 v[72:75], v[156:159], v[198:201], v[72:75]
	v_mfma_f32_16x16x32_bf16 v[64:67], v[156:159], v[206:209], v[64:67]
	s_waitcnt vmcnt(12) lgkmcnt(0)
	s_barrier
	v_mfma_f32_16x16x32_bf16 v[124:127], v[128:131], v[218:221], v[124:127]
	v_mfma_f32_16x16x32_bf16 v[116:119], v[128:131], v[226:229], v[116:119]
	ds_read_b128 v[160:163], v234 offset:49152
	v_mfma_f32_16x16x32_bf16 v[108:111], v[136:139], v[218:221], v[108:111]
	ds_read_b128 v[164:167], v234 offset:50176
	v_mfma_f32_16x16x32_bf16 v[100:103], v[136:139], v[226:229], v[100:103]
	ds_read_b128 v[168:171], v234 offset:51200
	s_add_u32 m0, s40, 0x1c000
	v_mfma_f32_16x16x32_bf16 v[92:95], v[144:147], v[218:221], v[92:95]
	ds_read_b128 v[172:175], v234 offset:52224
	v_mfma_f32_16x16x32_bf16 v[84:87], v[144:147], v[226:229], v[84:87]
	ds_read_b128 v[176:179], v234 offset:53248
	global_load_lds_dwordx4 v236, s[38:39]
	v_mfma_f32_16x16x32_bf16 v[76:79], v[152:155], v[218:221], v[76:79]
	ds_read_b128 v[180:183], v234 offset:54272
	v_mfma_f32_16x16x32_bf16 v[68:71], v[152:155], v[226:229], v[68:71]
	ds_read_b128 v[184:187], v234 offset:55296
	s_add_u32 m0, s40, 0x1e000
	v_mfma_f32_16x16x32_bf16 v[124:127], v[132:135], v[222:225], v[124:127]
	ds_read_b128 v[188:191], v234 offset:56320
	v_mfma_f32_16x16x32_bf16 v[116:119], v[132:135], v[230:233], v[116:119]
	global_load_lds_dwordx4 v237, s[38:39]
	v_mfma_f32_16x16x32_bf16 v[108:111], v[140:143], v[222:225], v[108:111]
	v_mfma_f32_16x16x32_bf16 v[100:103], v[140:143], v[230:233], v[100:103]
	s_add_u32 s38, s38, 0x80
	s_addc_u32 s39, s39, 0
	v_mfma_f32_16x16x32_bf16 v[92:95], v[148:151], v[222:225], v[92:95]
	v_mfma_f32_16x16x32_bf16 v[84:87], v[148:151], v[230:233], v[84:87]
	v_mfma_f32_16x16x32_bf16 v[76:79], v[156:159], v[222:225], v[76:79]
	v_mfma_f32_16x16x32_bf16 v[68:71], v[156:159], v[230:233], v[68:71]
	s_waitcnt vmcnt(12) lgkmcnt(0)
	s_barrier
; #define STAGE(P, BASE, br, kt) do { const u16* _gb = (BASE) + ((size_t)(br) * K + (size_t)(kt) * BK); \
;     __builtin_amdgcn_global_load_lds((const unsigned*)(_gb + goff0), (unsigned*)((char*)(P) + tid * 16), 16, 0, 0); \
;     __builtin_amdgcn_global_load_lds((const unsigned*)(_gb + (size_t)64 * K + goff0), (unsigned*)((char*)(P) + tid * 16 + 8192), 16, 0, 0); } while (0)
; #define LDA(dst, b, h) _Pragma("unroll") for (int m = 0; m < 4; ++m) _Pragma("unroll") for (int k = 0; k < 2; ++k) \
;     dst[m][k] = *reinterpret_cast<const bf16x8*>((char*)SA(b, h) + lds_byte(wr * 64 + m * 16 + fr, k * 32 + fq * 8))
; #define WAIT_V(n) asm volatile("s_waitcnt vmcnt(" #n ")" ::: "memory")
; #define WAIT_L(n) asm volatile("s_waitcnt lgkmcnt(" #n ")" ::: "memory")
; #define BAR __builtin_amdgcn_s_barrier()
; __device__ __forceinline__ void gemm_phase(KP p, char* shmc, const u16* __restrict__ A,
;                                            const u16* __restrict__ Bt, const int N, const int K, const int mode,
;                                            const float* __restrict__ xin, const float resw) {
;     ...
;     for (int t = 0; t < nt - 2; t += 2) {
;       LDB(B0, 0, 0); SCHED; LDA(At, 0, 0); STAGE(SA(1, 1), A, brow + HALF, t + 1);
;       WAIT_L(8); BAR; WAIT_L(0); MMA(0, 0, At, B0); BAR; SCHED;
;       LDB(B1, 0, 1); STAGE(SB(0, 0), Bt, bcol, t + 2);
;       BAR; WAIT_L(0); MMA(0, 1, At, B1); BAR;
;       LDA(At, 0, 1); STAGE(SA(0, 0), A, brow, t + 2);
;       BAR; WAIT_L(0); MMA(1, 0, At, B0); BAR; SCHED;
;       STAGE(SB(0, 1), Bt, bcol + HALF, t + 2);
;       WAIT_V(6); BAR; MMA(1, 1, At, B1); BAR;
;       LDB(B0, 1, 0); SCHED; LDA(At, 1, 0); STAGE(SA(0, 1), A, brow + HALF, t + 2);
;       WAIT_L(8); BAR; WAIT_L(0); MMA(0, 0, At, B0); BAR; SCHED;
;       LDB(B1, 1, 1); STAGE(SB(1, 0), Bt, bcol, t + 3);
;       BAR; WAIT_L(0); MMA(0, 1, At, B1); BAR;
;       LDA(At, 1, 1); STAGE(SA(1, 0), A, brow, t + 3);
;       BAR; WAIT_L(0); MMA(1, 0, At, B0); BAR; SCHED;
;       STAGE(SB(1, 1), Bt, bcol + HALF, t + 3);
;       WAIT_V(6); BAR; MMA(1, 1, At, B1); BAR;
;     }
;     { LDB(B0, 0, 0); LDA(At, 0, 0); STAGE(SA(1, 1), A, brow + HALF, nt - 1);
;       BAR; WAIT_L(0); MMA(0, 0, At, B0); BAR;
;       LDB(B1, 0, 1); BAR; WAIT_L(0); MMA(0, 1, At, B1); BAR;
;       LDA(At, 0, 1); WAIT_V(4); BAR; WAIT_L(0); MMA(1, 0, At, B0); MMA(1, 1, At, B1); BAR; }
	v_mfma_f32_16x16x32_bf16 v[56:59], v[160:163], v[194:197], v[56:59]
	v_mfma_f32_16x16x32_bf16 v[48:51], v[160:163], v[202:205], v[48:51]
	ds_read_b128 v[128:131], v234 offset:0
	v_mfma_f32_16x16x32_bf16 v[40:43], v[168:171], v[194:197], v[40:43]
	ds_read_b128 v[132:135], v234 offset:1024
	v_mfma_f32_16x16x32_bf16 v[32:35], v[168:171], v[202:205], v[32:35]
	ds_read_b128 v[136:139], v234 offset:2048
	s_add_u32 m0, s40, 0xc000
	v_mfma_f32_16x16x32_bf16 v[24:27], v[176:179], v[194:197], v[24:27]
	ds_read_b128 v[140:143], v234 offset:3072
	v_mfma_f32_16x16x32_bf16 v[16:19], v[176:179], v[202:205], v[16:19]
	ds_read_b128 v[144:147], v234 offset:4096
	global_load_lds_dwordx4 v236, s[8:9]
	v_mfma_f32_16x16x32_bf16 v[8:11], v[184:187], v[194:197], v[8:11]
	ds_read_b128 v[148:151], v234 offset:5120
	v_mfma_f32_16x16x32_bf16 v[0:3], v[184:187], v[202:205], v[0:3]
	ds_read_b128 v[152:155], v234 offset:6144
	s_add_u32 m0, s40, 0xe000
	v_mfma_f32_16x16x32_bf16 v[56:59], v[164:167], v[198:201], v[56:59]
	ds_read_b128 v[156:159], v234 offset:7168
	v_mfma_f32_16x16x32_bf16 v[48:51], v[164:167], v[206:209], v[48:51]
	global_load_lds_dwordx4 v237, s[8:9]
	v_mfma_f32_16x16x32_bf16 v[40:43], v[172:175], v[198:201], v[40:43]
	v_mfma_f32_16x16x32_bf16 v[32:35], v[172:175], v[206:209], v[32:35]
	s_add_u32 s8, s8, 0x80
	s_addc_u32 s9, s9, 0
	v_mfma_f32_16x16x32_bf16 v[24:27], v[180:183], v[198:201], v[24:27]
	v_mfma_f32_16x16x32_bf16 v[16:19], v[180:183], v[206:209], v[16:19]
	v_mfma_f32_16x16x32_bf16 v[8:11], v[188:191], v[198:201], v[8:11]
	v_mfma_f32_16x16x32_bf16 v[0:3], v[188:191], v[206:209], v[0:3]
	s_waitcnt vmcnt(12) lgkmcnt(0)
	s_barrier
	v_mfma_f32_16x16x32_bf16 v[60:63], v[160:163], v[218:221], v[60:63]
	v_mfma_f32_16x16x32_bf16 v[52:55], v[160:163], v[226:229], v[52:55]
	ds_read_b128 v[194:197], v235 offset:0
	v_mfma_f32_16x16x32_bf16 v[44:47], v[168:171], v[218:221], v[44:47]
	ds_read_b128 v[198:201], v235 offset:1024
	v_mfma_f32_16x16x32_bf16 v[36:39], v[168:171], v[226:229], v[36:39]
	ds_read_b128 v[202:205], v235 offset:2048
	s_add_u32 m0, s40, 0x0
	v_mfma_f32_16x16x32_bf16 v[28:31], v[176:179], v[218:221], v[28:31]
	ds_read_b128 v[206:209], v235 offset:3072
	v_mfma_f32_16x16x32_bf16 v[20:23], v[176:179], v[226:229], v[20:23]
	global_load_lds_dwordx4 v236, s[36:37]
	v_mfma_f32_16x16x32_bf16 v[12:15], v[184:187], v[218:221], v[12:15]
	v_mfma_f32_16x16x32_bf16 v[4:7], v[184:187], v[226:229], v[4:7]
	s_add_u32 m0, s40, 0x2000
	v_mfma_f32_16x16x32_bf16 v[60:63], v[164:167], v[222:225], v[60:63]
	v_mfma_f32_16x16x32_bf16 v[52:55], v[164:167], v[230:233], v[52:55]
	global_load_lds_dwordx4 v237, s[36:37]
	v_mfma_f32_16x16x32_bf16 v[44:47], v[172:175], v[222:225], v[44:47]
	v_mfma_f32_16x16x32_bf16 v[36:39], v[172:175], v[230:233], v[36:39]
	s_add_u32 s36, s36, 0x80
	s_addc_u32 s37, s37, 0
	v_mfma_f32_16x16x32_bf16 v[28:31], v[180:183], v[222:225], v[28:31]
	v_mfma_f32_16x16x32_bf16 v[20:23], v[180:183], v[230:233], v[20:23]
	v_mfma_f32_16x16x32_bf16 v[12:15], v[188:191], v[222:225], v[12:15]
	v_mfma_f32_16x16x32_bf16 v[4:7], v[188:191], v[230:233], v[4:7]
	s_add_i32 s41, s41, -1
	s_cmp_lg_u32 s41, 0
	s_cbranch_scc1 .Lmy_kloop_sw
	s_waitcnt vmcnt(12) lgkmcnt(0)
	s_barrier
	v_mfma_f32_16x16x32_bf16 v[120:123], v[128:131], v[194:197], v[120:123]
	v_mfma_f32_16x16x32_bf16 v[112:115], v[128:131], v[202:205], v[112:115]
	ds_read_b128 v[218:221], v235 offset:16384
	v_mfma_f32_16x16x32_bf16 v[104:107], v[136:139], v[194:197], v[104:107]
	ds_read_b128 v[222:225], v235 offset:17408
	v_mfma_f32_16x16x32_bf16 v[96:99], v[136:139], v[202:205], v[96:99]
	ds_read_b128 v[226:229], v235 offset:18432
	s_add_u32 m0, s40, 0x10000
	v_mfma_f32_16x16x32_bf16 v[88:91], v[144:147], v[194:197], v[88:91]
	ds_read_b128 v[230:233], v235 offset:19456
	v_mfma_f32_16x16x32_bf16 v[80:83], v[144:147], v[202:205], v[80:83]
	global_load_lds_dwordx4 v236, s[26:27]
	v_mfma_f32_16x16x32_bf16 v[72:75], v[152:155], v[194:197], v[72:75]
	v_mfma_f32_16x16x32_bf16 v[64:67], v[152:155], v[202:205], v[64:67]
	s_add_u32 m0, s40, 0x12000
	v_mfma_f32_16x16x32_bf16 v[120:123], v[132:135], v[198:201], v[120:123]
	v_mfma_f32_16x16x32_bf16 v[112:115], v[132:135], v[206:209], v[112:115]
	global_load_lds_dwordx4 v237, s[26:27]
	v_mfma_f32_16x16x32_bf16 v[104:107], v[140:143], v[198:201], v[104:107]
	v_mfma_f32_16x16x32_bf16 v[96:99], v[140:143], v[206:209], v[96:99]
	s_add_u32 s26, s26, 0x80
	s_addc_u32 s27, s27, 0
	v_mfma_f32_16x16x32_bf16 v[88:91], v[148:151], v[198:201], v[88:91]
	v_mfma_f32_16x16x32_bf16 v[80:83], v[148:151], v[206:209], v[80:83]
	v_mfma_f32_16x16x32_bf16 v[72:75], v[156:159], v[198:201], v[72:75]
	v_mfma_f32_16x16x32_bf16 v[64:67], v[156:159], v[206:209], v[64:67]
	s_waitcnt vmcnt(12) lgkmcnt(0)
	s_barrier
	v_mfma_f32_16x16x32_bf16 v[124:127], v[128:131], v[218:221], v[124:127]
	v_mfma_f32_16x16x32_bf16 v[116:119], v[128:131], v[226:229], v[116:119]
	ds_read_b128 v[160:163], v234 offset:16384
	v_mfma_f32_16x16x32_bf16 v[108:111], v[136:139], v[218:221], v[108:111]
	ds_read_b128 v[164:167], v234 offset:17408
	v_mfma_f32_16x16x32_bf16 v[100:103], v[136:139], v[226:229], v[100:103]
	ds_read_b128 v[168:171], v234 offset:18432
	s_add_u32 m0, s40, 0x14000
	v_mfma_f32_16x16x32_bf16 v[92:95], v[144:147], v[218:221], v[92:95]
	ds_read_b128 v[172:175], v234 offset:19456
	v_mfma_f32_16x16x32_bf16 v[84:87], v[144:147], v[226:229], v[84:87]
	ds_read_b128 v[176:179], v234 offset:20480
	global_load_lds_dwordx4 v236, s[38:39]
	v_mfma_f32_16x16x32_bf16 v[76:79], v[152:155], v[218:221], v[76:79]
	ds_read_b128 v[180:183], v234 offset:21504
	v_mfma_f32_16x16x32_bf16 v[68:71], v[152:155], v[226:229], v[68:71]
	ds_read_b128 v[184:187], v234 offset:22528
	s_add_u32 m0, s40, 0x16000
	v_mfma_f32_16x16x32_bf16 v[124:127], v[132:135], v[222:225], v[124:127]
	ds_read_b128 v[188:191], v234 offset:23552
	v_mfma_f32_16x16x32_bf16 v[116:119], v[132:135], v[230:233], v[116:119]
	global_load_lds_dwordx4 v237, s[38:39]
	v_mfma_f32_16x16x32_bf16 v[108:111], v[140:143], v[222:225], v[108:111]
	v_mfma_f32_16x16x32_bf16 v[100:103], v[140:143], v[230:233], v[100:103]
	s_add_u32 s38, s38, 0x80
	s_addc_u32 s39, s39, 0
	v_mfma_f32_16x16x32_bf16 v[92:95], v[148:151], v[222:225], v[92:95]
	v_mfma_f32_16x16x32_bf16 v[84:87], v[148:151], v[230:233], v[84:87]
	v_mfma_f32_16x16x32_bf16 v[76:79], v[156:159], v[222:225], v[76:79]
	v_mfma_f32_16x16x32_bf16 v[68:71], v[156:159], v[230:233], v[68:71]
	s_waitcnt vmcnt(12) lgkmcnt(0)
	s_barrier
; #define STAGE(P, BASE, br, kt) do { const u16* _gb = (BASE) + ((size_t)(br) * K + (size_t)(kt) * BK); \
;     __builtin_amdgcn_global_load_lds((const unsigned*)(_gb + goff0), (unsigned*)((char*)(P) + tid * 16), 16, 0, 0); \
;     __builtin_amdgcn_global_load_lds((const unsigned*)(_gb + (size_t)64 * K + goff0), (unsigned*)((char*)(P) + tid * 16 + 8192), 16, 0, 0); } while (0)
; #define WAIT_V(n) asm volatile("s_waitcnt vmcnt(" #n ")" ::: "memory")
; #define WAIT_L(n) asm volatile("s_waitcnt lgkmcnt(" #n ")" ::: "memory")
; #define BAR __builtin_amdgcn_s_barrier()
; __device__ __forceinline__ void gemm_phase(KP p, char* shmc, const u16* __restrict__ A,
;                                            const u16* __restrict__ Bt, const int N, const int K, const int mode,
;                                            const float* __restrict__ xin, const float resw) {
;     ...
;     for (int t = 0; t < nt - 2; t += 2) {
;       LDB(B0, 0, 0); SCHED; LDA(At, 0, 0); STAGE(SA(1, 1), A, brow + HALF, t + 1);
;       WAIT_L(8); BAR; WAIT_L(0); MMA(0, 0, At, B0); BAR; SCHED;
;       LDB(B1, 0, 1); STAGE(SB(0, 0), Bt, bcol, t + 2);
;       BAR; WAIT_L(0); MMA(0, 1, At, B1); BAR;
;       LDA(At, 0, 1); STAGE(SA(0, 0), A, brow, t + 2);
;       BAR; WAIT_L(0); MMA(1, 0, At, B0); BAR; SCHED;
;       STAGE(SB(0, 1), Bt, bcol + HALF, t + 2);
;       WAIT_V(6); BAR; MMA(1, 1, At, B1); BAR;
;       LDB(B0, 1, 0); SCHED; LDA(At, 1, 0); STAGE(SA(0, 1), A, brow + HALF, t + 2);
;       WAIT_L(8); BAR; WAIT_L(0); MMA(0, 0, At, B0); BAR; SCHED;
;       LDB(B1, 1, 1); STAGE(SB(1, 0), Bt, bcol, t + 3);
;       BAR; WAIT_L(0); MMA(0, 1, At, B1); BAR;
;       LDA(At, 1, 1); STAGE(SA(1, 0), A, brow, t + 3);
;       BAR; WAIT_L(0); MMA(1, 0, At, B0); BAR; SCHED;
;       STAGE(SB(1, 1), Bt, bcol + HALF, t + 3);
;       WAIT_V(6); BAR; MMA(1, 1, At, B1); BAR;
;     }
;     { LDB(B0, 0, 0); LDA(At, 0, 0); STAGE(SA(1, 1), A, brow + HALF, nt - 1);
;       BAR; WAIT_L(0); MMA(0, 0, At, B0); BAR;
;       LDB(B1, 0, 1); BAR; WAIT_L(0); MMA(0, 1, At, B1); BAR;
;       LDA(At, 0, 1); WAIT_V(4); BAR; WAIT_L(0); MMA(1, 0, At, B0); MMA(1, 1, At, B1); BAR; }
;     { LDB(B0, 1, 0); LDA(At, 1, 0); WAIT_V(2); BAR; WAIT_L(0); MMA(0, 0, At, B0); BAR;
;       LDB(B1, 1, 1); WAIT_V(0); BAR; WAIT_L(0); MMA(0, 1, At, B1); BAR;
;       LDA(At, 1, 1); BAR; WAIT_L(0); MMA(1, 0, At, B0); MMA(1, 1, At, B1); BAR; }
	v_mfma_f32_16x16x32_bf16 v[56:59], v[160:163], v[194:197], v[56:59]
	v_mfma_f32_16x16x32_bf16 v[48:51], v[160:163], v[202:205], v[48:51]
	ds_read_b128 v[128:131], v234 offset:32768
	v_mfma_f32_16x16x32_bf16 v[40:43], v[168:171], v[194:197], v[40:43]
	ds_read_b128 v[132:135], v234 offset:33792
	v_mfma_f32_16x16x32_bf16 v[32:35], v[168:171], v[202:205], v[32:35]
	ds_read_b128 v[136:139], v234 offset:34816
	s_add_u32 m0, s40, 0x4000
	v_mfma_f32_16x16x32_bf16 v[24:27], v[176:179], v[194:197], v[24:27]
	ds_read_b128 v[140:143], v234 offset:35840
	v_mfma_f32_16x16x32_bf16 v[16:19], v[176:179], v[202:205], v[16:19]
	ds_read_b128 v[144:147], v234 offset:36864
	global_load_lds_dwordx4 v236, s[8:9]
	v_mfma_f32_16x16x32_bf16 v[8:11], v[184:187], v[194:197], v[8:11]
	ds_read_b128 v[148:151], v234 offset:37888
	v_mfma_f32_16x16x32_bf16 v[0:3], v[184:187], v[202:205], v[0:3]
	ds_read_b128 v[152:155], v234 offset:38912
	s_add_u32 m0, s40, 0x6000
	v_mfma_f32_16x16x32_bf16 v[56:59], v[164:167], v[198:201], v[56:59]
	ds_read_b128 v[156:159], v234 offset:39936
	v_mfma_f32_16x16x32_bf16 v[48:51], v[164:167], v[206:209], v[48:51]
	global_load_lds_dwordx4 v237, s[8:9]
	v_mfma_f32_16x16x32_bf16 v[40:43], v[172:175], v[198:201], v[40:43]
	v_mfma_f32_16x16x32_bf16 v[32:35], v[172:175], v[206:209], v[32:35]
	s_add_u32 s8, s8, 0x80
	s_addc_u32 s9, s9, 0
	v_mfma_f32_16x16x32_bf16 v[24:27], v[180:183], v[198:201], v[24:27]
	v_mfma_f32_16x16x32_bf16 v[16:19], v[180:183], v[206:209], v[16:19]
	v_mfma_f32_16x16x32_bf16 v[8:11], v[188:191], v[198:201], v[8:11]
	v_mfma_f32_16x16x32_bf16 v[0:3], v[188:191], v[206:209], v[0:3]
	s_waitcnt vmcnt(12) lgkmcnt(0)
	s_barrier
	v_mfma_f32_16x16x32_bf16 v[60:63], v[160:163], v[218:221], v[60:63]
	v_mfma_f32_16x16x32_bf16 v[52:55], v[160:163], v[226:229], v[52:55]
	ds_read_b128 v[194:197], v235 offset:32768
	v_mfma_f32_16x16x32_bf16 v[44:47], v[168:171], v[218:221], v[44:47]
	ds_read_b128 v[198:201], v235 offset:33792
	v_mfma_f32_16x16x32_bf16 v[36:39], v[168:171], v[226:229], v[36:39]
	ds_read_b128 v[202:205], v235 offset:34816
	s_add_u32 m0, s40, 0x8000
	v_mfma_f32_16x16x32_bf16 v[28:31], v[176:179], v[218:221], v[28:31]
	ds_read_b128 v[206:209], v235 offset:35840
	v_mfma_f32_16x16x32_bf16 v[20:23], v[176:179], v[226:229], v[20:23]
	global_load_lds_dwordx4 v236, s[36:37]
	v_mfma_f32_16x16x32_bf16 v[12:15], v[184:187], v[218:221], v[12:15]
	v_mfma_f32_16x16x32_bf16 v[4:7], v[184:187], v[226:229], v[4:7]
	s_add_u32 m0, s40, 0xa000
	v_mfma_f32_16x16x32_bf16 v[60:63], v[164:167], v[222:225], v[60:63]
	v_mfma_f32_16x16x32_bf16 v[52:55], v[164:167], v[230:233], v[52:55]
	global_load_lds_dwordx4 v237, s[36:37]
	v_mfma_f32_16x16x32_bf16 v[44:47], v[172:175], v[222:225], v[44:47]
	v_mfma_f32_16x16x32_bf16 v[36:39], v[172:175], v[230:233], v[36:39]
	s_add_u32 s36, s36, 0x80
	s_addc_u32 s37, s37, 0
	v_mfma_f32_16x16x32_bf16 v[28:31], v[180:183], v[222:225], v[28:31]
	v_mfma_f32_16x16x32_bf16 v[20:23], v[180:183], v[230:233], v[20:23]
	v_mfma_f32_16x16x32_bf16 v[12:15], v[188:191], v[222:225], v[12:15]
	v_mfma_f32_16x16x32_bf16 v[4:7], v[188:191], v[230:233], v[4:7]
	s_waitcnt vmcnt(12) lgkmcnt(0)
	s_barrier
	v_mfma_f32_16x16x32_bf16 v[120:123], v[128:131], v[194:197], v[120:123]
	v_mfma_f32_16x16x32_bf16 v[112:115], v[128:131], v[202:205], v[112:115]
	ds_read_b128 v[218:221], v235 offset:49152
	v_mfma_f32_16x16x32_bf16 v[104:107], v[136:139], v[194:197], v[104:107]
	ds_read_b128 v[222:225], v235 offset:50176
	v_mfma_f32_16x16x32_bf16 v[96:99], v[136:139], v[202:205], v[96:99]
	ds_read_b128 v[226:229], v235 offset:51200
	s_add_u32 m0, s40, 0x18000
	v_mfma_f32_16x16x32_bf16 v[88:91], v[144:147], v[194:197], v[88:91]
	ds_read_b128 v[230:233], v235 offset:52224
	v_mfma_f32_16x16x32_bf16 v[80:83], v[144:147], v[202:205], v[80:83]
	global_load_lds_dwordx4 v236, s[26:27]
	v_mfma_f32_16x16x32_bf16 v[72:75], v[152:155], v[194:197], v[72:75]
	v_mfma_f32_16x16x32_bf16 v[64:67], v[152:155], v[202:205], v[64:67]
	s_add_u32 m0, s40, 0x1a000
	v_mfma_f32_16x16x32_bf16 v[120:123], v[132:135], v[198:201], v[120:123]
	v_mfma_f32_16x16x32_bf16 v[112:115], v[132:135], v[206:209], v[112:115]
	global_load_lds_dwordx4 v237, s[26:27]
	v_mfma_f32_16x16x32_bf16 v[104:107], v[140:143], v[198:201], v[104:107]
	v_mfma_f32_16x16x32_bf16 v[96:99], v[140:143], v[206:209], v[96:99]
	s_add_u32 s26, s26, 0x80
	s_addc_u32 s27, s27, 0
	v_mfma_f32_16x16x32_bf16 v[88:91], v[148:151], v[198:201], v[88:91]
	v_mfma_f32_16x16x32_bf16 v[80:83], v[148:151], v[206:209], v[80:83]
	v_mfma_f32_16x16x32_bf16 v[72:75], v[156:159], v[198:201], v[72:75]
	v_mfma_f32_16x16x32_bf16 v[64:67], v[156:159], v[206:209], v[64:67]
	s_waitcnt vmcnt(12) lgkmcnt(0)
	s_barrier
	v_mfma_f32_16x16x32_bf16 v[124:127], v[128:131], v[218:221], v[124:127]
	v_mfma_f32_16x16x32_bf16 v[116:119], v[128:131], v[226:229], v[116:119]
	ds_read_b128 v[160:163], v234 offset:49152
	v_mfma_f32_16x16x32_bf16 v[108:111], v[136:139], v[218:221], v[108:111]
	ds_read_b128 v[164:167], v234 offset:50176
	v_mfma_f32_16x16x32_bf16 v[100:103], v[136:139], v[226:229], v[100:103]
	ds_read_b128 v[168:171], v234 offset:51200
	s_add_u32 m0, s40, 0x1c000
	v_mfma_f32_16x16x32_bf16 v[92:95], v[144:147], v[218:221], v[92:95]
	ds_read_b128 v[172:175], v234 offset:52224
	v_mfma_f32_16x16x32_bf16 v[84:87], v[144:147], v[226:229], v[84:87]
	ds_read_b128 v[176:179], v234 offset:53248
	global_load_lds_dwordx4 v236, s[38:39]
	v_mfma_f32_16x16x32_bf16 v[76:79], v[152:155], v[218:221], v[76:79]
	ds_read_b128 v[180:183], v234 offset:54272
	v_mfma_f32_16x16x32_bf16 v[68:71], v[152:155], v[226:229], v[68:71]
	ds_read_b128 v[184:187], v234 offset:55296
	s_add_u32 m0, s40, 0x1e000
	v_mfma_f32_16x16x32_bf16 v[124:127], v[132:135], v[222:225], v[124:127]
	ds_read_b128 v[188:191], v234 offset:56320
	v_mfma_f32_16x16x32_bf16 v[116:119], v[132:135], v[230:233], v[116:119]
	global_load_lds_dwordx4 v237, s[38:39]
	v_mfma_f32_16x16x32_bf16 v[108:111], v[140:143], v[222:225], v[108:111]
	v_mfma_f32_16x16x32_bf16 v[100:103], v[140:143], v[230:233], v[100:103]
	s_add_u32 s38, s38, 0x80
	s_addc_u32 s39, s39, 0
	v_mfma_f32_16x16x32_bf16 v[92:95], v[148:151], v[222:225], v[92:95]
	v_mfma_f32_16x16x32_bf16 v[84:87], v[148:151], v[230:233], v[84:87]
	v_mfma_f32_16x16x32_bf16 v[76:79], v[156:159], v[222:225], v[76:79]
	v_mfma_f32_16x16x32_bf16 v[68:71], v[156:159], v[230:233], v[68:71]
	s_waitcnt vmcnt(12) lgkmcnt(0)
	s_barrier
; #define STAGE(P, BASE, br, kt) do { const u16* _gb = (BASE) + ((size_t)(br) * K + (size_t)(kt) * BK); \
;     __builtin_amdgcn_global_load_lds((const unsigned*)(_gb + goff0), (unsigned*)((char*)(P) + tid * 16), 16, 0, 0); \
;     __builtin_amdgcn_global_load_lds((const unsigned*)(_gb + (size_t)64 * K + goff0), (unsigned*)((char*)(P) + tid * 16 + 8192), 16, 0, 0); } while (0)
; #define LDA(dst, b, h) _Pragma("unroll") for (int m = 0; m < 4; ++m) _Pragma("unroll") for (int k = 0; k < 2; ++k) \
;     dst[m][k] = *reinterpret_cast<const bf16x8*>((char*)SA(b, h) + lds_byte(wr * 64 + m * 16 + fr, k * 32 + fq * 8))
; #define LDB(dst, b, h) _Pragma("unroll") for (int n = 0; n < 2; ++n) _Pragma("unroll") for (int k = 0; k < 2; ++k) \
;     dst[n][k] = *reinterpret_cast<const bf16x8*>((char*)SB(b, h) + lds_byte(wc * 32 + n * 16 + fr, k * 32 + fq * 8))
; #define MMA(ai, bj, At, Bt_) do { __builtin_amdgcn_s_setprio(1); \
;     _Pragma("unroll") for (int m = 0; m < 4; ++m) _Pragma("unroll") for (int n = 0; n < 2; ++n) _Pragma("unroll") for (int k = 0; k < 2; ++k) \
;       acc[ai][bj][m][n] = __builtin_amdgcn_mfma_f32_16x16x32_bf16(Bt_[n][k], At[m][k], acc[ai][bj][m][n], 0, 0, 0); \
;     __builtin_amdgcn_s_setprio(0); } while (0)
; #define WAIT_V(n) asm volatile("s_waitcnt vmcnt(" #n ")" ::: "memory")
; #define WAIT_L(n) asm volatile("s_waitcnt lgkmcnt(" #n ")" ::: "memory")
; #define BAR __builtin_amdgcn_s_barrier()
; __device__ __forceinline__ void gemm_phase(KP p, char* shmc, const u16* __restrict__ A,
;                                            const u16* __restrict__ Bt, const int N, const int K, const int mode,
;                                            const float* __restrict__ xin, const float resw) {
;     ...
;     { LDB(B0, 0, 0); LDA(At, 0, 0); STAGE(SA(1, 1), A, brow + HALF, nt - 1);
;       BAR; WAIT_L(0); MMA(0, 0, At, B0); BAR;
;       LDB(B1, 0, 1); BAR; WAIT_L(0); MMA(0, 1, At, B1); BAR;
;       LDA(At, 0, 1); WAIT_V(4); BAR; WAIT_L(0); MMA(1, 0, At, B0); MMA(1, 1, At, B1); BAR; }
;     { LDB(B0, 1, 0); LDA(At, 1, 0); WAIT_V(2); BAR; WAIT_L(0); MMA(0, 0, At, B0); BAR;
;       LDB(B1, 1, 1); WAIT_V(0); BAR; WAIT_L(0); MMA(0, 1, At, B1); BAR;
;       LDA(At, 1, 1); BAR; WAIT_L(0); MMA(1, 0, At, B0); MMA(1, 1, At, B1); BAR; }
	v_mfma_f32_16x16x32_bf16 v[56:59], v[160:163], v[194:197], v[56:59]
	v_mfma_f32_16x16x32_bf16 v[48:51], v[160:163], v[202:205], v[48:51]
	ds_read_b128 v[128:131], v234 offset:0
	v_mfma_f32_16x16x32_bf16 v[40:43], v[168:171], v[194:197], v[40:43]
	ds_read_b128 v[132:135], v234 offset:1024
	v_mfma_f32_16x16x32_bf16 v[32:35], v[168:171], v[202:205], v[32:35]
	ds_read_b128 v[136:139], v234 offset:2048
	s_add_u32 m0, s40, 0xc000
	v_mfma_f32_16x16x32_bf16 v[24:27], v[176:179], v[194:197], v[24:27]
	ds_read_b128 v[140:143], v234 offset:3072
	v_mfma_f32_16x16x32_bf16 v[16:19], v[176:179], v[202:205], v[16:19]
	ds_read_b128 v[144:147], v234 offset:4096
	global_load_lds_dwordx4 v236, s[8:9]
	v_mfma_f32_16x16x32_bf16 v[8:11], v[184:187], v[194:197], v[8:11]
	ds_read_b128 v[148:151], v234 offset:5120
	v_mfma_f32_16x16x32_bf16 v[0:3], v[184:187], v[202:205], v[0:3]
	ds_read_b128 v[152:155], v234 offset:6144
	s_add_u32 m0, s40, 0xe000
	v_mfma_f32_16x16x32_bf16 v[56:59], v[164:167], v[198:201], v[56:59]
	ds_read_b128 v[156:159], v234 offset:7168
	v_mfma_f32_16x16x32_bf16 v[48:51], v[164:167], v[206:209], v[48:51]
	global_load_lds_dwordx4 v237, s[8:9]
	v_mfma_f32_16x16x32_bf16 v[40:43], v[172:175], v[198:201], v[40:43]
	v_mfma_f32_16x16x32_bf16 v[32:35], v[172:175], v[206:209], v[32:35]
	s_add_u32 s8, s8, 0x80
	s_addc_u32 s9, s9, 0
	v_mfma_f32_16x16x32_bf16 v[24:27], v[180:183], v[198:201], v[24:27]
	v_mfma_f32_16x16x32_bf16 v[16:19], v[180:183], v[206:209], v[16:19]
	v_mfma_f32_16x16x32_bf16 v[8:11], v[188:191], v[198:201], v[8:11]
	v_mfma_f32_16x16x32_bf16 v[0:3], v[188:191], v[206:209], v[0:3]
	s_waitcnt vmcnt(12) lgkmcnt(0)
	s_barrier
	v_mfma_f32_16x16x32_bf16 v[60:63], v[160:163], v[218:221], v[60:63]
	v_mfma_f32_16x16x32_bf16 v[52:55], v[160:163], v[226:229], v[52:55]
	ds_read_b128 v[194:197], v235 offset:0
	v_mfma_f32_16x16x32_bf16 v[44:47], v[168:171], v[218:221], v[44:47]
	ds_read_b128 v[198:201], v235 offset:1024
	v_mfma_f32_16x16x32_bf16 v[36:39], v[168:171], v[226:229], v[36:39]
	ds_read_b128 v[202:205], v235 offset:2048
	v_mfma_f32_16x16x32_bf16 v[28:31], v[176:179], v[218:221], v[28:31]
	ds_read_b128 v[206:209], v235 offset:3072
	v_mfma_f32_16x16x32_bf16 v[20:23], v[176:179], v[226:229], v[20:23]
	v_mfma_f32_16x16x32_bf16 v[12:15], v[184:187], v[218:221], v[12:15]
	v_mfma_f32_16x16x32_bf16 v[4:7], v[184:187], v[226:229], v[4:7]
	v_mfma_f32_16x16x32_bf16 v[60:63], v[164:167], v[222:225], v[60:63]
	v_mfma_f32_16x16x32_bf16 v[52:55], v[164:167], v[230:233], v[52:55]
	v_mfma_f32_16x16x32_bf16 v[44:47], v[172:175], v[222:225], v[44:47]
	v_mfma_f32_16x16x32_bf16 v[36:39], v[172:175], v[230:233], v[36:39]
	v_mfma_f32_16x16x32_bf16 v[28:31], v[180:183], v[222:225], v[28:31]
	v_mfma_f32_16x16x32_bf16 v[20:23], v[180:183], v[230:233], v[20:23]
	v_mfma_f32_16x16x32_bf16 v[12:15], v[188:191], v[222:225], v[12:15]
	v_mfma_f32_16x16x32_bf16 v[4:7], v[188:191], v[230:233], v[4:7]
	s_waitcnt vmcnt(10) lgkmcnt(0)
	s_barrier
	v_mfma_f32_16x16x32_bf16 v[120:123], v[128:131], v[194:197], v[120:123]
	v_mfma_f32_16x16x32_bf16 v[112:115], v[128:131], v[202:205], v[112:115]
	ds_read_b128 v[218:221], v235 offset:16384
	v_mfma_f32_16x16x32_bf16 v[104:107], v[136:139], v[194:197], v[104:107]
	ds_read_b128 v[222:225], v235 offset:17408
	v_mfma_f32_16x16x32_bf16 v[96:99], v[136:139], v[202:205], v[96:99]
	ds_read_b128 v[226:229], v235 offset:18432
	v_mfma_f32_16x16x32_bf16 v[88:91], v[144:147], v[194:197], v[88:91]
	ds_read_b128 v[230:233], v235 offset:19456
	v_mfma_f32_16x16x32_bf16 v[80:83], v[144:147], v[202:205], v[80:83]
	v_mfma_f32_16x16x32_bf16 v[72:75], v[152:155], v[194:197], v[72:75]
	v_mfma_f32_16x16x32_bf16 v[64:67], v[152:155], v[202:205], v[64:67]
	v_mfma_f32_16x16x32_bf16 v[120:123], v[132:135], v[198:201], v[120:123]
	v_mfma_f32_16x16x32_bf16 v[112:115], v[132:135], v[206:209], v[112:115]
	v_mfma_f32_16x16x32_bf16 v[104:107], v[140:143], v[198:201], v[104:107]
	v_mfma_f32_16x16x32_bf16 v[96:99], v[140:143], v[206:209], v[96:99]
	v_mfma_f32_16x16x32_bf16 v[88:91], v[148:151], v[198:201], v[88:91]
	v_mfma_f32_16x16x32_bf16 v[80:83], v[148:151], v[206:209], v[80:83]
	v_mfma_f32_16x16x32_bf16 v[72:75], v[156:159], v[198:201], v[72:75]
	v_mfma_f32_16x16x32_bf16 v[64:67], v[156:159], v[206:209], v[64:67]
	s_waitcnt vmcnt(8) lgkmcnt(0)
	s_barrier
	v_mfma_f32_16x16x32_bf16 v[124:127], v[128:131], v[218:221], v[124:127]
	v_mfma_f32_16x16x32_bf16 v[116:119], v[128:131], v[226:229], v[116:119]
	ds_read_b128 v[160:163], v234 offset:16384
	v_mfma_f32_16x16x32_bf16 v[108:111], v[136:139], v[218:221], v[108:111]
	ds_read_b128 v[164:167], v234 offset:17408
	v_mfma_f32_16x16x32_bf16 v[100:103], v[136:139], v[226:229], v[100:103]
	ds_read_b128 v[168:171], v234 offset:18432
	v_mfma_f32_16x16x32_bf16 v[92:95], v[144:147], v[218:221], v[92:95]
	ds_read_b128 v[172:175], v234 offset:19456
	v_mfma_f32_16x16x32_bf16 v[84:87], v[144:147], v[226:229], v[84:87]
	ds_read_b128 v[176:179], v234 offset:20480
	v_mfma_f32_16x16x32_bf16 v[76:79], v[152:155], v[218:221], v[76:79]
	ds_read_b128 v[180:183], v234 offset:21504
	v_mfma_f32_16x16x32_bf16 v[68:71], v[152:155], v[226:229], v[68:71]
	ds_read_b128 v[184:187], v234 offset:22528
	v_mfma_f32_16x16x32_bf16 v[124:127], v[132:135], v[222:225], v[124:127]
	ds_read_b128 v[188:191], v234 offset:23552
	v_mfma_f32_16x16x32_bf16 v[116:119], v[132:135], v[230:233], v[116:119]
	v_mfma_f32_16x16x32_bf16 v[108:111], v[140:143], v[222:225], v[108:111]
	v_mfma_f32_16x16x32_bf16 v[100:103], v[140:143], v[230:233], v[100:103]
	v_mfma_f32_16x16x32_bf16 v[92:95], v[148:151], v[222:225], v[92:95]
	v_mfma_f32_16x16x32_bf16 v[84:87], v[148:151], v[230:233], v[84:87]
	v_mfma_f32_16x16x32_bf16 v[76:79], v[156:159], v[222:225], v[76:79]
	v_mfma_f32_16x16x32_bf16 v[68:71], v[156:159], v[230:233], v[68:71]
	s_waitcnt vmcnt(6) lgkmcnt(0)
	s_barrier
; #define STAGE(P, BASE, br, kt) do { const u16* _gb = (BASE) + ((size_t)(br) * K + (size_t)(kt) * BK); \
;     __builtin_amdgcn_global_load_lds((const unsigned*)(_gb + goff0), (unsigned*)((char*)(P) + tid * 16), 16, 0, 0); \
;     __builtin_amdgcn_global_load_lds((const unsigned*)(_gb + (size_t)64 * K + goff0), (unsigned*)((char*)(P) + tid * 16 + 8192), 16, 0, 0); } while (0)
; #define LDA(dst, b, h) _Pragma("unroll") for (int m = 0; m < 4; ++m) _Pragma("unroll") for (int k = 0; k < 2; ++k) \
;     dst[m][k] = *reinterpret_cast<const bf16x8*>((char*)SA(b, h) + lds_byte(wr * 64 + m * 16 + fr, k * 32 + fq * 8))
; #define LDB(dst, b, h) _Pragma("unroll") for (int n = 0; n < 2; ++n) _Pragma("unroll") for (int k = 0; k < 2; ++k) \
;     dst[n][k] = *reinterpret_cast<const bf16x8*>((char*)SB(b, h) + lds_byte(wc * 32 + n * 16 + fr, k * 32 + fq * 8))
; #define MMA(ai, bj, At, Bt_) do { __builtin_amdgcn_s_setprio(1); \
;     _Pragma("unroll") for (int m = 0; m < 4; ++m) _Pragma("unroll") for (int n = 0; n < 2; ++n) _Pragma("unroll") for (int k = 0; k < 2; ++k) \
;       acc[ai][bj][m][n] = __builtin_amdgcn_mfma_f32_16x16x32_bf16(Bt_[n][k], At[m][k], acc[ai][bj][m][n], 0, 0, 0); \
;     __builtin_amdgcn_s_setprio(0); } while (0)
; #define WAIT_V(n) asm volatile("s_waitcnt vmcnt(" #n ")" ::: "memory")
; #define WAIT_L(n) asm volatile("s_waitcnt lgkmcnt(" #n ")" ::: "memory")
; #define BAR __builtin_amdgcn_s_barrier()
; __device__ __forceinline__ void gemm_phase(KP p, char* shmc, const u16* __restrict__ A,
;                                            const u16* __restrict__ Bt, const int N, const int K, const int mode,
;                                            const float* __restrict__ xin, const float resw) {
;     ...
;     { LDB(B0, 0, 0); LDA(At, 0, 0); STAGE(SA(1, 1), A, brow + HALF, nt - 1);
;       BAR; WAIT_L(0); MMA(0, 0, At, B0); BAR;
;       LDB(B1, 0, 1); BAR; WAIT_L(0); MMA(0, 1, At, B1); BAR;
;       LDA(At, 0, 1); WAIT_V(4); BAR; WAIT_L(0); MMA(1, 0, At, B0); MMA(1, 1, At, B1); BAR; }
;     { LDB(B0, 1, 0); LDA(At, 1, 0); WAIT_V(2); BAR; WAIT_L(0); MMA(0, 0, At, B0); BAR;
;       LDB(B1, 1, 1); WAIT_V(0); BAR; WAIT_L(0); MMA(0, 1, At, B1); BAR;
;       LDA(At, 1, 1); BAR; WAIT_L(0); MMA(1, 0, At, B0); MMA(1, 1, At, B1); BAR; }
	v_mfma_f32_16x16x32_bf16 v[56:59], v[160:163], v[194:197], v[56:59]
	v_mfma_f32_16x16x32_bf16 v[48:51], v[160:163], v[202:205], v[48:51]
	ds_read_b128 v[128:131], v234 offset:32768
	v_mfma_f32_16x16x32_bf16 v[40:43], v[168:171], v[194:197], v[40:43]
	ds_read_b128 v[132:135], v234 offset:33792
	v_mfma_f32_16x16x32_bf16 v[32:35], v[168:171], v[202:205], v[32:35]
	ds_read_b128 v[136:139], v234 offset:34816
	v_mfma_f32_16x16x32_bf16 v[24:27], v[176:179], v[194:197], v[24:27]
	ds_read_b128 v[140:143], v234 offset:35840
	v_mfma_f32_16x16x32_bf16 v[16:19], v[176:179], v[202:205], v[16:19]
	ds_read_b128 v[144:147], v234 offset:36864
	v_mfma_f32_16x16x32_bf16 v[8:11], v[184:187], v[194:197], v[8:11]
	ds_read_b128 v[148:151], v234 offset:37888
	v_mfma_f32_16x16x32_bf16 v[0:3], v[184:187], v[202:205], v[0:3]
	ds_read_b128 v[152:155], v234 offset:38912
	v_mfma_f32_16x16x32_bf16 v[56:59], v[164:167], v[198:201], v[56:59]
	ds_read_b128 v[156:159], v234 offset:39936
	v_mfma_f32_16x16x32_bf16 v[48:51], v[164:167], v[206:209], v[48:51]
	v_mfma_f32_16x16x32_bf16 v[40:43], v[172:175], v[198:201], v[40:43]
	v_mfma_f32_16x16x32_bf16 v[32:35], v[172:175], v[206:209], v[32:35]
	v_mfma_f32_16x16x32_bf16 v[24:27], v[180:183], v[198:201], v[24:27]
	v_mfma_f32_16x16x32_bf16 v[16:19], v[180:183], v[206:209], v[16:19]
	v_mfma_f32_16x16x32_bf16 v[8:11], v[188:191], v[198:201], v[8:11]
	v_mfma_f32_16x16x32_bf16 v[0:3], v[188:191], v[206:209], v[0:3]
	s_waitcnt vmcnt(4) lgkmcnt(0)
	s_barrier
	v_mfma_f32_16x16x32_bf16 v[60:63], v[160:163], v[218:221], v[60:63]
	v_mfma_f32_16x16x32_bf16 v[52:55], v[160:163], v[226:229], v[52:55]
	ds_read_b128 v[194:197], v235 offset:32768
	v_mfma_f32_16x16x32_bf16 v[44:47], v[168:171], v[218:221], v[44:47]
	ds_read_b128 v[198:201], v235 offset:33792
	v_mfma_f32_16x16x32_bf16 v[36:39], v[168:171], v[226:229], v[36:39]
	ds_read_b128 v[202:205], v235 offset:34816
	v_mfma_f32_16x16x32_bf16 v[28:31], v[176:179], v[218:221], v[28:31]
	ds_read_b128 v[206:209], v235 offset:35840
	v_mfma_f32_16x16x32_bf16 v[20:23], v[176:179], v[226:229], v[20:23]
	v_mfma_f32_16x16x32_bf16 v[12:15], v[184:187], v[218:221], v[12:15]
	v_mfma_f32_16x16x32_bf16 v[4:7], v[184:187], v[226:229], v[4:7]
	v_mfma_f32_16x16x32_bf16 v[60:63], v[164:167], v[222:225], v[60:63]
	v_mfma_f32_16x16x32_bf16 v[52:55], v[164:167], v[230:233], v[52:55]
	v_mfma_f32_16x16x32_bf16 v[44:47], v[172:175], v[222:225], v[44:47]
	v_mfma_f32_16x16x32_bf16 v[36:39], v[172:175], v[230:233], v[36:39]
	v_mfma_f32_16x16x32_bf16 v[28:31], v[180:183], v[222:225], v[28:31]
	v_mfma_f32_16x16x32_bf16 v[20:23], v[180:183], v[230:233], v[20:23]
	v_mfma_f32_16x16x32_bf16 v[12:15], v[188:191], v[222:225], v[12:15]
	v_mfma_f32_16x16x32_bf16 v[4:7], v[188:191], v[230:233], v[4:7]
	s_waitcnt vmcnt(2) lgkmcnt(0)
	s_barrier
	v_mfma_f32_16x16x32_bf16 v[120:123], v[128:131], v[194:197], v[120:123]
	v_mfma_f32_16x16x32_bf16 v[112:115], v[128:131], v[202:205], v[112:115]
	ds_read_b128 v[218:221], v235 offset:49152
	v_mfma_f32_16x16x32_bf16 v[104:107], v[136:139], v[194:197], v[104:107]
	ds_read_b128 v[222:225], v235 offset:50176
	v_mfma_f32_16x16x32_bf16 v[96:99], v[136:139], v[202:205], v[96:99]
	ds_read_b128 v[226:229], v235 offset:51200
	v_mfma_f32_16x16x32_bf16 v[88:91], v[144:147], v[194:197], v[88:91]
	ds_read_b128 v[230:233], v235 offset:52224
	v_mfma_f32_16x16x32_bf16 v[80:83], v[144:147], v[202:205], v[80:83]
	v_mfma_f32_16x16x32_bf16 v[72:75], v[152:155], v[194:197], v[72:75]
	v_mfma_f32_16x16x32_bf16 v[64:67], v[152:155], v[202:205], v[64:67]
	v_mfma_f32_16x16x32_bf16 v[120:123], v[132:135], v[198:201], v[120:123]
	v_mfma_f32_16x16x32_bf16 v[112:115], v[132:135], v[206:209], v[112:115]
	v_mfma_f32_16x16x32_bf16 v[104:107], v[140:143], v[198:201], v[104:107]
	v_mfma_f32_16x16x32_bf16 v[96:99], v[140:143], v[206:209], v[96:99]
	v_mfma_f32_16x16x32_bf16 v[88:91], v[148:151], v[198:201], v[88:91]
	v_mfma_f32_16x16x32_bf16 v[80:83], v[148:151], v[206:209], v[80:83]
	v_mfma_f32_16x16x32_bf16 v[72:75], v[156:159], v[198:201], v[72:75]
	v_mfma_f32_16x16x32_bf16 v[64:67], v[156:159], v[206:209], v[64:67]
	s_waitcnt vmcnt(0) lgkmcnt(0)
	s_barrier
	v_mfma_f32_16x16x32_bf16 v[124:127], v[128:131], v[218:221], v[124:127]
	v_mfma_f32_16x16x32_bf16 v[116:119], v[128:131], v[226:229], v[116:119]
	ds_read_b128 v[160:163], v234 offset:49152
	v_mfma_f32_16x16x32_bf16 v[108:111], v[136:139], v[218:221], v[108:111]
	ds_read_b128 v[164:167], v234 offset:50176
	v_mfma_f32_16x16x32_bf16 v[100:103], v[136:139], v[226:229], v[100:103]
	ds_read_b128 v[168:171], v234 offset:51200
	v_mfma_f32_16x16x32_bf16 v[92:95], v[144:147], v[218:221], v[92:95]
	ds_read_b128 v[172:175], v234 offset:52224
	v_mfma_f32_16x16x32_bf16 v[84:87], v[144:147], v[226:229], v[84:87]
	ds_read_b128 v[176:179], v234 offset:53248
	v_mfma_f32_16x16x32_bf16 v[76:79], v[152:155], v[218:221], v[76:79]
	ds_read_b128 v[180:183], v234 offset:54272
	v_mfma_f32_16x16x32_bf16 v[68:71], v[152:155], v[226:229], v[68:71]
	ds_read_b128 v[184:187], v234 offset:55296
	v_mfma_f32_16x16x32_bf16 v[124:127], v[132:135], v[222:225], v[124:127]
	ds_read_b128 v[188:191], v234 offset:56320
	v_mfma_f32_16x16x32_bf16 v[116:119], v[132:135], v[230:233], v[116:119]
	v_mfma_f32_16x16x32_bf16 v[108:111], v[140:143], v[222:225], v[108:111]
	v_mfma_f32_16x16x32_bf16 v[100:103], v[140:143], v[230:233], v[100:103]
	v_mfma_f32_16x16x32_bf16 v[92:95], v[148:151], v[222:225], v[92:95]
	v_mfma_f32_16x16x32_bf16 v[84:87], v[148:151], v[230:233], v[84:87]
	v_mfma_f32_16x16x32_bf16 v[76:79], v[156:159], v[222:225], v[76:79]
	v_mfma_f32_16x16x32_bf16 v[68:71], v[156:159], v[230:233], v[68:71]
	s_waitcnt lgkmcnt(0)
	s_barrier
; #define LDA(dst, b, h) _Pragma("unroll") for (int m = 0; m < 4; ++m) _Pragma("unroll") for (int k = 0; k < 2; ++k) \
;     dst[m][k] = *reinterpret_cast<const bf16x8*>((char*)SA(b, h) + lds_byte(wr * 64 + m * 16 + fr, k * 32 + fq * 8))
; #define MMA(ai, bj, At, Bt_) do { __builtin_amdgcn_s_setprio(1); \
;     _Pragma("unroll") for (int m = 0; m < 4; ++m) _Pragma("unroll") for (int n = 0; n < 2; ++n) _Pragma("unroll") for (int k = 0; k < 2; ++k) \
;       acc[ai][bj][m][n] = __builtin_amdgcn_mfma_f32_16x16x32_bf16(Bt_[n][k], At[m][k], acc[ai][bj][m][n], 0, 0, 0); \
;     __builtin_amdgcn_s_setprio(0); } while (0)
; #define WAIT_L(n) asm volatile("s_waitcnt lgkmcnt(" #n ")" ::: "memory")
; #define BAR __builtin_amdgcn_s_barrier()
; #define TILE_PREFETCH(brow_, bcol_, par_) do { \
;     STAGE(SB(0, 0), Bt, bcol_, 0); STAGE(SA(0, 0), A, brow_, 0); \
;     STAGE(SB(0, 1), Bt, (bcol_) + HALF, 0); STAGE(SA(0, 1), A, (brow_) + HALF, 0); \
;     STAGE(SB(1, 0), Bt, bcol_, 1); STAGE(SA(1, 0), A, brow_, 1); STAGE(SB(1, 1), Bt, (bcol_) + HALF, 1); } while (0)
; __device__ __forceinline__ void gemm_phase(KP p, char* shmc, const u16* __restrict__ A,
;                                            const u16* __restrict__ Bt, const int N, const int K, const int mode,
;                                            const float* __restrict__ xin, const float resw) {
;     ...
;       LDA(At, 1, 1); BAR; WAIT_L(0); MMA(1, 0, At, B0); MMA(1, 1, At, B1); BAR; }
;     if (wr == 0) BAR;
;     const int ntix = tix + gridDim.x;
;     int nbrow = 0, nbcol = 0, npn = 0;
;     if (ntix < nwg) {
;       TILE_MAP(ntix, nbrow, nbcol, npn);
;       TILE_PREFETCH(nbrow, nbcol, par ^ 1);
;     }
	v_mfma_f32_16x16x32_bf16 v[56:59], v[160:163], v[194:197], v[56:59]
	v_mfma_f32_16x16x32_bf16 v[48:51], v[160:163], v[202:205], v[48:51]
	v_mfma_f32_16x16x32_bf16 v[40:43], v[168:171], v[194:197], v[40:43]
	v_mfma_f32_16x16x32_bf16 v[32:35], v[168:171], v[202:205], v[32:35]
	v_mfma_f32_16x16x32_bf16 v[24:27], v[176:179], v[194:197], v[24:27]
	v_mfma_f32_16x16x32_bf16 v[16:19], v[176:179], v[202:205], v[16:19]
	v_mfma_f32_16x16x32_bf16 v[8:11], v[184:187], v[194:197], v[8:11]
	v_mfma_f32_16x16x32_bf16 v[0:3], v[184:187], v[202:205], v[0:3]
	v_mfma_f32_16x16x32_bf16 v[56:59], v[164:167], v[198:201], v[56:59]
	v_mfma_f32_16x16x32_bf16 v[48:51], v[164:167], v[206:209], v[48:51]
	v_mfma_f32_16x16x32_bf16 v[40:43], v[172:175], v[198:201], v[40:43]
	v_mfma_f32_16x16x32_bf16 v[32:35], v[172:175], v[206:209], v[32:35]
	v_mfma_f32_16x16x32_bf16 v[24:27], v[180:183], v[198:201], v[24:27]
	v_mfma_f32_16x16x32_bf16 v[16:19], v[180:183], v[206:209], v[16:19]
	v_mfma_f32_16x16x32_bf16 v[8:11], v[188:191], v[198:201], v[8:11]
	v_mfma_f32_16x16x32_bf16 v[0:3], v[188:191], v[206:209], v[0:3]
	v_mfma_f32_16x16x32_bf16 v[60:63], v[160:163], v[218:221], v[60:63]
	v_mfma_f32_16x16x32_bf16 v[52:55], v[160:163], v[226:229], v[52:55]
	v_mfma_f32_16x16x32_bf16 v[44:47], v[168:171], v[218:221], v[44:47]
	v_mfma_f32_16x16x32_bf16 v[36:39], v[168:171], v[226:229], v[36:39]
	v_mfma_f32_16x16x32_bf16 v[28:31], v[176:179], v[218:221], v[28:31]
	v_mfma_f32_16x16x32_bf16 v[20:23], v[176:179], v[226:229], v[20:23]
	v_mfma_f32_16x16x32_bf16 v[12:15], v[184:187], v[218:221], v[12:15]
	v_mfma_f32_16x16x32_bf16 v[4:7], v[184:187], v[226:229], v[4:7]
	v_mfma_f32_16x16x32_bf16 v[60:63], v[164:167], v[222:225], v[60:63]
	v_mfma_f32_16x16x32_bf16 v[52:55], v[164:167], v[230:233], v[52:55]
	v_mfma_f32_16x16x32_bf16 v[44:47], v[172:175], v[222:225], v[44:47]
	v_mfma_f32_16x16x32_bf16 v[36:39], v[172:175], v[230:233], v[36:39]
	v_mfma_f32_16x16x32_bf16 v[28:31], v[180:183], v[222:225], v[28:31]
	v_mfma_f32_16x16x32_bf16 v[20:23], v[180:183], v[230:233], v[20:23]
	v_mfma_f32_16x16x32_bf16 v[12:15], v[188:191], v[222:225], v[12:15]
	v_mfma_f32_16x16x32_bf16 v[4:7], v[188:191], v[230:233], v[4:7]
.Lmy_join:
	s_nop 7
	s_nop 7
	s_add_i32 s66, s66, s3
	s_cmp_ge_i32 s66, s51
	s_cselect_b64 s[6:7], -1, 0
	s_mov_b32 s26, 0
	s_and_b64 vcc, exec, s[6:7]
	s_mov_b32 s45, 0
	s_mov_b32 s44, 0
	s_cbranch_vccnz .LBB0_55
	s_ashr_i32 s8, s66, 31
	s_lshr_b32 s8, s8, 29
	s_add_i32 s8, s66, s8
	s_ashr_i32 s9, s8, 3
	s_and_b32 s8, s8, -8
	s_sub_i32 s8, s66, s8
	s_lshr_b32 s26, s8, 31
	s_or_b32 s26, s26, s68
	s_mul_i32 s8, s26, s8
	s_add_i32 s8, s8, s9
	s_abs_i32 s26, s8
	s_mul_hi_u32 s27, s26, s69
	s_mul_i32 s36, s27, s81
	s_sub_i32 s26, s26, s36
	s_ashr_i32 s9, s8, 31
	s_add_i32 s36, s27, 1
	s_sub_i32 s37, s26, s81
	s_cmp_ge_u32 s26, s81
	s_cselect_b32 s27, s36, s27
	s_cselect_b32 s26, s37, s26
	s_add_i32 s36, s27, 1
	s_cmp_ge_u32 s26, s81
	s_cselect_b32 s26, s36, s27
	s_xor_b32 s26, s26, s9
	s_sub_i32 s9, s26, s9
	s_lshl_b32 s26, s9, 2
	s_sub_i32 s27, 64, s26
	s_min_i32 s27, s27, 4
	s_abs_i32 s36, s27
	v_cvt_f32_u32_e32 v130, s36
	s_sub_i32 s38, 0, s36
	s_mul_i32 s9, s9, s81
	s_sub_i32 s8, s8, s9
	v_rcp_iflag_f32_e32 v130, v130
	s_abs_i32 s37, s8
	s_xor_b32 s9, s8, s27
	s_ashr_i32 s9, s9, 31
	v_mul_f32_e32 v130, 0x4f7ffffe, v130
	v_cvt_u32_f32_e32 v130, v130
	s_nop 0
	v_readfirstlane_b32 s39, v130
	s_mul_i32 s38, s38, s39
	s_mul_hi_u32 s38, s39, s38
	s_add_i32 s39, s39, s38
	s_mul_hi_u32 s38, s37, s39
	s_mul_i32 s39, s38, s36
	s_sub_i32 s37, s37, s39
	s_add_i32 s39, s38, 1
	s_sub_i32 s40, s37, s36
	s_cmp_ge_u32 s37, s36
	s_cselect_b32 s38, s39, s38
	s_cselect_b32 s37, s40, s37
	s_add_i32 s39, s38, 1
	s_cmp_ge_u32 s37, s36
	s_cselect_b32 s36, s39, s38
	s_xor_b32 s36, s36, s9
	s_sub_i32 s44, s36, s9
	s_mul_i32 s9, s44, s27
	s_sub_i32 s8, s8, s9
	s_add_i32 s8, s8, s26
	s_lshl_b32 s45, s44, 8
	s_lshl_b32 s26, s8, 8
	s_mul_hi_i32 s9, s45, s50
	s_mul_i32 s8, s45, s50
	s_lshl_b64 s[8:9], s[8:9], 1
	s_add_u32 s8, s14, s8
	s_addc_u32 s9, s15, s9
	s_lshl_b32 s27, s72, 1
	s_mul_hi_i32 s41, s26, s50
	s_mul_i32 s40, s26, s50
	s_lshl_b64 s[40:41], s[40:41], 1
	s_add_u32 s40, s12, s40
	s_addc_u32 s41, s13, s41
	s_add_u32 s42, s8, s27
	s_addc_u32 s43, s9, 0
	s_add_u32 s46, s40, s27
	s_addc_u32 s47, s41, 0
	v_readfirstlane_b32 s27, v238
	s_nop 1
	s_add_u32 m0, s27, 0x10000
	s_nop 0
	global_load_lds_dwordx4 v236, s[8:9]
	s_add_u32 m0, s27, 0x12000
	s_nop 0
	global_load_lds_dwordx4 v237, s[8:9]
	s_add_u32 m0, s27, 0x0
	s_nop 0
	global_load_lds_dwordx4 v236, s[40:41]
	s_add_u32 m0, s27, 0x2000
	s_nop 0
	global_load_lds_dwordx4 v237, s[40:41]
	s_add_u32 m0, s27, 0x14000
	s_nop 0
	global_load_lds_dwordx4 v236, s[42:43]
	s_add_u32 m0, s27, 0x16000
	s_nop 0
	global_load_lds_dwordx4 v237, s[42:43]
	s_add_u32 m0, s27, 0x4000
	s_nop 0
	global_load_lds_dwordx4 v236, s[46:47]
	s_add_u32 m0, s27, 0x6000
	s_nop 0
	global_load_lds_dwordx4 v237, s[46:47]
	s_add_u32 s8, s8, 0x80
	s_addc_u32 s9, s9, 0
	s_add_u32 s40, s40, 0x80
	s_addc_u32 s41, s41, 0
	s_add_u32 s42, s42, 0x80
	s_addc_u32 s43, s43, 0
	s_add_u32 s46, s46, 0x80
	s_addc_u32 s47, s47, 0
	s_add_u32 m0, s27, 0x18000
	s_nop 0
	global_load_lds_dwordx4 v236, s[8:9]
	s_add_u32 m0, s27, 0x1a000
	s_nop 0
	global_load_lds_dwordx4 v237, s[8:9]
	s_add_u32 m0, s27, 0x8000
	s_nop 0
	global_load_lds_dwordx4 v236, s[40:41]
	s_add_u32 m0, s27, 0xa000
	s_nop 0
	global_load_lds_dwordx4 v237, s[40:41]
	s_add_u32 m0, s27, 0x1c000
	s_nop 0
	global_load_lds_dwordx4 v236, s[42:43]
	s_add_u32 m0, s27, 0x1e000
	s_nop 0
	global_load_lds_dwordx4 v237, s[42:43]
	s_add_u32 m0, s27, 0xc000
	s_nop 0
	global_load_lds_dwordx4 v236, s[46:47]
	s_add_u32 m0, s27, 0xe000
	s_nop 0
	global_load_lds_dwordx4 v237, s[46:47]

; __device__ __forceinline__ void epilogue(KP p, f32x4 (&acc)[2][2][4][2], const float* s_inv, const int mode,
;                                          const float* __restrict__ xin, const float resw, const int brow, const int bcol,
;                                          const int pn) {
;     ...
;   } else {
; #pragma unroll
;     for (int ai = 0; ai < 2; ++ai)
; #pragma unroll
;       for (int m = 0; m < 4; ++m) {
;         const int rl = ai * HALF + wr * 64 + m * 16 + fr;
;         const int row = brow + rl;
;         const float sc = rsqrtf((s_inv[rl] + s_inv[256 + rl]) * (1.f / D_) + EPS_);
; #pragma unroll
;         for (int bj = 0; bj < 2; ++bj) {
;           const int col = bcol + bj * HALF + wc * 32 + fq * 8;
;           float v[8];
; #pragma unroll
;           for (int n = 0; n < 2; ++n)
; #pragma unroll
;             for (int r = 0; r < 4; ++r) v[n * 4 + r] = acc[ai][bj][m][n][r] * sc;
;           if (pn >= 8 && pn < 12) {
;             u16* d = p->vT + (size_t)(col - 2048) * S_ + row;
; #pragma unroll
;             for (int e = 0; e < 8; ++e) d[(size_t)e * S_] = f2bf(v[e]);
;           } else {
;             u16* d;
;             if (pn < 4) {
;               const float qs = 0.08838834764831845f;
; #pragma unroll
;               for (int e = 0; e < 8; ++e) v[e] *= qs;
;               d = p->q + (size_t)row * 1024 + col;
;             } else if (pn < 8) {
;               d = p->k + (size_t)row * 1024 + (col - 1024);
;             } else {
;               if (pn < 16) {
; #pragma unroll
;                 for (int e = 0; e < 8; ++e) v[e] = gelu_tanh(v[e]);
;               }
;               d = p->uvp + (size_t)row * 1536 + (col - 3072);
.LBB0_57:
	s_lshl_b32 s6, s90, 11
	v_mov_b32_e32 v238, v210
	s_add_i32 s27, s6, 0
	s_add_i32 s27, s27, 0x20000
	v_ashrrev_i32_e32 v128, 2, v238
	v_bfe_u32 v235, v238, 6, 2
	v_and_b32_e32 v236, 15, v238
	v_bfe_u32 v234, v238, 4, 2
	v_and_b32_e32 v237, 0xffffffc0, v128
	s_cmp_lt_i32 s49, 1
	s_mov_b64 s[6:7], -1
	s_cbranch_scc1 .LBB0_287
	s_cmp_lg_u32 s49, 1
	s_cbranch_scc0 .LBB0_284
	s_sub_i32 s6, s73, 8
	s_cmp_lt_u32 s6, 4
	s_cbranch_scc1 .Lmy_vepi
	v_or_b32_e32 v128, v237, v236
	v_lshl_add_u32 v160, v128, 2, s27
	ds_read2st64_b32 v[132:133], v160 offset1:4
	v_lshlrev_b32_e32 v129, 5, v235
	v_lshlrev_b32_e32 v130, 3, v234
	v_add3_u32 v130, v129, s28, v130
	s_and_b32 s6, s73, -4
	s_waitcnt lgkmcnt(0)
	v_add_f32_e32 v129, v132, v133
	v_fmamk_f32 v129, v129, 0x3a000000, v211
	v_mul_f32_e32 v131, 0x4b800000, v129
	v_cmp_gt_f32_e32 vcc, s77, v129
	s_cmp_lg_u32 s6, 8
	s_cselect_b64 s[6:7], -1, 0
	v_cndmask_b32_e32 v129, v129, v131, vcc
	v_rsq_f32_e32 v129, v129
	s_cmp_gt_i32 s73, 3
	s_cselect_b64 s[40:41], -1, 0
	s_cmp_gt_u32 s73, 7
	v_add_u32_e32 v132, s24, v128
	v_mul_f32_e32 v131, 0x45800000, v129
	s_cselect_b64 s[38:39], -1, 0
	s_cmp_lt_u32 s73, 16
	v_cndmask_b32_e32 v138, v129, v131, vcc
	v_ashrrev_i32_e32 v133, 31, v132
	v_mad_i64_i32 v[136:137], s[8:9], v132, s87, 0
	s_cselect_b64 s[36:37], -1, 0
	v_lshlrev_b64 v[134:135], 11, v[132:133]
	v_pk_mul_f32 v[146:147], v[120:121], v[138:139] op_sel_hi:[1,0]
	v_pk_mul_f32 v[144:145], v[122:123], v[138:139] op_sel_hi:[1,0]
	v_pk_mul_f32 v[142:143], v[112:113], v[138:139] op_sel_hi:[1,0]
	v_pk_mul_f32 v[140:141], v[114:115], v[138:139] op_sel_hi:[1,0]
	s_mov_b64 s[8:9], -1
	s_and_b64 vcc, exec, s[6:7]
	s_cbranch_vccz .LBB0_71
	s_and_b64 vcc, exec, s[40:41]
	s_cbranch_vccz .LBB0_68
	s_and_b64 vcc, exec, s[38:39]
	s_cbranch_vccz .LBB0_65
	s_andn2_b64 vcc, exec, s[36:37]
	v_mov_b64_e32 v[156:157], v[140:141]
	v_mov_b64_e32 v[152:153], v[142:143]
	v_mov_b64_e32 v[150:151], v[144:145]
	v_mov_b64_e32 v[148:149], v[146:147]
	s_cbranch_vccnz .LBB0_64
	v_mul_f32_e32 v129, 0x3d372713, v146
	v_mul_f32_e32 v129, v146, v129
	v_mul_f32_e32 v131, 0x3d372713, v147
	v_fma_f32 v129, v146, v129, v146
	v_mul_f32_e32 v131, v147, v131
	v_mul_f32_e32 v129, 0x3f4c422a, v129
	v_fma_f32 v131, v147, v131, v147
	v_add_f32_e32 v129, v129, v129
	v_mul_f32_e32 v131, 0x3f4c422a, v131
	v_mul_f32_e32 v129, 0x3fb8aa3b, v129
	v_add_f32_e32 v131, v131, v131
	v_exp_f32_e32 v129, v129
	v_mul_f32_e32 v131, 0x3fb8aa3b, v131
	v_exp_f32_e32 v131, v131
	v_pk_mul_f32 v[150:151], v[146:147], 0.5 op_sel_hi:[1,0]
	v_add_f32_e32 v129, 1.0, v129
	v_rcp_f32_e32 v148, v129
	v_add_f32_e32 v129, 1.0, v131
	v_rcp_f32_e32 v149, v129
	v_mul_f32_e32 v129, 0x3d372713, v144
	v_mul_f32_e32 v129, v144, v129
	v_mul_f32_e32 v131, 0x3d372713, v145
	v_fma_f32 v129, v144, v129, v144
	v_mul_f32_e32 v131, v145, v131
	v_mul_f32_e32 v129, 0x3f4c422a, v129
	v_fma_f32 v131, v145, v131, v145
	v_add_f32_e32 v129, v129, v129
	v_mul_f32_e32 v131, 0x3f4c422a, v131
	v_mul_f32_e32 v129, 0x3fb8aa3b, v129
	v_add_f32_e32 v131, v131, v131
	v_exp_f32_e32 v129, v129
	v_mul_f32_e32 v131, 0x3fb8aa3b, v131
	v_exp_f32_e32 v131, v131
	v_pk_fma_f32 v[148:149], v[148:149], 2.0, 1.0 op_sel_hi:[1,0,0] neg_lo:[1,0,0] neg_hi:[1,0,0]
	v_add_f32_e32 v129, 1.0, v129
	v_rcp_f32_e32 v152, v129
	v_add_f32_e32 v129, 1.0, v131
	v_rcp_f32_e32 v153, v129
	v_mul_f32_e32 v129, 0x3d372713, v142
	v_mul_f32_e32 v129, v142, v129
	v_mul_f32_e32 v131, 0x3d372713, v143
	v_fma_f32 v129, v142, v129, v142
	v_mul_f32_e32 v131, v143, v131
	v_mul_f32_e32 v129, 0x3f4c422a, v129
	v_fma_f32 v131, v143, v131, v143
	v_add_f32_e32 v129, v129, v129
	v_mul_f32_e32 v131, 0x3f4c422a, v131
	v_mul_f32_e32 v129, 0x3fb8aa3b, v129
	v_add_f32_e32 v131, v131, v131
	v_exp_f32_e32 v129, v129
	v_mul_f32_e32 v131, 0x3fb8aa3b, v131
	v_exp_f32_e32 v131, v131
	v_pk_add_f32 v[148:149], v[148:149], 1.0 op_sel_hi:[1,0]
	v_pk_fma_f32 v[152:153], v[152:153], 2.0, 1.0 op_sel_hi:[1,0,0] neg_lo:[1,0,0] neg_hi:[1,0,0]
	v_pk_mul_f32 v[148:149], v[150:151], v[148:149]
	v_pk_mul_f32 v[150:151], v[144:145], 0.5 op_sel_hi:[1,0]
	v_pk_add_f32 v[152:153], v[152:153], 1.0 op_sel_hi:[1,0]
	v_add_f32_e32 v129, 1.0, v129
	v_pk_mul_f32 v[150:151], v[150:151], v[152:153]
	v_rcp_f32_e32 v152, v129
	v_add_f32_e32 v129, 1.0, v131
	v_rcp_f32_e32 v153, v129
	v_mul_f32_e32 v129, 0x3d372713, v140
	v_mul_f32_e32 v129, v140, v129
	v_mul_f32_e32 v131, 0x3d372713, v141
	v_fma_f32 v129, v140, v129, v140
	v_mul_f32_e32 v131, v141, v131
	v_mul_f32_e32 v129, 0x3f4c422a, v129
	v_fma_f32 v131, v141, v131, v141
	v_add_f32_e32 v129, v129, v129
	v_mul_f32_e32 v131, 0x3f4c422a, v131
	v_mul_f32_e32 v129, 0x3fb8aa3b, v129
	v_add_f32_e32 v131, v131, v131
	v_exp_f32_e32 v129, v129
	v_mul_f32_e32 v131, 0x3fb8aa3b, v131
	v_exp_f32_e32 v131, v131
	v_pk_fma_f32 v[152:153], v[152:153], 2.0, 1.0 op_sel_hi:[1,0,0] neg_lo:[1,0,0] neg_hi:[1,0,0]
	v_add_f32_e32 v129, 1.0, v129
	v_rcp_f32_e32 v156, v129
	v_add_f32_e32 v129, 1.0, v131
	v_rcp_f32_e32 v157, v129
	v_pk_mul_f32 v[154:155], v[142:143], 0.5 op_sel_hi:[1,0]
	v_pk_add_f32 v[152:153], v[152:153], 1.0 op_sel_hi:[1,0]
	v_pk_fma_f32 v[156:157], v[156:157], 2.0, 1.0 op_sel_hi:[1,0,0] neg_lo:[1,0,0] neg_hi:[1,0,0]
	v_pk_mul_f32 v[152:153], v[154:155], v[152:153]
	v_pk_mul_f32 v[154:155], v[140:141], 0.5 op_sel_hi:[1,0]
	v_pk_add_f32 v[156:157], v[156:157], 1.0 op_sel_hi:[1,0]
	s_nop 0
	v_pk_mul_f32 v[156:157], v[154:155], v[156:157]

; __device__ __forceinline__ void epilogue(KP p, f32x4 (&acc)[2][2][4][2], const float* s_inv, const int mode,
;                                          const float* __restrict__ xin, const float resw, const int brow, const int bcol,
;                                          const int pn) {
;     ...
; #pragma unroll
;     for (int ai = 0; ai < 2; ++ai)
; #pragma unroll
;       for (int m = 0; m < 4; ++m) {
;         const int rl = ai * HALF + wr * 64 + m * 16 + fr;
;         const int row = brow + rl;
;         const float sc = rsqrtf((s_inv[rl] + s_inv[256 + rl]) * (1.f / D_) + EPS_);
; #pragma unroll
;         for (int bj = 0; bj < 2; ++bj) {
;           const int col = bcol + bj * HALF + wc * 32 + fq * 8;
;           float v[8];
; #pragma unroll
;           for (int n = 0; n < 2; ++n)
; #pragma unroll
;             for (int r = 0; r < 4; ++r) v[n * 4 + r] = acc[ai][bj][m][n][r] * sc;
;           if (pn >= 8 && pn < 12) {
;             u16* d = p->vT + (size_t)(col - 2048) * S_ + row;
; #pragma unroll
;             for (int e = 0; e < 8; ++e) d[(size_t)e * S_] = f2bf(v[e]);
.Lmy_vepi:
	s_load_dwordx2 s[6:7], s[0:1], 0xd0
	v_and_b32_e32 v128, 63, v210
	v_lshrrev_b32_e32 v129, 6, v210
	v_and_b32_e32 v130, 15, v128
	v_lshrrev_b32_e32 v131, 4, v128
	v_lshrrev_b32_e32 v132, 2, v129
	v_and_b32_e32 v133, 3, v129
	v_lshlrev_b32_e32 v134, 8, v132
	v_lshl_add_u32 v134, v131, 4, v134
	v_add_u32_e32 v134, s27, v134
	v_lshrrev_b32_e32 v135, 2, v130
	v_lshlrev_b32_e32 v135, 3, v135
	v_and_b32_e32 v136, 3, v130
	v_add_u32_e32 v135, v135, v136
	v_lshl_add_u32 v135, v133, 5, v135
	v_add_u32_e32 v135, s28, v135
	v_add_u32_e32 v135, 0xfffff800, v135
	v_lshlrev_b32_e32 v136, 6, v132
	v_lshl_add_u32 v136, v131, 2, v136
	v_add_u32_e32 v136, s24, v136
	v_lshlrev_b32_e32 v138, 15, v135
	v_lshl_add_u32 v138, v136, 1, v138
	v_mov_b32_e32 v139, 0
	s_waitcnt lgkmcnt(0)
	s_add_u32 s36, s6, 0x20000
	s_addc_u32 s37, s7, 0
	s_add_u32 s38, s6, 0x400000
	s_addc_u32 s39, s7, 0
	s_add_u32 s40, s6, 0x420000
	s_addc_u32 s41, s7, 0
	v_lshl_add_u64 v[140:141], s[6:7], 0, v[138:139]
	v_lshl_add_u64 v[142:143], s[36:37], 0, v[138:139]
	v_lshl_add_u64 v[164:165], s[38:39], 0, v[138:139]
	v_lshl_add_u64 v[166:167], s[40:41], 0, v[138:139]
	ds_read_b128 v[144:147], v134 offset:0
	ds_read_b128 v[148:151], v134 offset:1024
	s_waitcnt lgkmcnt(0)
	v_add_f32_e32 v152, v144, v148
	v_add_f32_e32 v153, v145, v149
	v_add_f32_e32 v154, v146, v150
	v_add_f32_e32 v155, v147, v151
	v_fmamk_f32 v152, v152, 0x3a000000, v211
	v_fmamk_f32 v153, v153, 0x3a000000, v211
	v_fmamk_f32 v154, v154, 0x3a000000, v211
	v_fmamk_f32 v155, v155, 0x3a000000, v211
	v_mul_f32_e32 v156, 0x4b800000, v152
	v_mul_f32_e32 v157, 0x4b800000, v153
	v_mul_f32_e32 v158, 0x4b800000, v154
	v_mul_f32_e32 v159, 0x4b800000, v155
	v_cmp_gt_f32_e64 s[8:9], s77, v152
	v_cmp_gt_f32_e64 s[42:43], s77, v153
	v_cmp_gt_f32_e64 s[46:47], s77, v154
	v_cmp_gt_f32_e32 vcc, s77, v155
	s_nop 1
	v_cndmask_b32_e64 v152, v152, v156, s[8:9]
	v_cndmask_b32_e64 v153, v153, v157, s[42:43]
	v_cndmask_b32_e64 v154, v154, v158, s[46:47]
	v_cndmask_b32_e32 v155, v155, v159, vcc
	v_rsq_f32_e32 v152, v152
	v_rsq_f32_e32 v153, v153
	v_rsq_f32_e32 v154, v154
	v_rsq_f32_e32 v155, v155
	v_mul_f32_e32 v156, 0x45800000, v152
	v_mul_f32_e32 v157, 0x45800000, v153
	v_mul_f32_e32 v158, 0x45800000, v154
	v_mul_f32_e32 v159, 0x45800000, v155
	v_cndmask_b32_e64 v152, v152, v156, s[8:9]
	v_cndmask_b32_e64 v153, v153, v157, s[42:43]
	v_cndmask_b32_e64 v154, v154, v158, s[46:47]
	v_cndmask_b32_e32 v155, v155, v159, vcc
	v_mul_f32_e32 v168, v120, v152
	v_mul_f32_e32 v169, v121, v153
	v_mul_f32_e32 v170, v122, v154
	v_mul_f32_e32 v171, v123, v155
	v_cvt_pk_bf16_f32 v172, v168, v169
	v_cvt_pk_bf16_f32 v173, v170, v171
	global_store_dwordx2 v[140:141], v[172:173], off
	v_mul_f32_e32 v174, v112, v152
	v_mul_f32_e32 v175, v113, v153
	v_mul_f32_e32 v176, v114, v154
	v_mul_f32_e32 v177, v115, v155
	v_cvt_pk_bf16_f32 v178, v174, v175
	v_cvt_pk_bf16_f32 v179, v176, v177
	global_store_dwordx2 v[142:143], v[178:179], off
	v_mul_f32_e32 v168, v124, v152
	v_mul_f32_e32 v169, v125, v153
	v_mul_f32_e32 v170, v126, v154
	v_mul_f32_e32 v171, v127, v155
	v_cvt_pk_bf16_f32 v172, v168, v169
	v_cvt_pk_bf16_f32 v173, v170, v171
	global_store_dwordx2 v[164:165], v[172:173], off
	v_mul_f32_e32 v174, v116, v152
	v_mul_f32_e32 v175, v117, v153
	v_mul_f32_e32 v176, v118, v154
	v_mul_f32_e32 v177, v119, v155
	v_cvt_pk_bf16_f32 v178, v174, v175
	v_cvt_pk_bf16_f32 v179, v176, v177
	global_store_dwordx2 v[166:167], v[178:179], off
	ds_read_b128 v[144:147], v134 offset:64
	ds_read_b128 v[148:151], v134 offset:1088
	s_waitcnt lgkmcnt(0)
	v_add_f32_e32 v152, v144, v148
	v_add_f32_e32 v153, v145, v149
	v_add_f32_e32 v154, v146, v150
	v_add_f32_e32 v155, v147, v151
	v_fmamk_f32 v152, v152, 0x3a000000, v211
	v_fmamk_f32 v153, v153, 0x3a000000, v211
	v_fmamk_f32 v154, v154, 0x3a000000, v211
	v_fmamk_f32 v155, v155, 0x3a000000, v211
	v_mul_f32_e32 v156, 0x4b800000, v152
	v_mul_f32_e32 v157, 0x4b800000, v153
	v_mul_f32_e32 v158, 0x4b800000, v154
	v_mul_f32_e32 v159, 0x4b800000, v155
	v_cmp_gt_f32_e64 s[8:9], s77, v152
	v_cmp_gt_f32_e64 s[42:43], s77, v153
	v_cmp_gt_f32_e64 s[46:47], s77, v154
	v_cmp_gt_f32_e32 vcc, s77, v155
	s_nop 1
	v_cndmask_b32_e64 v152, v152, v156, s[8:9]
	v_cndmask_b32_e64 v153, v153, v157, s[42:43]
	v_cndmask_b32_e64 v154, v154, v158, s[46:47]
	v_cndmask_b32_e32 v155, v155, v159, vcc
	v_rsq_f32_e32 v152, v152
	v_rsq_f32_e32 v153, v153
	v_rsq_f32_e32 v154, v154
	v_rsq_f32_e32 v155, v155
	v_mul_f32_e32 v156, 0x45800000, v152
	v_mul_f32_e32 v157, 0x45800000, v153
	v_mul_f32_e32 v158, 0x45800000, v154
	v_mul_f32_e32 v159, 0x45800000, v155
	v_cndmask_b32_e64 v152, v152, v156, s[8:9]
	v_cndmask_b32_e64 v153, v153, v157, s[42:43]
	v_cndmask_b32_e64 v154, v154, v158, s[46:47]
	v_cndmask_b32_e32 v155, v155, v159, vcc
	v_mul_f32_e32 v168, v104, v152
	v_mul_f32_e32 v169, v105, v153
	v_mul_f32_e32 v170, v106, v154
	v_mul_f32_e32 v171, v107, v155
	v_cvt_pk_bf16_f32 v172, v168, v169
	v_cvt_pk_bf16_f32 v173, v170, v171
	global_store_dwordx2 v[140:141], v[172:173], off offset:32
	v_mul_f32_e32 v174, v96, v152
	v_mul_f32_e32 v175, v97, v153
	v_mul_f32_e32 v176, v98, v154
	v_mul_f32_e32 v177, v99, v155
	v_cvt_pk_bf16_f32 v178, v174, v175
	v_cvt_pk_bf16_f32 v179, v176, v177
	global_store_dwordx2 v[142:143], v[178:179], off offset:32
	v_mul_f32_e32 v168, v108, v152
	v_mul_f32_e32 v169, v109, v153
	v_mul_f32_e32 v170, v110, v154
	v_mul_f32_e32 v171, v111, v155
	v_cvt_pk_bf16_f32 v172, v168, v169
	v_cvt_pk_bf16_f32 v173, v170, v171
	global_store_dwordx2 v[164:165], v[172:173], off offset:32
	v_mul_f32_e32 v174, v100, v152
	v_mul_f32_e32 v175, v101, v153
	v_mul_f32_e32 v176, v102, v154
	v_mul_f32_e32 v177, v103, v155
	v_cvt_pk_bf16_f32 v178, v174, v175
	v_cvt_pk_bf16_f32 v179, v176, v177
	global_store_dwordx2 v[166:167], v[178:179], off offset:32
	ds_read_b128 v[144:147], v134 offset:128
	ds_read_b128 v[148:151], v134 offset:1152
	s_waitcnt lgkmcnt(0)
; __device__ __forceinline__ void epilogue(KP p, f32x4 (&acc)[2][2][4][2], const float* s_inv, const int mode,
;                                          const float* __restrict__ xin, const float resw, const int brow, const int bcol,
;                                          const int pn) {
;     ...
; #pragma unroll
;     for (int ai = 0; ai < 2; ++ai)
; #pragma unroll
;       for (int m = 0; m < 4; ++m) {
;         const int rl = ai * HALF + wr * 64 + m * 16 + fr;
;         const int row = brow + rl;
;         const float sc = rsqrtf((s_inv[rl] + s_inv[256 + rl]) * (1.f / D_) + EPS_);
; #pragma unroll
;         for (int bj = 0; bj < 2; ++bj) {
;           const int col = bcol + bj * HALF + wc * 32 + fq * 8;
;           float v[8];
; #pragma unroll
;           for (int n = 0; n < 2; ++n)
; #pragma unroll
;             for (int r = 0; r < 4; ++r) v[n * 4 + r] = acc[ai][bj][m][n][r] * sc;
;           if (pn >= 8 && pn < 12) {
;             u16* d = p->vT + (size_t)(col - 2048) * S_ + row;
; #pragma unroll
;             for (int e = 0; e < 8; ++e) d[(size_t)e * S_] = f2bf(v[e]);
	v_add_f32_e32 v152, v144, v148
	v_add_f32_e32 v153, v145, v149
	v_add_f32_e32 v154, v146, v150
	v_add_f32_e32 v155, v147, v151
	v_fmamk_f32 v152, v152, 0x3a000000, v211
	v_fmamk_f32 v153, v153, 0x3a000000, v211
	v_fmamk_f32 v154, v154, 0x3a000000, v211
	v_fmamk_f32 v155, v155, 0x3a000000, v211
	v_mul_f32_e32 v156, 0x4b800000, v152
	v_mul_f32_e32 v157, 0x4b800000, v153
	v_mul_f32_e32 v158, 0x4b800000, v154
	v_mul_f32_e32 v159, 0x4b800000, v155
	v_cmp_gt_f32_e64 s[8:9], s77, v152
	v_cmp_gt_f32_e64 s[42:43], s77, v153
	v_cmp_gt_f32_e64 s[46:47], s77, v154
	v_cmp_gt_f32_e32 vcc, s77, v155
	s_nop 1
	v_cndmask_b32_e64 v152, v152, v156, s[8:9]
	v_cndmask_b32_e64 v153, v153, v157, s[42:43]
	v_cndmask_b32_e64 v154, v154, v158, s[46:47]
	v_cndmask_b32_e32 v155, v155, v159, vcc
	v_rsq_f32_e32 v152, v152
	v_rsq_f32_e32 v153, v153
	v_rsq_f32_e32 v154, v154
	v_rsq_f32_e32 v155, v155
	v_mul_f32_e32 v156, 0x45800000, v152
	v_mul_f32_e32 v157, 0x45800000, v153
	v_mul_f32_e32 v158, 0x45800000, v154
	v_mul_f32_e32 v159, 0x45800000, v155
	v_cndmask_b32_e64 v152, v152, v156, s[8:9]
	v_cndmask_b32_e64 v153, v153, v157, s[42:43]
	v_cndmask_b32_e64 v154, v154, v158, s[46:47]
	v_cndmask_b32_e32 v155, v155, v159, vcc
	v_mul_f32_e32 v168, v88, v152
	v_mul_f32_e32 v169, v89, v153
	v_mul_f32_e32 v170, v90, v154
	v_mul_f32_e32 v171, v91, v155
	v_cvt_pk_bf16_f32 v172, v168, v169
	v_cvt_pk_bf16_f32 v173, v170, v171
	global_store_dwordx2 v[140:141], v[172:173], off offset:64
	v_mul_f32_e32 v174, v80, v152
	v_mul_f32_e32 v175, v81, v153
	v_mul_f32_e32 v176, v82, v154
	v_mul_f32_e32 v177, v83, v155
	v_cvt_pk_bf16_f32 v178, v174, v175
	v_cvt_pk_bf16_f32 v179, v176, v177
	global_store_dwordx2 v[142:143], v[178:179], off offset:64
	v_mul_f32_e32 v168, v92, v152
	v_mul_f32_e32 v169, v93, v153
	v_mul_f32_e32 v170, v94, v154
	v_mul_f32_e32 v171, v95, v155
	v_cvt_pk_bf16_f32 v172, v168, v169
	v_cvt_pk_bf16_f32 v173, v170, v171
	global_store_dwordx2 v[164:165], v[172:173], off offset:64
	v_mul_f32_e32 v174, v84, v152
	v_mul_f32_e32 v175, v85, v153
	v_mul_f32_e32 v176, v86, v154
	v_mul_f32_e32 v177, v87, v155
	v_cvt_pk_bf16_f32 v178, v174, v175
	v_cvt_pk_bf16_f32 v179, v176, v177
	global_store_dwordx2 v[166:167], v[178:179], off offset:64
	ds_read_b128 v[144:147], v134 offset:192
	ds_read_b128 v[148:151], v134 offset:1216
	s_waitcnt lgkmcnt(0)
	v_add_f32_e32 v152, v144, v148
	v_add_f32_e32 v153, v145, v149
	v_add_f32_e32 v154, v146, v150
	v_add_f32_e32 v155, v147, v151
	v_fmamk_f32 v152, v152, 0x3a000000, v211
	v_fmamk_f32 v153, v153, 0x3a000000, v211
	v_fmamk_f32 v154, v154, 0x3a000000, v211
	v_fmamk_f32 v155, v155, 0x3a000000, v211
	v_mul_f32_e32 v156, 0x4b800000, v152
	v_mul_f32_e32 v157, 0x4b800000, v153
	v_mul_f32_e32 v158, 0x4b800000, v154
	v_mul_f32_e32 v159, 0x4b800000, v155
	v_cmp_gt_f32_e64 s[8:9], s77, v152
	v_cmp_gt_f32_e64 s[42:43], s77, v153
	v_cmp_gt_f32_e64 s[46:47], s77, v154
	v_cmp_gt_f32_e32 vcc, s77, v155
	s_nop 1
	v_cndmask_b32_e64 v152, v152, v156, s[8:9]
	v_cndmask_b32_e64 v153, v153, v157, s[42:43]
	v_cndmask_b32_e64 v154, v154, v158, s[46:47]
	v_cndmask_b32_e32 v155, v155, v159, vcc
	v_rsq_f32_e32 v152, v152
	v_rsq_f32_e32 v153, v153
	v_rsq_f32_e32 v154, v154
	v_rsq_f32_e32 v155, v155
	v_mul_f32_e32 v156, 0x45800000, v152
	v_mul_f32_e32 v157, 0x45800000, v153
	v_mul_f32_e32 v158, 0x45800000, v154
	v_mul_f32_e32 v159, 0x45800000, v155
	v_cndmask_b32_e64 v152, v152, v156, s[8:9]
	v_cndmask_b32_e64 v153, v153, v157, s[42:43]
	v_cndmask_b32_e64 v154, v154, v158, s[46:47]
	v_cndmask_b32_e32 v155, v155, v159, vcc
	v_mul_f32_e32 v168, v72, v152
	v_mul_f32_e32 v169, v73, v153
	v_mul_f32_e32 v170, v74, v154
	v_mul_f32_e32 v171, v75, v155
	v_cvt_pk_bf16_f32 v172, v168, v169
	v_cvt_pk_bf16_f32 v173, v170, v171
	global_store_dwordx2 v[140:141], v[172:173], off offset:96
	v_mul_f32_e32 v174, v64, v152
	v_mul_f32_e32 v175, v65, v153
	v_mul_f32_e32 v176, v66, v154
	v_mul_f32_e32 v177, v67, v155
	v_cvt_pk_bf16_f32 v178, v174, v175
	v_cvt_pk_bf16_f32 v179, v176, v177
	global_store_dwordx2 v[142:143], v[178:179], off offset:96
	v_mul_f32_e32 v168, v76, v152
	v_mul_f32_e32 v169, v77, v153
	v_mul_f32_e32 v170, v78, v154
	v_mul_f32_e32 v171, v79, v155
	v_cvt_pk_bf16_f32 v172, v168, v169
	v_cvt_pk_bf16_f32 v173, v170, v171
	global_store_dwordx2 v[164:165], v[172:173], off offset:96
	v_mul_f32_e32 v174, v68, v152
	v_mul_f32_e32 v175, v69, v153
	v_mul_f32_e32 v176, v70, v154
	v_mul_f32_e32 v177, v71, v155
	v_cvt_pk_bf16_f32 v178, v174, v175
	v_cvt_pk_bf16_f32 v179, v176, v177
	global_store_dwordx2 v[166:167], v[178:179], off offset:96
	ds_read_b128 v[144:147], v134 offset:512
	ds_read_b128 v[148:151], v134 offset:1536
	s_waitcnt lgkmcnt(0)
; __device__ __forceinline__ void epilogue(KP p, f32x4 (&acc)[2][2][4][2], const float* s_inv, const int mode,
;                                          const float* __restrict__ xin, const float resw, const int brow, const int bcol,
;                                          const int pn) {
;     ...
; #pragma unroll
;     for (int ai = 0; ai < 2; ++ai)
; #pragma unroll
;       for (int m = 0; m < 4; ++m) {
;         const int rl = ai * HALF + wr * 64 + m * 16 + fr;
;         const int row = brow + rl;
;         const float sc = rsqrtf((s_inv[rl] + s_inv[256 + rl]) * (1.f / D_) + EPS_);
; #pragma unroll
;         for (int bj = 0; bj < 2; ++bj) {
;           const int col = bcol + bj * HALF + wc * 32 + fq * 8;
;           float v[8];
; #pragma unroll
;           for (int n = 0; n < 2; ++n)
; #pragma unroll
;             for (int r = 0; r < 4; ++r) v[n * 4 + r] = acc[ai][bj][m][n][r] * sc;
;           if (pn >= 8 && pn < 12) {
;             u16* d = p->vT + (size_t)(col - 2048) * S_ + row;
; #pragma unroll
;             for (int e = 0; e < 8; ++e) d[(size_t)e * S_] = f2bf(v[e]);
	v_add_f32_e32 v152, v144, v148
	v_add_f32_e32 v153, v145, v149
	v_add_f32_e32 v154, v146, v150
	v_add_f32_e32 v155, v147, v151
	v_fmamk_f32 v152, v152, 0x3a000000, v211
	v_fmamk_f32 v153, v153, 0x3a000000, v211
	v_fmamk_f32 v154, v154, 0x3a000000, v211
	v_fmamk_f32 v155, v155, 0x3a000000, v211
	v_mul_f32_e32 v156, 0x4b800000, v152
	v_mul_f32_e32 v157, 0x4b800000, v153
	v_mul_f32_e32 v158, 0x4b800000, v154
	v_mul_f32_e32 v159, 0x4b800000, v155
	v_cmp_gt_f32_e64 s[8:9], s77, v152
	v_cmp_gt_f32_e64 s[42:43], s77, v153
	v_cmp_gt_f32_e64 s[46:47], s77, v154
	v_cmp_gt_f32_e32 vcc, s77, v155
	s_nop 1
	v_cndmask_b32_e64 v152, v152, v156, s[8:9]
	v_cndmask_b32_e64 v153, v153, v157, s[42:43]
	v_cndmask_b32_e64 v154, v154, v158, s[46:47]
	v_cndmask_b32_e32 v155, v155, v159, vcc
	v_rsq_f32_e32 v152, v152
	v_rsq_f32_e32 v153, v153
	v_rsq_f32_e32 v154, v154
	v_rsq_f32_e32 v155, v155
	v_mul_f32_e32 v156, 0x45800000, v152
	v_mul_f32_e32 v157, 0x45800000, v153
	v_mul_f32_e32 v158, 0x45800000, v154
	v_mul_f32_e32 v159, 0x45800000, v155
	v_cndmask_b32_e64 v152, v152, v156, s[8:9]
	v_cndmask_b32_e64 v153, v153, v157, s[42:43]
	v_cndmask_b32_e64 v154, v154, v158, s[46:47]
	v_cndmask_b32_e32 v155, v155, v159, vcc
	v_mul_f32_e32 v168, v56, v152
	v_mul_f32_e32 v169, v57, v153
	v_mul_f32_e32 v170, v58, v154
	v_mul_f32_e32 v171, v59, v155
	v_cvt_pk_bf16_f32 v172, v168, v169
	v_cvt_pk_bf16_f32 v173, v170, v171
	global_store_dwordx2 v[140:141], v[172:173], off offset:256
	v_mul_f32_e32 v174, v48, v152
	v_mul_f32_e32 v175, v49, v153
	v_mul_f32_e32 v176, v50, v154
	v_mul_f32_e32 v177, v51, v155
	v_cvt_pk_bf16_f32 v178, v174, v175
	v_cvt_pk_bf16_f32 v179, v176, v177
	global_store_dwordx2 v[142:143], v[178:179], off offset:256
	v_mul_f32_e32 v168, v60, v152
	v_mul_f32_e32 v169, v61, v153
	v_mul_f32_e32 v170, v62, v154
	v_mul_f32_e32 v171, v63, v155
	v_cvt_pk_bf16_f32 v172, v168, v169
	v_cvt_pk_bf16_f32 v173, v170, v171
	global_store_dwordx2 v[164:165], v[172:173], off offset:256
	v_mul_f32_e32 v174, v52, v152
	v_mul_f32_e32 v175, v53, v153
	v_mul_f32_e32 v176, v54, v154
	v_mul_f32_e32 v177, v55, v155
	v_cvt_pk_bf16_f32 v178, v174, v175
	v_cvt_pk_bf16_f32 v179, v176, v177
	global_store_dwordx2 v[166:167], v[178:179], off offset:256
	ds_read_b128 v[144:147], v134 offset:576
	ds_read_b128 v[148:151], v134 offset:1600
	s_waitcnt lgkmcnt(0)
	v_add_f32_e32 v152, v144, v148
	v_add_f32_e32 v153, v145, v149
	v_add_f32_e32 v154, v146, v150
	v_add_f32_e32 v155, v147, v151
	v_fmamk_f32 v152, v152, 0x3a000000, v211
	v_fmamk_f32 v153, v153, 0x3a000000, v211
	v_fmamk_f32 v154, v154, 0x3a000000, v211
	v_fmamk_f32 v155, v155, 0x3a000000, v211
	v_mul_f32_e32 v156, 0x4b800000, v152
	v_mul_f32_e32 v157, 0x4b800000, v153
	v_mul_f32_e32 v158, 0x4b800000, v154
	v_mul_f32_e32 v159, 0x4b800000, v155
	v_cmp_gt_f32_e64 s[8:9], s77, v152
	v_cmp_gt_f32_e64 s[42:43], s77, v153
	v_cmp_gt_f32_e64 s[46:47], s77, v154
	v_cmp_gt_f32_e32 vcc, s77, v155
	s_nop 1
	v_cndmask_b32_e64 v152, v152, v156, s[8:9]
	v_cndmask_b32_e64 v153, v153, v157, s[42:43]
	v_cndmask_b32_e64 v154, v154, v158, s[46:47]
	v_cndmask_b32_e32 v155, v155, v159, vcc
	v_rsq_f32_e32 v152, v152
	v_rsq_f32_e32 v153, v153
	v_rsq_f32_e32 v154, v154
	v_rsq_f32_e32 v155, v155
	v_mul_f32_e32 v156, 0x45800000, v152
	v_mul_f32_e32 v157, 0x45800000, v153
	v_mul_f32_e32 v158, 0x45800000, v154
	v_mul_f32_e32 v159, 0x45800000, v155
	v_cndmask_b32_e64 v152, v152, v156, s[8:9]
	v_cndmask_b32_e64 v153, v153, v157, s[42:43]
	v_cndmask_b32_e64 v154, v154, v158, s[46:47]
	v_cndmask_b32_e32 v155, v155, v159, vcc
	v_mul_f32_e32 v168, v40, v152
	v_mul_f32_e32 v169, v41, v153
	v_mul_f32_e32 v170, v42, v154
	v_mul_f32_e32 v171, v43, v155
	v_cvt_pk_bf16_f32 v172, v168, v169
	v_cvt_pk_bf16_f32 v173, v170, v171
	global_store_dwordx2 v[140:141], v[172:173], off offset:288
	v_mul_f32_e32 v174, v32, v152
	v_mul_f32_e32 v175, v33, v153
	v_mul_f32_e32 v176, v34, v154
	v_mul_f32_e32 v177, v35, v155
	v_cvt_pk_bf16_f32 v178, v174, v175
	v_cvt_pk_bf16_f32 v179, v176, v177
	global_store_dwordx2 v[142:143], v[178:179], off offset:288
	v_mul_f32_e32 v168, v44, v152
	v_mul_f32_e32 v169, v45, v153
	v_mul_f32_e32 v170, v46, v154
	v_mul_f32_e32 v171, v47, v155
	v_cvt_pk_bf16_f32 v172, v168, v169
	v_cvt_pk_bf16_f32 v173, v170, v171
	global_store_dwordx2 v[164:165], v[172:173], off offset:288
	v_mul_f32_e32 v174, v36, v152
	v_mul_f32_e32 v175, v37, v153
	v_mul_f32_e32 v176, v38, v154
	v_mul_f32_e32 v177, v39, v155
	v_cvt_pk_bf16_f32 v178, v174, v175
	v_cvt_pk_bf16_f32 v179, v176, v177
	global_store_dwordx2 v[166:167], v[178:179], off offset:288
	ds_read_b128 v[144:147], v134 offset:640
	ds_read_b128 v[148:151], v134 offset:1664
	s_waitcnt lgkmcnt(0)
; __device__ __forceinline__ void epilogue(KP p, f32x4 (&acc)[2][2][4][2], const float* s_inv, const int mode,
;                                          const float* __restrict__ xin, const float resw, const int brow, const int bcol,
;                                          const int pn) {
;     ...
; #pragma unroll
;     for (int ai = 0; ai < 2; ++ai)
; #pragma unroll
;       for (int m = 0; m < 4; ++m) {
;         const int rl = ai * HALF + wr * 64 + m * 16 + fr;
;         const int row = brow + rl;
;         const float sc = rsqrtf((s_inv[rl] + s_inv[256 + rl]) * (1.f / D_) + EPS_);
; #pragma unroll
;         for (int bj = 0; bj < 2; ++bj) {
;           const int col = bcol + bj * HALF + wc * 32 + fq * 8;
;           float v[8];
; #pragma unroll
;           for (int n = 0; n < 2; ++n)
; #pragma unroll
;             for (int r = 0; r < 4; ++r) v[n * 4 + r] = acc[ai][bj][m][n][r] * sc;
;           if (pn >= 8 && pn < 12) {
;             u16* d = p->vT + (size_t)(col - 2048) * S_ + row;
; #pragma unroll
;             for (int e = 0; e < 8; ++e) d[(size_t)e * S_] = f2bf(v[e]);
	v_add_f32_e32 v152, v144, v148
	v_add_f32_e32 v153, v145, v149
	v_add_f32_e32 v154, v146, v150
	v_add_f32_e32 v155, v147, v151
	v_fmamk_f32 v152, v152, 0x3a000000, v211
	v_fmamk_f32 v153, v153, 0x3a000000, v211
	v_fmamk_f32 v154, v154, 0x3a000000, v211
	v_fmamk_f32 v155, v155, 0x3a000000, v211
	v_mul_f32_e32 v156, 0x4b800000, v152
	v_mul_f32_e32 v157, 0x4b800000, v153
	v_mul_f32_e32 v158, 0x4b800000, v154
	v_mul_f32_e32 v159, 0x4b800000, v155
	v_cmp_gt_f32_e64 s[8:9], s77, v152
	v_cmp_gt_f32_e64 s[42:43], s77, v153
	v_cmp_gt_f32_e64 s[46:47], s77, v154
	v_cmp_gt_f32_e32 vcc, s77, v155
	s_nop 1
	v_cndmask_b32_e64 v152, v152, v156, s[8:9]
	v_cndmask_b32_e64 v153, v153, v157, s[42:43]
	v_cndmask_b32_e64 v154, v154, v158, s[46:47]
	v_cndmask_b32_e32 v155, v155, v159, vcc
	v_rsq_f32_e32 v152, v152
	v_rsq_f32_e32 v153, v153
	v_rsq_f32_e32 v154, v154
	v_rsq_f32_e32 v155, v155
	v_mul_f32_e32 v156, 0x45800000, v152
	v_mul_f32_e32 v157, 0x45800000, v153
	v_mul_f32_e32 v158, 0x45800000, v154
	v_mul_f32_e32 v159, 0x45800000, v155
	v_cndmask_b32_e64 v152, v152, v156, s[8:9]
	v_cndmask_b32_e64 v153, v153, v157, s[42:43]
	v_cndmask_b32_e64 v154, v154, v158, s[46:47]
	v_cndmask_b32_e32 v155, v155, v159, vcc
	v_mul_f32_e32 v168, v24, v152
	v_mul_f32_e32 v169, v25, v153
	v_mul_f32_e32 v170, v26, v154
	v_mul_f32_e32 v171, v27, v155
	v_cvt_pk_bf16_f32 v172, v168, v169
	v_cvt_pk_bf16_f32 v173, v170, v171
	global_store_dwordx2 v[140:141], v[172:173], off offset:320
	v_mul_f32_e32 v174, v16, v152
	v_mul_f32_e32 v175, v17, v153
	v_mul_f32_e32 v176, v18, v154
	v_mul_f32_e32 v177, v19, v155
	v_cvt_pk_bf16_f32 v178, v174, v175
	v_cvt_pk_bf16_f32 v179, v176, v177
	global_store_dwordx2 v[142:143], v[178:179], off offset:320
	v_mul_f32_e32 v168, v28, v152
	v_mul_f32_e32 v169, v29, v153
	v_mul_f32_e32 v170, v30, v154
	v_mul_f32_e32 v171, v31, v155
	v_cvt_pk_bf16_f32 v172, v168, v169
	v_cvt_pk_bf16_f32 v173, v170, v171
	global_store_dwordx2 v[164:165], v[172:173], off offset:320
	v_mul_f32_e32 v174, v20, v152
	v_mul_f32_e32 v175, v21, v153
	v_mul_f32_e32 v176, v22, v154
	v_mul_f32_e32 v177, v23, v155
	v_cvt_pk_bf16_f32 v178, v174, v175
	v_cvt_pk_bf16_f32 v179, v176, v177
	global_store_dwordx2 v[166:167], v[178:179], off offset:320
	ds_read_b128 v[144:147], v134 offset:704
	ds_read_b128 v[148:151], v134 offset:1728
	s_waitcnt lgkmcnt(0)
	v_add_f32_e32 v152, v144, v148
	v_add_f32_e32 v153, v145, v149
	v_add_f32_e32 v154, v146, v150
	v_add_f32_e32 v155, v147, v151
	v_fmamk_f32 v152, v152, 0x3a000000, v211
	v_fmamk_f32 v153, v153, 0x3a000000, v211
	v_fmamk_f32 v154, v154, 0x3a000000, v211
	v_fmamk_f32 v155, v155, 0x3a000000, v211
	v_mul_f32_e32 v156, 0x4b800000, v152
	v_mul_f32_e32 v157, 0x4b800000, v153
	v_mul_f32_e32 v158, 0x4b800000, v154
	v_mul_f32_e32 v159, 0x4b800000, v155
	v_cmp_gt_f32_e64 s[8:9], s77, v152
	v_cmp_gt_f32_e64 s[42:43], s77, v153
	v_cmp_gt_f32_e64 s[46:47], s77, v154
	v_cmp_gt_f32_e32 vcc, s77, v155
	s_nop 1
	v_cndmask_b32_e64 v152, v152, v156, s[8:9]
	v_cndmask_b32_e64 v153, v153, v157, s[42:43]
	v_cndmask_b32_e64 v154, v154, v158, s[46:47]
	v_cndmask_b32_e32 v155, v155, v159, vcc
	v_rsq_f32_e32 v152, v152
	v_rsq_f32_e32 v153, v153
	v_rsq_f32_e32 v154, v154
	v_rsq_f32_e32 v155, v155
	v_mul_f32_e32 v156, 0x45800000, v152
	v_mul_f32_e32 v157, 0x45800000, v153
	v_mul_f32_e32 v158, 0x45800000, v154
	v_mul_f32_e32 v159, 0x45800000, v155
	v_cndmask_b32_e64 v152, v152, v156, s[8:9]
	v_cndmask_b32_e64 v153, v153, v157, s[42:43]
	v_cndmask_b32_e64 v154, v154, v158, s[46:47]
	v_cndmask_b32_e32 v155, v155, v159, vcc
	v_mul_f32_e32 v168, v8, v152
	v_mul_f32_e32 v169, v9, v153
	v_mul_f32_e32 v170, v10, v154
	v_mul_f32_e32 v171, v11, v155
	v_cvt_pk_bf16_f32 v172, v168, v169
	v_cvt_pk_bf16_f32 v173, v170, v171
	global_store_dwordx2 v[140:141], v[172:173], off offset:352
	v_mul_f32_e32 v174, v0, v152
	v_mul_f32_e32 v175, v1, v153
	v_mul_f32_e32 v176, v2, v154
	v_mul_f32_e32 v177, v3, v155
	v_cvt_pk_bf16_f32 v178, v174, v175
	v_cvt_pk_bf16_f32 v179, v176, v177
	global_store_dwordx2 v[142:143], v[178:179], off offset:352
	v_mul_f32_e32 v168, v12, v152
	v_mul_f32_e32 v169, v13, v153
	v_mul_f32_e32 v170, v14, v154
	v_mul_f32_e32 v171, v15, v155
	v_cvt_pk_bf16_f32 v172, v168, v169
	v_cvt_pk_bf16_f32 v173, v170, v171
	global_store_dwordx2 v[164:165], v[172:173], off offset:352
	v_mul_f32_e32 v174, v4, v152
	v_mul_f32_e32 v175, v5, v153
	v_mul_f32_e32 v176, v6, v154
	v_mul_f32_e32 v177, v7, v155
	v_cvt_pk_bf16_f32 v178, v174, v175
	v_cvt_pk_bf16_f32 v179, v176, v177
	global_store_dwordx2 v[166:167], v[178:179], off offset:352
	s_branch .LBB0_313
